# additionally removed the per-quadrant s_setprio flips in the GEMM phases (on top of no-setprio attention + pipelined mem-attention reads)
# speedup vs baseline: 1.0027x; 1.0027x over previous
; #define PG8_STAGE(bufoff, gbase, voff) do { _Pragma("unroll") for (int _i = 0; _i < 2; ++_i) \
;     __builtin_amdgcn_global_load_lds((const unsigned*)((const char*)(gbase) + (voff)[_i]), (LAS unsigned*)(lds + (bufoff) + ldsw + _i * 8192), 16, 0, 0); } while (0)
; #define PG8_LDA(dst, b, h) do { _Pragma("unroll") for (int m = 0; m < 4; ++m) _Pragma("unroll") for (int k = 0; k < 2; ++k) dst[m][k] = *(const LAS bf16x8*)(lds + PG8_SA(b, h) + aoff + m * 2048 + k * 1024); } while (0)
; #define PG8_LDB(dst, b, h) do { _Pragma("unroll") for (int n = 0; n < 2; ++n) _Pragma("unroll") for (int k = 0; k < 2; ++k) dst[n][k] = *(const LAS bf16x8*)(lds + PG8_SB(b, h) + boff + n * 2048 + k * 1024); } while (0)
; #define PG8_MMA(ai, bj, At, Bt) do { __builtin_amdgcn_s_setprio(1); _Pragma("unroll") for (int m = 0; m < 4; ++m) _Pragma("unroll") for (int n = 0; n < 2; ++n) _Pragma("unroll") for (int k = 0; k < 2; ++k) \
;     acc[ai][bj][m][n] = __builtin_amdgcn_mfma_f32_16x16x32_bf16(Bt[n][k], At[m][k], acc[ai][bj][m][n], 0, 0, 0); __builtin_amdgcn_s_setprio(0); } while (0)
; #define PG8_WAIT_L(n) asm volatile("s_waitcnt lgkmcnt(" #n ")" ::: "memory")
; #define PG8_BAR __builtin_amdgcn_s_barrier()
; #define PG8_SCHED __builtin_amdgcn_sched_barrier(0)
; template <class Epi, class Sched>
; __device__ __forceinline__ void gemm_phase(LAS unsigned char* lds, const Gemm g, const Sched& S, const Epi& E) {
;     ...
;       PG8_LDB(B0, 0, 0); PG8_SCHED; PG8_LDA(At, 0, 0); PG8_STAGE(PG8_SA(1, 1), a1 + hstepA, voffA);
;       PG8_WAIT_L(8); PG8_BAR; PG8_WAIT_L(0); PG8_MMA(0, 0, At, B0); PG8_BAR; PG8_SCHED;
;       PG8_LDB(B1, 0, 1); PG8_STAGE(PG8_SB(0, 0), b2, voffB);
;       PG8_BAR; PG8_WAIT_L(0); PG8_MMA(0, 1, At, B1); PG8_BAR;
;       PG8_LDA(At, 0, 1); PG8_STAGE(PG8_SA(0, 0), a2, voffA);
;       PG8_BAR; PG8_WAIT_L(0); PG8_MMA(1, 0, At, B0); PG8_BAR; PG8_SCHED;
.LBB0_152:
	s_add_u32 s7, s36, 0xfffc0080
	s_addc_u32 s8, s37, -1
	s_add_i32 s9, 0, 0x10000
	v_add_u32_e32 v149, s9, v174
	ds_read_b128 v[128:131], v149
	ds_read_b128 v[132:135], v149 offset:1024
	ds_read_b128 v[150:153], v149 offset:2048
	ds_read_b128 v[154:157], v149 offset:3072
	s_cmp_eq_u32 s6, 12
	s_cselect_b32 vcc_hi, s13, s8
	s_cselect_b32 vcc_lo, s42, s7
	s_cselect_b32 s65, s39, s5
	s_cselect_b32 s64, s43, s4
	v_lshl_add_u64 v[158:159], s[36:37], 0, v[142:143]
	s_add_i32 m0, s93, 0xc000
	ds_read_b128 v[176:179], v175
	ds_read_b128 v[180:183], v175 offset:1024
	ds_read_b128 v[184:187], v175 offset:2048
	ds_read_b128 v[188:191], v175 offset:3072
	ds_read_b128 v[192:195], v175 offset:4096
	ds_read_b128 v[196:199], v175 offset:5120
	ds_read_b128 v[200:203], v175 offset:6144
	ds_read_b128 v[210:213], v175 offset:7168
	global_load_lds_dwordx4 v[158:159], off
	v_lshl_add_u64 v[158:159], s[36:37], 0, v[144:145]
	s_add_i32 m0, s93, 0xe000
	s_nop 0
	global_load_lds_dwordx4 v[158:159], off
	s_waitcnt lgkmcnt(8)
	s_barrier
	s_waitcnt lgkmcnt(0)
	s_waitcnt lgkmcnt(0)
	v_mfma_f32_16x16x32_bf16 v[124:127], v[128:131], v[176:179], v[124:127]
	v_mfma_f32_16x16x32_bf16 v[120:123], v[150:153], v[176:179], v[120:123]
	v_mfma_f32_16x16x32_bf16 v[108:111], v[128:131], v[184:187], v[108:111]
	v_mfma_f32_16x16x32_bf16 v[104:107], v[150:153], v[184:187], v[104:107]
	v_mfma_f32_16x16x32_bf16 v[92:95], v[128:131], v[192:195], v[92:95]
	v_mfma_f32_16x16x32_bf16 v[88:91], v[150:153], v[192:195], v[88:91]
	v_mfma_f32_16x16x32_bf16 v[76:79], v[128:131], v[200:203], v[76:79]
	v_mfma_f32_16x16x32_bf16 v[72:75], v[150:153], v[200:203], v[72:75]
	v_mfma_f32_16x16x32_bf16 v[124:127], v[132:135], v[180:183], v[124:127]
	v_mfma_f32_16x16x32_bf16 v[120:123], v[154:157], v[180:183], v[120:123]
	v_mfma_f32_16x16x32_bf16 v[108:111], v[132:135], v[188:191], v[108:111]
	v_mfma_f32_16x16x32_bf16 v[104:107], v[154:157], v[188:191], v[104:107]
	v_mfma_f32_16x16x32_bf16 v[92:95], v[132:135], v[196:199], v[92:95]
	v_mfma_f32_16x16x32_bf16 v[88:91], v[154:157], v[196:199], v[88:91]
	v_mfma_f32_16x16x32_bf16 v[76:79], v[132:135], v[210:213], v[76:79]
	v_mfma_f32_16x16x32_bf16 v[72:75], v[154:157], v[210:213], v[72:75]
	s_barrier
	s_add_i32 s7, 0, 0x14000
	s_add_i32 s8, s9, s97
	v_add_u32_e32 v149, s7, v174
	v_lshl_add_u64 v[158:159], s[64:65], 0, v[138:139]
	s_mov_b32 m0, s8
	ds_read_b128 v[214:217], v149
	ds_read_b128 v[218:221], v149 offset:1024
	ds_read_b128 v[222:225], v149 offset:2048
	ds_read_b128 v[226:229], v149 offset:3072
	global_load_lds_dwordx4 v[158:159], off
	v_lshl_add_u64 v[172:173], s[64:65], 0, v[136:137]
	s_add_i32 m0, s8, 0x2000
	s_nop 0
	global_load_lds_dwordx4 v[172:173], off
	s_barrier
	s_waitcnt lgkmcnt(0)
	s_waitcnt lgkmcnt(0)
	v_mfma_f32_16x16x32_bf16 v[116:119], v[214:217], v[176:179], v[116:119]
	v_mfma_f32_16x16x32_bf16 v[112:115], v[222:225], v[176:179], v[112:115]
	v_mfma_f32_16x16x32_bf16 v[100:103], v[214:217], v[184:187], v[100:103]
	v_mfma_f32_16x16x32_bf16 v[96:99], v[222:225], v[184:187], v[96:99]
	v_mfma_f32_16x16x32_bf16 v[84:87], v[214:217], v[192:195], v[84:87]
	v_mfma_f32_16x16x32_bf16 v[80:83], v[222:225], v[192:195], v[80:83]
	v_mfma_f32_16x16x32_bf16 v[68:71], v[214:217], v[200:203], v[68:71]
	v_mfma_f32_16x16x32_bf16 v[64:67], v[222:225], v[200:203], v[64:67]
	v_mfma_f32_16x16x32_bf16 v[116:119], v[218:221], v[180:183], v[116:119]
	v_mfma_f32_16x16x32_bf16 v[112:115], v[226:229], v[180:183], v[112:115]
	v_mfma_f32_16x16x32_bf16 v[100:103], v[218:221], v[188:191], v[100:103]
	v_mfma_f32_16x16x32_bf16 v[96:99], v[226:229], v[188:191], v[96:99]
	v_mfma_f32_16x16x32_bf16 v[84:87], v[218:221], v[196:199], v[84:87]
	v_mfma_f32_16x16x32_bf16 v[80:83], v[226:229], v[196:199], v[80:83]
	v_mfma_f32_16x16x32_bf16 v[68:71], v[218:221], v[210:213], v[68:71]
	v_mfma_f32_16x16x32_bf16 v[64:67], v[226:229], v[210:213], v[64:67]
	s_mov_b32 m0, s93
	v_lshl_add_u64 v[230:231], vcc, 0, v[138:139]
	s_barrier
	ds_read_b128 v[176:179], v175 offset:16384
	ds_read_b128 v[180:183], v175 offset:17408
	ds_read_b128 v[184:187], v175 offset:18432
	ds_read_b128 v[188:191], v175 offset:19456
	ds_read_b128 v[192:195], v175 offset:20480
	ds_read_b128 v[196:199], v175 offset:21504
	ds_read_b128 v[200:203], v175 offset:22528
	ds_read_b128 v[210:213], v175 offset:23552
	global_load_lds_dwordx4 v[230:231], off
	v_lshl_add_u64 v[232:233], vcc, 0, v[136:137]
	s_mov_b32 m0, s94
	s_nop 0
	global_load_lds_dwordx4 v[232:233], off
	s_barrier
	s_waitcnt lgkmcnt(0)
	s_waitcnt lgkmcnt(0)
	v_mfma_f32_16x16x32_bf16 v[60:63], v[128:131], v[176:179], v[60:63]
	v_mfma_f32_16x16x32_bf16 v[56:59], v[150:153], v[176:179], v[56:59]
	v_mfma_f32_16x16x32_bf16 v[44:47], v[128:131], v[184:187], v[44:47]
	v_mfma_f32_16x16x32_bf16 v[40:43], v[150:153], v[184:187], v[40:43]
	v_mfma_f32_16x16x32_bf16 v[28:31], v[128:131], v[192:195], v[28:31]
	v_mfma_f32_16x16x32_bf16 v[24:27], v[150:153], v[192:195], v[24:27]
	v_mfma_f32_16x16x32_bf16 v[12:15], v[128:131], v[200:203], v[12:15]
	v_mfma_f32_16x16x32_bf16 v[8:11], v[150:153], v[200:203], v[8:11]
	v_mfma_f32_16x16x32_bf16 v[60:63], v[132:135], v[180:183], v[60:63]
	v_mfma_f32_16x16x32_bf16 v[56:59], v[154:157], v[180:183], v[56:59]
	v_mfma_f32_16x16x32_bf16 v[44:47], v[132:135], v[188:191], v[44:47]
	v_mfma_f32_16x16x32_bf16 v[40:43], v[154:157], v[188:191], v[40:43]
	v_mfma_f32_16x16x32_bf16 v[28:31], v[132:135], v[196:199], v[28:31]
	v_mfma_f32_16x16x32_bf16 v[24:27], v[154:157], v[196:199], v[24:27]
	v_mfma_f32_16x16x32_bf16 v[12:15], v[132:135], v[210:213], v[12:15]
	v_mfma_f32_16x16x32_bf16 v[8:11], v[154:157], v[210:213], v[8:11]
	s_barrier
; #define PG8_STAGE(bufoff, gbase, voff) do { _Pragma("unroll") for (int _i = 0; _i < 2; ++_i) \
;     __builtin_amdgcn_global_load_lds((const unsigned*)((const char*)(gbase) + (voff)[_i]), (LAS unsigned*)(lds + (bufoff) + ldsw + _i * 8192), 16, 0, 0); } while (0)
; #define PG8_LDA(dst, b, h) do { _Pragma("unroll") for (int m = 0; m < 4; ++m) _Pragma("unroll") for (int k = 0; k < 2; ++k) dst[m][k] = *(const LAS bf16x8*)(lds + PG8_SA(b, h) + aoff + m * 2048 + k * 1024); } while (0)
; #define PG8_LDB(dst, b, h) do { _Pragma("unroll") for (int n = 0; n < 2; ++n) _Pragma("unroll") for (int k = 0; k < 2; ++k) dst[n][k] = *(const LAS bf16x8*)(lds + PG8_SB(b, h) + boff + n * 2048 + k * 1024); } while (0)
; #define PG8_MMA(ai, bj, At, Bt) do { __builtin_amdgcn_s_setprio(1); _Pragma("unroll") for (int m = 0; m < 4; ++m) _Pragma("unroll") for (int n = 0; n < 2; ++n) _Pragma("unroll") for (int k = 0; k < 2; ++k) \
;     acc[ai][bj][m][n] = __builtin_amdgcn_mfma_f32_16x16x32_bf16(Bt[n][k], At[m][k], acc[ai][bj][m][n], 0, 0, 0); __builtin_amdgcn_s_setprio(0); } while (0)
; #define PG8_WAIT_V(n) asm volatile("s_waitcnt vmcnt(" #n ")" ::: "memory")
; #define PG8_WAIT_L(n) asm volatile("s_waitcnt lgkmcnt(" #n ")" ::: "memory")
; #define PG8_BAR __builtin_amdgcn_s_barrier()
; #define PG8_SCHED __builtin_amdgcn_sched_barrier(0)
; template <class Epi, class Sched>
; __device__ __forceinline__ void gemm_phase(LAS unsigned char* lds, const Gemm g, const Sched& S, const Epi& E) {
;     ...
;       PG8_STAGE(PG8_SB(0, 1), b2 + hstepB, voffB);
;       PG8_WAIT_V(6); PG8_BAR; PG8_MMA(1, 1, At, B1); PG8_BAR;
;       PG8_LDB(B0, 1, 0); PG8_SCHED; PG8_LDA(At, 1, 0); PG8_STAGE(PG8_SA(0, 1), a2 + hstepA, voffA);
;       PG8_WAIT_L(8); PG8_BAR; PG8_WAIT_L(0); PG8_MMA(0, 0, At, B0); PG8_BAR; PG8_SCHED;
;       PG8_LDB(B1, 1, 1); PG8_STAGE(PG8_SB(1, 0), b3, voffB);
;       PG8_BAR; PG8_WAIT_L(0); PG8_MMA(0, 1, At, B1); PG8_BAR;
;       PG8_LDA(At, 1, 1); PG8_STAGE(PG8_SA(1, 0), a3, voffA);
	s_add_u32 s8, s64, 0x40000
	s_addc_u32 s9, s65, 0
	s_add_i32 s7, s7, s97
	v_lshl_add_u64 v[128:129], s[8:9], 0, v[138:139]
	s_mov_b32 m0, s7
	s_nop 0
	global_load_lds_dwordx4 v[128:129], off
	v_lshl_add_u64 v[128:129], s[8:9], 0, v[136:137]
	s_add_i32 m0, s7, 0x2000
	s_nop 0
	global_load_lds_dwordx4 v[128:129], off
	s_waitcnt vmcnt(6)
	s_barrier
	v_mfma_f32_16x16x32_bf16 v[52:55], v[214:217], v[176:179], v[52:55]
	v_mfma_f32_16x16x32_bf16 v[48:51], v[222:225], v[176:179], v[48:51]
	v_mfma_f32_16x16x32_bf16 v[36:39], v[214:217], v[184:187], v[36:39]
	v_mfma_f32_16x16x32_bf16 v[32:35], v[222:225], v[184:187], v[32:35]
	v_mfma_f32_16x16x32_bf16 v[20:23], v[214:217], v[192:195], v[20:23]
	v_mfma_f32_16x16x32_bf16 v[16:19], v[222:225], v[192:195], v[16:19]
	v_mfma_f32_16x16x32_bf16 v[4:7], v[214:217], v[200:203], v[4:7]
	v_mfma_f32_16x16x32_bf16 v[0:3], v[222:225], v[200:203], v[0:3]
	v_mfma_f32_16x16x32_bf16 v[52:55], v[218:221], v[180:183], v[52:55]
	v_mfma_f32_16x16x32_bf16 v[48:51], v[226:229], v[180:183], v[48:51]
	v_mfma_f32_16x16x32_bf16 v[36:39], v[218:221], v[188:191], v[36:39]
	v_mfma_f32_16x16x32_bf16 v[32:35], v[226:229], v[188:191], v[32:35]
	v_mfma_f32_16x16x32_bf16 v[20:23], v[218:221], v[196:199], v[20:23]
	v_mfma_f32_16x16x32_bf16 v[16:19], v[226:229], v[196:199], v[16:19]
	v_mfma_f32_16x16x32_bf16 v[4:7], v[218:221], v[210:213], v[4:7]
	v_mfma_f32_16x16x32_bf16 v[0:3], v[226:229], v[210:213], v[0:3]
	s_add_i32 s7, 0, 0x18000
	v_add_u32_e32 v149, s7, v174
	s_barrier
	ds_read_b128 v[128:131], v149
	ds_read_b128 v[132:135], v149 offset:1024
	ds_read_b128 v[150:153], v149 offset:2048
	ds_read_b128 v[154:157], v149 offset:3072
	s_add_u32 s8, vcc_lo, 0x40000
	s_addc_u32 s9, vcc_hi, 0
	s_mov_b32 m0, s40
	v_lshl_add_u64 v[214:215], s[8:9], 0, v[138:139]
	ds_read_b128 v[176:179], v175 offset:32768
	ds_read_b128 v[180:183], v175 offset:33792
	ds_read_b128 v[184:187], v175 offset:34816
	ds_read_b128 v[188:191], v175 offset:35840
	ds_read_b128 v[192:195], v175 offset:36864
	ds_read_b128 v[196:199], v175 offset:37888
	ds_read_b128 v[200:203], v175 offset:38912
	ds_read_b128 v[210:213], v175 offset:39936
	global_load_lds_dwordx4 v[214:215], off
	v_lshl_add_u64 v[214:215], s[8:9], 0, v[136:137]
	s_mov_b32 m0, s41
	s_nop 0
	global_load_lds_dwordx4 v[214:215], off
	s_waitcnt lgkmcnt(8)
	s_barrier
	s_waitcnt lgkmcnt(0)
	s_waitcnt lgkmcnt(0)
	v_mfma_f32_16x16x32_bf16 v[124:127], v[128:131], v[176:179], v[124:127]
	v_mfma_f32_16x16x32_bf16 v[120:123], v[150:153], v[176:179], v[120:123]
	v_mfma_f32_16x16x32_bf16 v[108:111], v[128:131], v[184:187], v[108:111]
	v_mfma_f32_16x16x32_bf16 v[104:107], v[150:153], v[184:187], v[104:107]
	v_mfma_f32_16x16x32_bf16 v[92:95], v[128:131], v[192:195], v[92:95]
	v_mfma_f32_16x16x32_bf16 v[88:91], v[150:153], v[192:195], v[88:91]
	v_mfma_f32_16x16x32_bf16 v[76:79], v[128:131], v[200:203], v[76:79]
	v_mfma_f32_16x16x32_bf16 v[72:75], v[150:153], v[200:203], v[72:75]
	v_mfma_f32_16x16x32_bf16 v[124:127], v[132:135], v[180:183], v[124:127]
	v_mfma_f32_16x16x32_bf16 v[120:123], v[154:157], v[180:183], v[120:123]
	v_mfma_f32_16x16x32_bf16 v[108:111], v[132:135], v[188:191], v[108:111]
	v_mfma_f32_16x16x32_bf16 v[104:107], v[154:157], v[188:191], v[104:107]
	v_mfma_f32_16x16x32_bf16 v[92:95], v[132:135], v[196:199], v[92:95]
	v_mfma_f32_16x16x32_bf16 v[88:91], v[154:157], v[196:199], v[88:91]
	v_mfma_f32_16x16x32_bf16 v[76:79], v[132:135], v[210:213], v[76:79]
	v_mfma_f32_16x16x32_bf16 v[72:75], v[154:157], v[210:213], v[72:75]
	s_barrier
	s_add_i32 vcc_lo, 0, 0x1c000
	s_add_i32 s7, s7, s97
	v_add_u32_e32 v149, vcc_lo, v174
	v_lshl_add_u64 v[158:159], v[158:159], 0, s[10:11]
	s_mov_b32 m0, s7
	ds_read_b128 v[214:217], v149
	ds_read_b128 v[218:221], v149 offset:1024
	ds_read_b128 v[222:225], v149 offset:2048
	ds_read_b128 v[226:229], v149 offset:3072
	global_load_lds_dwordx4 v[158:159], off
	v_lshl_add_u64 v[158:159], v[172:173], 0, s[10:11]
	s_add_i32 m0, s7, 0x2000
	s_nop 0
	global_load_lds_dwordx4 v[158:159], off
	s_barrier
	s_waitcnt lgkmcnt(0)
	s_waitcnt lgkmcnt(0)
	v_mfma_f32_16x16x32_bf16 v[116:119], v[214:217], v[176:179], v[116:119]
	v_mfma_f32_16x16x32_bf16 v[112:115], v[222:225], v[176:179], v[112:115]
	v_mfma_f32_16x16x32_bf16 v[100:103], v[214:217], v[184:187], v[100:103]
	v_mfma_f32_16x16x32_bf16 v[96:99], v[222:225], v[184:187], v[96:99]
	v_mfma_f32_16x16x32_bf16 v[84:87], v[214:217], v[192:195], v[84:87]
	v_mfma_f32_16x16x32_bf16 v[80:83], v[222:225], v[192:195], v[80:83]
	v_mfma_f32_16x16x32_bf16 v[68:71], v[214:217], v[200:203], v[68:71]
	v_mfma_f32_16x16x32_bf16 v[64:67], v[222:225], v[200:203], v[64:67]
	v_mfma_f32_16x16x32_bf16 v[116:119], v[218:221], v[180:183], v[116:119]
	v_mfma_f32_16x16x32_bf16 v[112:115], v[226:229], v[180:183], v[112:115]
	v_mfma_f32_16x16x32_bf16 v[100:103], v[218:221], v[188:191], v[100:103]
	v_mfma_f32_16x16x32_bf16 v[96:99], v[226:229], v[188:191], v[96:99]
	v_mfma_f32_16x16x32_bf16 v[84:87], v[218:221], v[196:199], v[84:87]
	v_mfma_f32_16x16x32_bf16 v[80:83], v[226:229], v[196:199], v[80:83]
	v_mfma_f32_16x16x32_bf16 v[68:71], v[218:221], v[210:213], v[68:71]
	v_mfma_f32_16x16x32_bf16 v[64:67], v[226:229], v[210:213], v[64:67]
	s_mov_b32 m0, s62
	v_lshl_add_u64 v[158:159], v[230:231], 0, s[10:11]
	s_barrier
	ds_read_b128 v[176:179], v175 offset:49152
	ds_read_b128 v[180:183], v175 offset:50176
	ds_read_b128 v[184:187], v175 offset:51200
	ds_read_b128 v[188:191], v175 offset:52224
	ds_read_b128 v[192:195], v175 offset:53248
	ds_read_b128 v[196:199], v175 offset:54272
	ds_read_b128 v[200:203], v175 offset:55296
	ds_read_b128 v[210:213], v175 offset:56320
	global_load_lds_dwordx4 v[158:159], off
	v_lshl_add_u64 v[158:159], v[232:233], 0, s[10:11]
	s_mov_b32 m0, s63
	s_nop 0
	global_load_lds_dwordx4 v[158:159], off
	s_barrier
; __device__ __forceinline__ unsigned cvtpk(float lo, float hi) { unsigned r; asm volatile("v_cvt_pk_bf16_f32 %0, %1, %2" : "=v"(r) : "v"(lo), "v"(hi)); return r; }
; #define PG8_STAGE(bufoff, gbase, voff) do { _Pragma("unroll") for (int _i = 0; _i < 2; ++_i) \
;     __builtin_amdgcn_global_load_lds((const unsigned*)((const char*)(gbase) + (voff)[_i]), (LAS unsigned*)(lds + (bufoff) + ldsw + _i * 8192), 16, 0, 0); } while (0)
; #define PG8_MMA(ai, bj, At, Bt) do { __builtin_amdgcn_s_setprio(1); _Pragma("unroll") for (int m = 0; m < 4; ++m) _Pragma("unroll") for (int n = 0; n < 2; ++n) _Pragma("unroll") for (int k = 0; k < 2; ++k) \
;     acc[ai][bj][m][n] = __builtin_amdgcn_mfma_f32_16x16x32_bf16(Bt[n][k], At[m][k], acc[ai][bj][m][n], 0, 0, 0); __builtin_amdgcn_s_setprio(0); } while (0)
; template <class Epi, class Sched>
; __device__ __forceinline__ void gemm_phase(LAS unsigned char* lds, const Gemm g, const Sched& S, const Epi& E) {
;     ...
;       PG8_BAR; PG8_WAIT_L(0); PG8_MMA(1, 0, At, B0); PG8_BAR; PG8_SCHED;
;       PG8_STAGE(PG8_SB(1, 1), b3 + hstepB, voffB);
;       PG8_WAIT_V(6); PG8_BAR; PG8_MMA(1, 1, At, B1); PG8_BAR;
;   __device__ __forceinline__ void operator()(const f32x4 (&acc)[2][2][4][2], const pg8::Unit& u, int wr, int wc, int fr, int fq) const {
;     ...
;     } else if (kd == EK_ROTR_Q || kd == EK_ROTR_K) {
;       const float sc = (kd == EK_ROTR_K) ? 0.08838834764831845f : 1.0f;
; #pragma unroll
;       for (int ai = 0; ai < 2; ++ai)
; #pragma unroll
;         for (int m = 0; m < 4; ++m) { const int row = row0 + ai * 128 + m * 16;
;           const f32x4* cs = (const f32x4*)(rope + ((size_t)row * 64 + 16 * wc + 4 * fq) * 2);
;           const f32x4 cs0 = cs[0], cs1 = cs[1];
;           const float c_[4] = {cs0[0], cs0[2], cs1[0], cs1[2]}, s_[4] = {cs0[1], cs0[3], cs1[1], cs1[3]};
;           bf16_t* rowp = O + (size_t)row * ldc + colt + 16 * wc + 4 * fq;
; #pragma unroll
;           for (int bj = 0; bj < 2; ++bj) { const f32x4 x1 = acc[ai][bj][m][0], x2 = acc[ai][bj][m][1]; float o1[4], o2[4];
; #pragma unroll
;             for (int j = 0; j < 4; ++j) { o1[j] = (x1[j] * c_[j] - x2[j] * s_[j]) * sc; o2[j] = (x1[j] * s_[j] + x2[j] * c_[j]) * sc; }
;             u32x2 w1 = {cvtpk(o1[0], o1[1]), cvtpk(o1[2], o1[3])}, w2 = {cvtpk(o2[0], o2[1]), cvtpk(o2[2], o2[3])};
;             *(u32x2*)(rowp + bj * 128) = w1; *(u32x2*)(rowp + bj * 128 + 64) = w2; } }
	s_waitcnt lgkmcnt(0)
	s_waitcnt lgkmcnt(0)
	v_mfma_f32_16x16x32_bf16 v[60:63], v[128:131], v[176:179], v[60:63]
	v_mfma_f32_16x16x32_bf16 v[56:59], v[150:153], v[176:179], v[56:59]
	v_mfma_f32_16x16x32_bf16 v[44:47], v[128:131], v[184:187], v[44:47]
	v_mfma_f32_16x16x32_bf16 v[40:43], v[150:153], v[184:187], v[40:43]
	v_mfma_f32_16x16x32_bf16 v[28:31], v[128:131], v[192:195], v[28:31]
	v_mfma_f32_16x16x32_bf16 v[24:27], v[150:153], v[192:195], v[24:27]
	v_mfma_f32_16x16x32_bf16 v[12:15], v[128:131], v[200:203], v[12:15]
	v_mfma_f32_16x16x32_bf16 v[8:11], v[150:153], v[200:203], v[8:11]
	v_mfma_f32_16x16x32_bf16 v[60:63], v[132:135], v[180:183], v[60:63]
	v_mfma_f32_16x16x32_bf16 v[56:59], v[154:157], v[180:183], v[56:59]
	v_mfma_f32_16x16x32_bf16 v[44:47], v[132:135], v[188:191], v[44:47]
	v_mfma_f32_16x16x32_bf16 v[40:43], v[154:157], v[188:191], v[40:43]
	v_mfma_f32_16x16x32_bf16 v[28:31], v[132:135], v[196:199], v[28:31]
	v_mfma_f32_16x16x32_bf16 v[24:27], v[154:157], v[196:199], v[24:27]
	v_mfma_f32_16x16x32_bf16 v[12:15], v[132:135], v[210:213], v[12:15]
	v_mfma_f32_16x16x32_bf16 v[8:11], v[154:157], v[210:213], v[8:11]
	s_barrier
	s_add_u32 s8, s64, 0x40080
	s_addc_u32 s9, s65, 0
	s_add_i32 s7, vcc_lo, s97
	v_lshl_add_u64 v[128:129], s[8:9], 0, v[138:139]
	s_mov_b32 m0, s7
	s_nop 0
	global_load_lds_dwordx4 v[128:129], off
	v_lshl_add_u64 v[128:129], s[8:9], 0, v[136:137]
	s_add_i32 m0, s7, 0x2000
	s_nop 0
	global_load_lds_dwordx4 v[128:129], off
	s_waitcnt vmcnt(6)
	s_barrier
	v_mfma_f32_16x16x32_bf16 v[52:55], v[214:217], v[176:179], v[52:55]
	v_mfma_f32_16x16x32_bf16 v[48:51], v[222:225], v[176:179], v[48:51]
	v_mfma_f32_16x16x32_bf16 v[36:39], v[214:217], v[184:187], v[36:39]
	v_mfma_f32_16x16x32_bf16 v[32:35], v[222:225], v[184:187], v[32:35]
	v_mfma_f32_16x16x32_bf16 v[20:23], v[214:217], v[192:195], v[20:23]
	v_mfma_f32_16x16x32_bf16 v[16:19], v[222:225], v[192:195], v[16:19]
	v_mfma_f32_16x16x32_bf16 v[4:7], v[214:217], v[200:203], v[4:7]
	v_mfma_f32_16x16x32_bf16 v[0:3], v[222:225], v[200:203], v[0:3]
	v_mfma_f32_16x16x32_bf16 v[52:55], v[218:221], v[180:183], v[52:55]
	v_mfma_f32_16x16x32_bf16 v[48:51], v[226:229], v[180:183], v[48:51]
	v_mfma_f32_16x16x32_bf16 v[36:39], v[218:221], v[188:191], v[36:39]
	v_mfma_f32_16x16x32_bf16 v[32:35], v[226:229], v[188:191], v[32:35]
	v_mfma_f32_16x16x32_bf16 v[20:23], v[218:221], v[196:199], v[20:23]
	v_mfma_f32_16x16x32_bf16 v[16:19], v[226:229], v[196:199], v[16:19]
	v_mfma_f32_16x16x32_bf16 v[4:7], v[218:221], v[210:213], v[4:7]
	v_mfma_f32_16x16x32_bf16 v[0:3], v[226:229], v[210:213], v[0:3]
	s_add_i32 s6, s6, 2
	s_add_u32 s36, s36, 0x100
	s_addc_u32 s37, s37, 0
	s_add_u32 s4, s4, 0x100
	s_addc_u32 s5, s5, 0
	s_cmp_gt_u32 s6, 13
	s_barrier
	s_cbranch_scc0 .LBB0_152
	s_lshl_b32 s64, s14, 8
	s_cmp_gt_u32 s14, 15
	s_cselect_b64 s[4:5], -1, 0
	s_sub_i32 s6, s14, 28
	s_cmp_lt_u32 s6, -4
	s_cselect_b64 s[6:7], -1, 0
	s_and_b64 s[4:5], s[4:5], s[6:7]
	v_cndmask_b32_e64 v128, 0, 1, s[4:5]
	v_lshl_add_u32 v158, s25, 8, v141
	s_cmp_gt_u32 s14, 7
	v_readfirstlane_b32 s4, v128
	s_cselect_b32 s4, s4, 3
	s_cmp_gt_i32 s14, 3
	v_ashrrev_i32_e32 v159, 31, v158
	s_cselect_b32 s13, s4, 2
	v_lshlrev_b64 v[128:129], 14, v[158:159]
	s_cmp_gt_u32 s13, 1
	s_mov_b64 s[36:37], -1
	v_lshl_add_u64 v[156:157], s[46:47], 0, v[128:129]
	v_or_b32_e32 v154, 16, v158
	v_or_b32_e32 v152, 32, v158
	v_or_b32_e32 v150, 48, v158
	s_cbranch_scc0 .LBB0_155
	v_lshlrev_b64 v[128:129], 9, v[158:159]
	v_or_b32_e32 v129, v129, v147
	v_or_b32_e32 v128, v128, v146
	v_lshl_add_u64 v[132:133], s[22:23], 0, v[128:129]
	global_load_dwordx4 v[128:131], v[132:133], off offset:16
	s_nop 0
	global_load_dwordx4 v[132:135], v[132:133], off
	v_mov_b32_e32 v176, v124
	v_mov_b32_e32 v177, v120
	s_and_b32 s4, s14, -4
	s_cmp_eq_u32 s4, 4
	s_cselect_b64 vcc, -1, 0
	v_cndmask_b32_e32 v160, 1.0, v206, vcc
	s_ashr_i32 s65, s64, 31
	s_lshl_b64 s[36:37], s[64:65], 1
	v_lshl_add_u64 v[172:173], v[156:157], 0, s[36:37]
	s_mov_b32 s25, s15
	v_lshl_add_u64 v[172:173], v[172:173], 0, s[24:25]
	v_mov_b32_e32 v149, v161
	v_lshl_add_u64 v[172:173], v[172:173], 0, v[148:149]
	s_waitcnt vmcnt(0)
	v_pk_mul_f32 v[176:177], v[176:177], v[132:133]
	s_nop 0
	v_sub_f32_e32 v151, v176, v177
	v_mov_b32_e32 v176, v120
	v_mov_b32_e32 v177, v124
	v_pk_mul_f32 v[176:177], v[176:177], v[132:133]
	v_mul_f32_e32 v151, v160, v151
	v_add_f32_e32 v153, v177, v176
	v_mov_b32_e32 v176, v125
	v_mov_b32_e32 v177, v121
	v_pk_mul_f32 v[176:177], v[176:177], v[134:135]
	v_mul_f32_e32 v153, v160, v153
	v_sub_f32_e32 v155, v176, v177
	v_mov_b32_e32 v176, v121
	v_mov_b32_e32 v177, v125
	v_pk_mul_f32 v[176:177], v[176:177], v[134:135]
	v_mul_f32_e32 v155, v160, v155
	v_add_f32_e32 v159, v177, v176
	v_mov_b32_e32 v176, v126
	v_mov_b32_e32 v177, v122
	v_pk_mul_f32 v[176:177], v[176:177], v[128:129]
	v_mul_f32_e32 v159, v160, v159
	v_sub_f32_e32 v176, v176, v177
	v_mul_f32_e32 v178, v160, v176
	v_mov_b32_e32 v176, v122
	v_mov_b32_e32 v177, v126
	v_pk_mul_f32 v[176:177], v[176:177], v[128:129]
	s_nop 0
	v_add_f32_e32 v176, v177, v176
	v_mul_f32_e32 v179, v160, v176
	v_mov_b32_e32 v176, v127
	v_mov_b32_e32 v177, v123
	v_pk_mul_f32 v[176:177], v[176:177], v[130:131]
	s_nop 0
	v_sub_f32_e32 v176, v176, v177
	v_mul_f32_e32 v180, v160, v176
	v_mov_b32_e32 v176, v123
	v_mov_b32_e32 v177, v127
	v_pk_mul_f32 v[176:177], v[176:177], v[130:131]
	s_nop 0
	v_add_f32_e32 v176, v177, v176
	v_mul_f32_e32 v181, v160, v176
	v_cvt_pk_bf16_f32 v176, v151, v155
	v_cvt_pk_bf16_f32 v177, v178, v180
	v_cvt_pk_bf16_f32 v178, v153, v159
	v_cvt_pk_bf16_f32 v179, v179, v181
	global_store_dwordx2 v[172:173], v[176:177], off
; __device__ __forceinline__ unsigned cvtpk(float lo, float hi) { unsigned r; asm volatile("v_cvt_pk_bf16_f32 %0, %1, %2" : "=v"(r) : "v"(lo), "v"(hi)); return r; }
;   __device__ __forceinline__ void operator()(const f32x4 (&acc)[2][2][4][2], const pg8::Unit& u, int wr, int wc, int fr, int fq) const {
;     ...
;         for (int m = 0; m < 4; ++m) { const int row = row0 + ai * 128 + m * 16;
;           const f32x4* cs = (const f32x4*)(rope + ((size_t)row * 64 + 16 * wc + 4 * fq) * 2);
;           const f32x4 cs0 = cs[0], cs1 = cs[1];
;           const float c_[4] = {cs0[0], cs0[2], cs1[0], cs1[2]}, s_[4] = {cs0[1], cs0[3], cs1[1], cs1[3]};
;           bf16_t* rowp = O + (size_t)row * ldc + colt + 16 * wc + 4 * fq;
; #pragma unroll
;           for (int bj = 0; bj < 2; ++bj) { const f32x4 x1 = acc[ai][bj][m][0], x2 = acc[ai][bj][m][1]; float o1[4], o2[4];
; #pragma unroll
;             for (int j = 0; j < 4; ++j) { o1[j] = (x1[j] * c_[j] - x2[j] * s_[j]) * sc; o2[j] = (x1[j] * s_[j] + x2[j] * c_[j]) * sc; }
;             u32x2 w1 = {cvtpk(o1[0], o1[1]), cvtpk(o1[2], o1[3])}, w2 = {cvtpk(o2[0], o2[1]), cvtpk(o2[2], o2[3])};
;             *(u32x2*)(rowp + bj * 128) = w1; *(u32x2*)(rowp + bj * 128 + 64) = w2; } }
	global_store_dwordx2 v[172:173], v[178:179], off offset:128
	v_mov_b32_e32 v176, v116
	v_mov_b32_e32 v177, v112
	v_pk_mul_f32 v[176:177], v[176:177], v[132:133]
	s_nop 0
	v_sub_f32_e32 v151, v176, v177
	v_mov_b32_e32 v176, v112
	v_mov_b32_e32 v177, v116
	v_pk_mul_f32 v[132:133], v[176:177], v[132:133]
	v_mul_f32_e32 v151, v160, v151
	v_add_f32_e32 v132, v133, v132
	v_mul_f32_e32 v153, v160, v132
	v_mov_b32_e32 v132, v117
	v_mov_b32_e32 v133, v113
	v_pk_mul_f32 v[132:133], v[132:133], v[134:135]
	v_mov_b32_e32 v176, v108
	v_sub_f32_e32 v132, v132, v133
	v_mul_f32_e32 v155, v160, v132
	v_mov_b32_e32 v132, v113
	v_mov_b32_e32 v133, v117
	v_pk_mul_f32 v[132:133], v[132:133], v[134:135]
	v_mov_b32_e32 v177, v104
	v_add_f32_e32 v132, v133, v132
	v_mul_f32_e32 v134, v160, v132
	v_mov_b32_e32 v132, v118
	v_mov_b32_e32 v133, v114
	v_pk_mul_f32 v[132:133], v[132:133], v[128:129]
	s_nop 0
	v_sub_f32_e32 v132, v132, v133
	v_mul_f32_e32 v135, v160, v132
	v_mov_b32_e32 v132, v114
	v_mov_b32_e32 v133, v118
	v_pk_mul_f32 v[128:129], v[132:133], v[128:129]
	s_nop 0
	v_add_f32_e32 v128, v129, v128
	v_mul_f32_e32 v132, v160, v128
	v_mov_b32_e32 v128, v119
	v_mov_b32_e32 v129, v115
	v_pk_mul_f32 v[128:129], v[128:129], v[130:131]
	s_nop 0
	v_sub_f32_e32 v128, v128, v129
	v_mul_f32_e32 v133, v160, v128
	v_mov_b32_e32 v128, v115
	v_mov_b32_e32 v129, v119
	v_pk_mul_f32 v[128:129], v[128:129], v[130:131]
	s_nop 0
	v_add_f32_e32 v128, v129, v128
	v_mul_f32_e32 v131, v160, v128
	v_cvt_pk_bf16_f32 v128, v151, v155
	v_cvt_pk_bf16_f32 v129, v135, v133
	v_ashrrev_i32_e32 v155, 31, v154
	v_cvt_pk_bf16_f32 v130, v153, v134
	v_cvt_pk_bf16_f32 v131, v132, v131
	global_store_dwordx2 v[172:173], v[128:129], off offset:256
	global_store_dwordx2 v[172:173], v[130:131], off offset:384
	v_lshlrev_b64 v[128:129], 9, v[154:155]
	v_or_b32_e32 v129, v129, v147
	v_or_b32_e32 v128, v128, v146
	v_lshl_add_u64 v[132:133], s[22:23], 0, v[128:129]
	global_load_dwordx4 v[128:131], v[132:133], off offset:16
	s_nop 0
	global_load_dwordx4 v[132:135], v[132:133], off
	v_lshlrev_b64 v[172:173], 14, v[154:155]
	v_lshl_add_u64 v[172:173], s[46:47], 0, v[172:173]
	v_lshl_add_u64 v[172:173], v[172:173], 0, s[36:37]
	v_lshl_add_u64 v[172:173], v[172:173], 0, s[24:25]
	v_lshl_add_u64 v[172:173], v[172:173], 0, v[148:149]
	s_waitcnt vmcnt(0)
	v_pk_mul_f32 v[176:177], v[176:177], v[132:133]
	s_nop 0
	v_sub_f32_e32 v151, v176, v177
	v_mov_b32_e32 v176, v104
	v_mov_b32_e32 v177, v108
	v_pk_mul_f32 v[176:177], v[176:177], v[132:133]
	v_mul_f32_e32 v151, v160, v151
	v_add_f32_e32 v153, v177, v176
	v_mov_b32_e32 v176, v109
	v_mov_b32_e32 v177, v105
	v_pk_mul_f32 v[176:177], v[176:177], v[134:135]
	v_mul_f32_e32 v153, v160, v153
	v_sub_f32_e32 v155, v176, v177
	v_mov_b32_e32 v176, v105
	v_mov_b32_e32 v177, v109
	v_pk_mul_f32 v[176:177], v[176:177], v[134:135]
	v_mul_f32_e32 v155, v160, v155
	v_add_f32_e32 v159, v177, v176
	v_mov_b32_e32 v176, v110
	v_mov_b32_e32 v177, v106
	v_pk_mul_f32 v[176:177], v[176:177], v[128:129]
	v_mul_f32_e32 v159, v160, v159
	v_sub_f32_e32 v176, v176, v177
	v_mul_f32_e32 v178, v160, v176
	v_mov_b32_e32 v176, v106
	v_mov_b32_e32 v177, v110
	v_pk_mul_f32 v[176:177], v[176:177], v[128:129]
	s_nop 0
	v_add_f32_e32 v176, v177, v176
	v_mul_f32_e32 v179, v160, v176
	v_mov_b32_e32 v176, v111
	v_mov_b32_e32 v177, v107
	v_pk_mul_f32 v[176:177], v[176:177], v[130:131]
	s_nop 0
	v_sub_f32_e32 v176, v176, v177
	v_mul_f32_e32 v180, v160, v176
	v_mov_b32_e32 v176, v107
	v_mov_b32_e32 v177, v111
	v_pk_mul_f32 v[176:177], v[176:177], v[130:131]
	s_nop 0
	v_add_f32_e32 v176, v177, v176
	v_mul_f32_e32 v181, v160, v176
	v_cvt_pk_bf16_f32 v176, v151, v155
	v_cvt_pk_bf16_f32 v177, v178, v180
	v_cvt_pk_bf16_f32 v178, v153, v159
	v_cvt_pk_bf16_f32 v179, v179, v181
	global_store_dwordx2 v[172:173], v[176:177], off
	global_store_dwordx2 v[172:173], v[178:179], off offset:128
	v_mov_b32_e32 v176, v100
	v_mov_b32_e32 v177, v96
	v_pk_mul_f32 v[176:177], v[176:177], v[132:133]
	s_nop 0
	v_sub_f32_e32 v151, v176, v177
	v_mov_b32_e32 v176, v96
	v_mov_b32_e32 v177, v100
	v_pk_mul_f32 v[132:133], v[176:177], v[132:133]
	v_mul_f32_e32 v151, v160, v151
	v_add_f32_e32 v132, v133, v132
	v_mul_f32_e32 v153, v160, v132
	v_mov_b32_e32 v132, v101
	v_mov_b32_e32 v133, v97
	v_pk_mul_f32 v[132:133], v[132:133], v[134:135]
	v_mov_b32_e32 v176, v92
	v_sub_f32_e32 v132, v132, v133
	v_mul_f32_e32 v155, v160, v132
	v_mov_b32_e32 v132, v97
	v_mov_b32_e32 v133, v101
	v_pk_mul_f32 v[132:133], v[132:133], v[134:135]
	v_mov_b32_e32 v177, v88
	v_add_f32_e32 v132, v133, v132
	v_mul_f32_e32 v134, v160, v132
	v_mov_b32_e32 v132, v102
	v_mov_b32_e32 v133, v98
	v_pk_mul_f32 v[132:133], v[132:133], v[128:129]
	s_nop 0
	v_sub_f32_e32 v132, v132, v133
	v_mul_f32_e32 v135, v160, v132
	v_mov_b32_e32 v132, v98
	v_mov_b32_e32 v133, v102
	v_pk_mul_f32 v[128:129], v[132:133], v[128:129]
	s_nop 0
	v_add_f32_e32 v128, v129, v128
	v_mul_f32_e32 v132, v160, v128
	v_mov_b32_e32 v128, v103
	v_mov_b32_e32 v129, v99
	v_pk_mul_f32 v[128:129], v[128:129], v[130:131]
	s_nop 0
	v_sub_f32_e32 v128, v128, v129
	v_mul_f32_e32 v133, v160, v128
	v_mov_b32_e32 v128, v99
	v_mov_b32_e32 v129, v103
	v_pk_mul_f32 v[128:129], v[128:129], v[130:131]
	s_nop 0
	v_add_f32_e32 v128, v129, v128
	v_mul_f32_e32 v131, v160, v128
	v_cvt_pk_bf16_f32 v128, v151, v155
	v_cvt_pk_bf16_f32 v129, v135, v133
	v_cvt_pk_bf16_f32 v130, v153, v134
	v_ashrrev_i32_e32 v153, 31, v152
	v_cvt_pk_bf16_f32 v131, v132, v131
	global_store_dwordx2 v[172:173], v[128:129], off offset:256
	global_store_dwordx2 v[172:173], v[130:131], off offset:384
	v_lshlrev_b64 v[128:129], 9, v[152:153]
	v_or_b32_e32 v129, v129, v147
	v_or_b32_e32 v128, v128, v146
	v_lshl_add_u64 v[132:133], s[22:23], 0, v[128:129]
	global_load_dwordx4 v[128:131], v[132:133], off offset:16
	s_nop 0
	global_load_dwordx4 v[132:135], v[132:133], off
	v_lshlrev_b64 v[172:173], 14, v[152:153]
	v_lshl_add_u64 v[172:173], s[46:47], 0, v[172:173]
	v_lshl_add_u64 v[172:173], v[172:173], 0, s[36:37]
	v_lshl_add_u64 v[172:173], v[172:173], 0, s[24:25]
	v_lshl_add_u64 v[172:173], v[172:173], 0, v[148:149]
	s_waitcnt vmcnt(0)
; __device__ __forceinline__ unsigned cvtpk(float lo, float hi) { unsigned r; asm volatile("v_cvt_pk_bf16_f32 %0, %1, %2" : "=v"(r) : "v"(lo), "v"(hi)); return r; }
;   __device__ __forceinline__ void operator()(const f32x4 (&acc)[2][2][4][2], const pg8::Unit& u, int wr, int wc, int fr, int fq) const {
;     ...
;         for (int m = 0; m < 4; ++m) { const int row = row0 + ai * 128 + m * 16;
;           const f32x4* cs = (const f32x4*)(rope + ((size_t)row * 64 + 16 * wc + 4 * fq) * 2);
;           const f32x4 cs0 = cs[0], cs1 = cs[1];
;           const float c_[4] = {cs0[0], cs0[2], cs1[0], cs1[2]}, s_[4] = {cs0[1], cs0[3], cs1[1], cs1[3]};
;           bf16_t* rowp = O + (size_t)row * ldc + colt + 16 * wc + 4 * fq;
; #pragma unroll
;           for (int bj = 0; bj < 2; ++bj) { const f32x4 x1 = acc[ai][bj][m][0], x2 = acc[ai][bj][m][1]; float o1[4], o2[4];
; #pragma unroll
;             for (int j = 0; j < 4; ++j) { o1[j] = (x1[j] * c_[j] - x2[j] * s_[j]) * sc; o2[j] = (x1[j] * s_[j] + x2[j] * c_[j]) * sc; }
;             u32x2 w1 = {cvtpk(o1[0], o1[1]), cvtpk(o1[2], o1[3])}, w2 = {cvtpk(o2[0], o2[1]), cvtpk(o2[2], o2[3])};
;             *(u32x2*)(rowp + bj * 128) = w1; *(u32x2*)(rowp + bj * 128 + 64) = w2; } }
	v_pk_mul_f32 v[176:177], v[176:177], v[132:133]
	s_nop 0
	v_sub_f32_e32 v151, v176, v177
	v_mov_b32_e32 v176, v88
	v_mov_b32_e32 v177, v92
	v_pk_mul_f32 v[176:177], v[176:177], v[132:133]
	v_mul_f32_e32 v151, v160, v151
	v_add_f32_e32 v153, v177, v176
	v_mov_b32_e32 v176, v93
	v_mov_b32_e32 v177, v89
	v_pk_mul_f32 v[176:177], v[176:177], v[134:135]
	v_mul_f32_e32 v153, v160, v153
	v_sub_f32_e32 v155, v176, v177
	v_mov_b32_e32 v176, v89
	v_mov_b32_e32 v177, v93
	v_pk_mul_f32 v[176:177], v[176:177], v[134:135]
	v_mul_f32_e32 v155, v160, v155
	v_add_f32_e32 v159, v177, v176
	v_mov_b32_e32 v176, v94
	v_mov_b32_e32 v177, v90
	v_pk_mul_f32 v[176:177], v[176:177], v[128:129]
	v_mul_f32_e32 v159, v160, v159
	v_sub_f32_e32 v176, v176, v177
	v_mul_f32_e32 v178, v160, v176
	v_mov_b32_e32 v176, v90
	v_mov_b32_e32 v177, v94
	v_pk_mul_f32 v[176:177], v[176:177], v[128:129]
	s_nop 0
	v_add_f32_e32 v176, v177, v176
	v_mul_f32_e32 v179, v160, v176
	v_mov_b32_e32 v176, v95
	v_mov_b32_e32 v177, v91
	v_pk_mul_f32 v[176:177], v[176:177], v[130:131]
	s_nop 0
	v_sub_f32_e32 v176, v176, v177
	v_mul_f32_e32 v180, v160, v176
	v_mov_b32_e32 v176, v91
	v_mov_b32_e32 v177, v95
	v_pk_mul_f32 v[176:177], v[176:177], v[130:131]
	s_nop 0
	v_add_f32_e32 v176, v177, v176
	v_mul_f32_e32 v181, v160, v176
	v_cvt_pk_bf16_f32 v176, v151, v155
	v_cvt_pk_bf16_f32 v177, v178, v180
	v_cvt_pk_bf16_f32 v178, v153, v159
	v_cvt_pk_bf16_f32 v179, v179, v181
	global_store_dwordx2 v[172:173], v[176:177], off
	global_store_dwordx2 v[172:173], v[178:179], off offset:128
	v_mov_b32_e32 v176, v84
	v_mov_b32_e32 v177, v80
	v_pk_mul_f32 v[176:177], v[176:177], v[132:133]
	s_nop 0
	v_sub_f32_e32 v151, v176, v177
	v_mov_b32_e32 v176, v80
	v_mov_b32_e32 v177, v84
	v_pk_mul_f32 v[132:133], v[176:177], v[132:133]
	v_mul_f32_e32 v151, v160, v151
	v_add_f32_e32 v132, v133, v132
	v_mul_f32_e32 v153, v160, v132
	v_mov_b32_e32 v132, v85
	v_mov_b32_e32 v133, v81
	v_pk_mul_f32 v[132:133], v[132:133], v[134:135]
	v_mov_b32_e32 v176, v76
	v_sub_f32_e32 v132, v132, v133
	v_mul_f32_e32 v155, v160, v132
	v_mov_b32_e32 v132, v81
	v_mov_b32_e32 v133, v85
	v_pk_mul_f32 v[132:133], v[132:133], v[134:135]
	v_mov_b32_e32 v177, v72
	v_add_f32_e32 v132, v133, v132
	v_mul_f32_e32 v134, v160, v132
	v_mov_b32_e32 v132, v86
	v_mov_b32_e32 v133, v82
	v_pk_mul_f32 v[132:133], v[132:133], v[128:129]
	s_nop 0
	v_sub_f32_e32 v132, v132, v133
	v_mul_f32_e32 v135, v160, v132
	v_mov_b32_e32 v132, v82
	v_mov_b32_e32 v133, v86
	v_pk_mul_f32 v[128:129], v[132:133], v[128:129]
	s_nop 0
	v_add_f32_e32 v128, v129, v128
	v_mul_f32_e32 v132, v160, v128
	v_mov_b32_e32 v128, v87
	v_mov_b32_e32 v129, v83
	v_pk_mul_f32 v[128:129], v[128:129], v[130:131]
	s_nop 0
	v_sub_f32_e32 v128, v128, v129
	v_mul_f32_e32 v133, v160, v128
	v_mov_b32_e32 v128, v83
	v_mov_b32_e32 v129, v87
	v_pk_mul_f32 v[128:129], v[128:129], v[130:131]
	s_nop 0
	v_add_f32_e32 v128, v129, v128
	v_mul_f32_e32 v131, v160, v128
	v_cvt_pk_bf16_f32 v128, v151, v155
	v_cvt_pk_bf16_f32 v129, v135, v133
	v_ashrrev_i32_e32 v151, 31, v150
	v_cvt_pk_bf16_f32 v130, v153, v134
	v_cvt_pk_bf16_f32 v131, v132, v131
	global_store_dwordx2 v[172:173], v[128:129], off offset:256
	global_store_dwordx2 v[172:173], v[130:131], off offset:384
	v_lshlrev_b64 v[128:129], 9, v[150:151]
	v_or_b32_e32 v129, v129, v147
	v_or_b32_e32 v128, v128, v146
	v_lshl_add_u64 v[132:133], s[22:23], 0, v[128:129]
	global_load_dwordx4 v[128:131], v[132:133], off offset:16
	s_nop 0
	global_load_dwordx4 v[132:135], v[132:133], off
	v_lshlrev_b64 v[172:173], 14, v[150:151]
	v_lshl_add_u64 v[172:173], s[46:47], 0, v[172:173]
	v_lshl_add_u64 v[172:173], v[172:173], 0, s[36:37]
	v_lshl_add_u64 v[172:173], v[172:173], 0, s[24:25]
	v_lshl_add_u64 v[172:173], v[172:173], 0, v[148:149]
	s_waitcnt vmcnt(0)
	v_pk_mul_f32 v[176:177], v[176:177], v[132:133]
	s_nop 0
	v_sub_f32_e32 v151, v176, v177
	v_mov_b32_e32 v176, v72
	v_mov_b32_e32 v177, v76
	v_pk_mul_f32 v[176:177], v[176:177], v[132:133]
	v_mul_f32_e32 v151, v160, v151
	v_add_f32_e32 v153, v177, v176
	v_mov_b32_e32 v176, v77
	v_mov_b32_e32 v177, v73
	v_pk_mul_f32 v[176:177], v[176:177], v[134:135]
	v_mul_f32_e32 v153, v160, v153
	v_sub_f32_e32 v155, v176, v177
	v_mov_b32_e32 v176, v73
	v_mov_b32_e32 v177, v77
	v_pk_mul_f32 v[176:177], v[176:177], v[134:135]
	v_mul_f32_e32 v155, v160, v155
	v_add_f32_e32 v159, v177, v176
	v_mov_b32_e32 v176, v78
	v_mov_b32_e32 v177, v74
	v_pk_mul_f32 v[176:177], v[176:177], v[128:129]
	v_mul_f32_e32 v159, v160, v159
	v_sub_f32_e32 v176, v176, v177
	v_mul_f32_e32 v178, v160, v176
	v_mov_b32_e32 v176, v74
	v_mov_b32_e32 v177, v78
	v_pk_mul_f32 v[176:177], v[176:177], v[128:129]
	s_nop 0
	v_add_f32_e32 v176, v177, v176
	v_mul_f32_e32 v179, v160, v176
	v_mov_b32_e32 v176, v79
	v_mov_b32_e32 v177, v75
	v_pk_mul_f32 v[176:177], v[176:177], v[130:131]
	s_nop 0
	v_sub_f32_e32 v176, v176, v177
	v_mul_f32_e32 v180, v160, v176
	v_mov_b32_e32 v176, v75
	v_mov_b32_e32 v177, v79
	v_pk_mul_f32 v[176:177], v[176:177], v[130:131]
	s_nop 0
	v_add_f32_e32 v176, v177, v176
	v_mul_f32_e32 v181, v160, v176
	v_cvt_pk_bf16_f32 v176, v151, v155
	v_cvt_pk_bf16_f32 v177, v178, v180
	v_cvt_pk_bf16_f32 v178, v153, v159
	v_cvt_pk_bf16_f32 v179, v179, v181
	global_store_dwordx2 v[172:173], v[176:177], off
	global_store_dwordx2 v[172:173], v[178:179], off offset:128
	v_mov_b32_e32 v176, v68
	v_mov_b32_e32 v177, v64
	v_pk_mul_f32 v[176:177], v[176:177], v[132:133]
	s_nop 0
	v_sub_f32_e32 v151, v176, v177
	v_mov_b32_e32 v176, v64
	v_mov_b32_e32 v177, v68
	v_pk_mul_f32 v[132:133], v[176:177], v[132:133]
	v_mul_f32_e32 v151, v160, v151
	v_add_f32_e32 v132, v133, v132
; __device__ __forceinline__ unsigned cvtpk(float lo, float hi) { unsigned r; asm volatile("v_cvt_pk_bf16_f32 %0, %1, %2" : "=v"(r) : "v"(lo), "v"(hi)); return r; }
;   __device__ __forceinline__ void operator()(const f32x4 (&acc)[2][2][4][2], const pg8::Unit& u, int wr, int wc, int fr, int fq) const {
;     ...
;         for (int m = 0; m < 4; ++m) { const int row = row0 + ai * 128 + m * 16;
;           const f32x4* cs = (const f32x4*)(rope + ((size_t)row * 64 + 16 * wc + 4 * fq) * 2);
;           const f32x4 cs0 = cs[0], cs1 = cs[1];
;           const float c_[4] = {cs0[0], cs0[2], cs1[0], cs1[2]}, s_[4] = {cs0[1], cs0[3], cs1[1], cs1[3]};
;           bf16_t* rowp = O + (size_t)row * ldc + colt + 16 * wc + 4 * fq;
; #pragma unroll
;           for (int bj = 0; bj < 2; ++bj) { const f32x4 x1 = acc[ai][bj][m][0], x2 = acc[ai][bj][m][1]; float o1[4], o2[4];
; #pragma unroll
;             for (int j = 0; j < 4; ++j) { o1[j] = (x1[j] * c_[j] - x2[j] * s_[j]) * sc; o2[j] = (x1[j] * s_[j] + x2[j] * c_[j]) * sc; }
;             u32x2 w1 = {cvtpk(o1[0], o1[1]), cvtpk(o1[2], o1[3])}, w2 = {cvtpk(o2[0], o2[1]), cvtpk(o2[2], o2[3])};
;             *(u32x2*)(rowp + bj * 128) = w1; *(u32x2*)(rowp + bj * 128 + 64) = w2; } }
	v_mul_f32_e32 v153, v160, v132
	v_mov_b32_e32 v132, v69
	v_mov_b32_e32 v133, v65
	v_pk_mul_f32 v[132:133], v[132:133], v[134:135]
	v_mov_b32_e32 v176, v60
	v_sub_f32_e32 v132, v132, v133
	v_mul_f32_e32 v155, v160, v132
	v_mov_b32_e32 v132, v65
	v_mov_b32_e32 v133, v69
	v_pk_mul_f32 v[132:133], v[132:133], v[134:135]
	v_mov_b32_e32 v177, v56
	v_add_f32_e32 v132, v133, v132
	v_mul_f32_e32 v134, v160, v132
	v_mov_b32_e32 v132, v70
	v_mov_b32_e32 v133, v66
	v_pk_mul_f32 v[132:133], v[132:133], v[128:129]
	s_nop 0
	v_sub_f32_e32 v132, v132, v133
	v_mul_f32_e32 v135, v160, v132
	v_mov_b32_e32 v132, v66
	v_mov_b32_e32 v133, v70
	v_pk_mul_f32 v[128:129], v[132:133], v[128:129]
	s_nop 0
	v_add_f32_e32 v128, v129, v128
	v_mul_f32_e32 v132, v160, v128
	v_mov_b32_e32 v128, v71
	v_mov_b32_e32 v129, v67
	v_pk_mul_f32 v[128:129], v[128:129], v[130:131]
	s_nop 0
	v_sub_f32_e32 v128, v128, v129
	v_mul_f32_e32 v133, v160, v128
	v_mov_b32_e32 v128, v67
	v_mov_b32_e32 v129, v71
	v_pk_mul_f32 v[128:129], v[128:129], v[130:131]
	s_nop 0
	v_add_f32_e32 v128, v129, v128
	v_mul_f32_e32 v131, v160, v128
	v_cvt_pk_bf16_f32 v128, v151, v155
	v_cvt_pk_bf16_f32 v129, v135, v133
	v_cvt_pk_bf16_f32 v130, v153, v134
	v_cvt_pk_bf16_f32 v131, v132, v131
	global_store_dwordx2 v[172:173], v[128:129], off offset:256
	global_store_dwordx2 v[172:173], v[130:131], off offset:384
	v_add_u32_e32 v172, 0x80, v158
	v_ashrrev_i32_e32 v173, 31, v172
	v_lshlrev_b64 v[128:129], 9, v[172:173]
	v_or_b32_e32 v129, v129, v147
	v_or_b32_e32 v128, v128, v146
	v_lshl_add_u64 v[132:133], s[22:23], 0, v[128:129]
	global_load_dwordx4 v[128:131], v[132:133], off offset:16
	s_nop 0
	global_load_dwordx4 v[132:135], v[132:133], off
	v_lshlrev_b64 v[172:173], 14, v[172:173]
	v_lshl_add_u64 v[172:173], s[46:47], 0, v[172:173]
	v_lshl_add_u64 v[172:173], v[172:173], 0, s[36:37]
	v_lshl_add_u64 v[172:173], v[172:173], 0, s[24:25]
	v_lshl_add_u64 v[172:173], v[172:173], 0, v[148:149]
	s_waitcnt vmcnt(0)
	v_pk_mul_f32 v[176:177], v[176:177], v[132:133]
	s_nop 0
	v_sub_f32_e32 v151, v176, v177
	v_mov_b32_e32 v176, v56
	v_mov_b32_e32 v177, v60
	v_pk_mul_f32 v[176:177], v[176:177], v[132:133]
	v_mul_f32_e32 v151, v160, v151
	v_add_f32_e32 v153, v177, v176
	v_mov_b32_e32 v176, v61
	v_mov_b32_e32 v177, v57
	v_pk_mul_f32 v[176:177], v[176:177], v[134:135]
	v_mul_f32_e32 v153, v160, v153
	v_sub_f32_e32 v155, v176, v177
	v_mov_b32_e32 v176, v57
	v_mov_b32_e32 v177, v61
	v_pk_mul_f32 v[176:177], v[176:177], v[134:135]
	v_mul_f32_e32 v155, v160, v155
	v_add_f32_e32 v159, v177, v176
	v_mov_b32_e32 v176, v62
	v_mov_b32_e32 v177, v58
	v_pk_mul_f32 v[176:177], v[176:177], v[128:129]
	v_mul_f32_e32 v159, v160, v159
	v_sub_f32_e32 v176, v176, v177
	v_mul_f32_e32 v178, v160, v176
	v_mov_b32_e32 v176, v58
	v_mov_b32_e32 v177, v62
	v_pk_mul_f32 v[176:177], v[176:177], v[128:129]
	s_nop 0
	v_add_f32_e32 v176, v177, v176
	v_mul_f32_e32 v179, v160, v176
	v_mov_b32_e32 v176, v63
	v_mov_b32_e32 v177, v59
	v_pk_mul_f32 v[176:177], v[176:177], v[130:131]
	s_nop 0
	v_sub_f32_e32 v176, v176, v177
	v_mul_f32_e32 v180, v160, v176
	v_mov_b32_e32 v176, v59
	v_mov_b32_e32 v177, v63
	v_pk_mul_f32 v[176:177], v[176:177], v[130:131]
	s_nop 0
	v_add_f32_e32 v176, v177, v176
	v_mul_f32_e32 v181, v160, v176
	v_cvt_pk_bf16_f32 v176, v151, v155
	v_cvt_pk_bf16_f32 v177, v178, v180
	v_cvt_pk_bf16_f32 v178, v153, v159
	v_cvt_pk_bf16_f32 v179, v179, v181
	global_store_dwordx2 v[172:173], v[176:177], off
	global_store_dwordx2 v[172:173], v[178:179], off offset:128
	v_mov_b32_e32 v176, v52
	v_mov_b32_e32 v177, v48
	v_pk_mul_f32 v[176:177], v[176:177], v[132:133]
	s_nop 0
	v_sub_f32_e32 v151, v176, v177
	v_mov_b32_e32 v176, v48
	v_mov_b32_e32 v177, v52
	v_pk_mul_f32 v[132:133], v[176:177], v[132:133]
	v_mul_f32_e32 v151, v160, v151
	v_add_f32_e32 v132, v133, v132
	v_mul_f32_e32 v153, v160, v132
	v_mov_b32_e32 v132, v53
	v_mov_b32_e32 v133, v49
	v_pk_mul_f32 v[132:133], v[132:133], v[134:135]
	v_mov_b32_e32 v176, v44
	v_sub_f32_e32 v132, v132, v133
	v_mul_f32_e32 v155, v160, v132
	v_mov_b32_e32 v132, v49
	v_mov_b32_e32 v133, v53
	v_pk_mul_f32 v[132:133], v[132:133], v[134:135]
	v_mov_b32_e32 v177, v40
	v_add_f32_e32 v132, v133, v132
	v_mul_f32_e32 v134, v160, v132
	v_mov_b32_e32 v132, v54
	v_mov_b32_e32 v133, v50
	v_pk_mul_f32 v[132:133], v[132:133], v[128:129]
	s_nop 0
	v_sub_f32_e32 v132, v132, v133
	v_mul_f32_e32 v135, v160, v132
	v_mov_b32_e32 v132, v50
	v_mov_b32_e32 v133, v54
	v_pk_mul_f32 v[128:129], v[132:133], v[128:129]
	s_nop 0
	v_add_f32_e32 v128, v129, v128
	v_mul_f32_e32 v132, v160, v128
	v_mov_b32_e32 v128, v55
	v_mov_b32_e32 v129, v51
	v_pk_mul_f32 v[128:129], v[128:129], v[130:131]
	s_nop 0
	v_sub_f32_e32 v128, v128, v129
	v_mul_f32_e32 v133, v160, v128
	v_mov_b32_e32 v128, v51
	v_mov_b32_e32 v129, v55
	v_pk_mul_f32 v[128:129], v[128:129], v[130:131]
	s_nop 0
	v_add_f32_e32 v128, v129, v128
	v_mul_f32_e32 v131, v160, v128
	v_cvt_pk_bf16_f32 v128, v151, v155
	v_cvt_pk_bf16_f32 v129, v135, v133
	v_cvt_pk_bf16_f32 v130, v153, v134
	v_cvt_pk_bf16_f32 v131, v132, v131
	global_store_dwordx2 v[172:173], v[128:129], off offset:256
	global_store_dwordx2 v[172:173], v[130:131], off offset:384
	v_add_u32_e32 v172, 0x90, v158
	v_ashrrev_i32_e32 v173, 31, v172
	v_lshlrev_b64 v[128:129], 9, v[172:173]
	v_or_b32_e32 v129, v129, v147
	v_or_b32_e32 v128, v128, v146
	v_lshl_add_u64 v[132:133], s[22:23], 0, v[128:129]
	global_load_dwordx4 v[128:131], v[132:133], off offset:16
	s_nop 0
	global_load_dwordx4 v[132:135], v[132:133], off
	v_lshlrev_b64 v[172:173], 14, v[172:173]
	v_lshl_add_u64 v[172:173], s[46:47], 0, v[172:173]
	v_lshl_add_u64 v[172:173], v[172:173], 0, s[36:37]
	v_lshl_add_u64 v[172:173], v[172:173], 0, s[24:25]
	v_lshl_add_u64 v[172:173], v[172:173], 0, v[148:149]
	s_waitcnt vmcnt(0)
; __device__ __forceinline__ unsigned cvtpk(float lo, float hi) { unsigned r; asm volatile("v_cvt_pk_bf16_f32 %0, %1, %2" : "=v"(r) : "v"(lo), "v"(hi)); return r; }
;   __device__ __forceinline__ void operator()(const f32x4 (&acc)[2][2][4][2], const pg8::Unit& u, int wr, int wc, int fr, int fq) const {
;     ...
;         for (int m = 0; m < 4; ++m) { const int row = row0 + ai * 128 + m * 16;
;           const f32x4* cs = (const f32x4*)(rope + ((size_t)row * 64 + 16 * wc + 4 * fq) * 2);
;           const f32x4 cs0 = cs[0], cs1 = cs[1];
;           const float c_[4] = {cs0[0], cs0[2], cs1[0], cs1[2]}, s_[4] = {cs0[1], cs0[3], cs1[1], cs1[3]};
;           bf16_t* rowp = O + (size_t)row * ldc + colt + 16 * wc + 4 * fq;
; #pragma unroll
;           for (int bj = 0; bj < 2; ++bj) { const f32x4 x1 = acc[ai][bj][m][0], x2 = acc[ai][bj][m][1]; float o1[4], o2[4];
; #pragma unroll
;             for (int j = 0; j < 4; ++j) { o1[j] = (x1[j] * c_[j] - x2[j] * s_[j]) * sc; o2[j] = (x1[j] * s_[j] + x2[j] * c_[j]) * sc; }
;             u32x2 w1 = {cvtpk(o1[0], o1[1]), cvtpk(o1[2], o1[3])}, w2 = {cvtpk(o2[0], o2[1]), cvtpk(o2[2], o2[3])};
;             *(u32x2*)(rowp + bj * 128) = w1; *(u32x2*)(rowp + bj * 128 + 64) = w2; } }
	v_pk_mul_f32 v[176:177], v[176:177], v[132:133]
	s_nop 0
	v_sub_f32_e32 v151, v176, v177
	v_mov_b32_e32 v176, v40
	v_mov_b32_e32 v177, v44
	v_pk_mul_f32 v[176:177], v[176:177], v[132:133]
	v_mul_f32_e32 v151, v160, v151
	v_add_f32_e32 v153, v177, v176
	v_mov_b32_e32 v176, v45
	v_mov_b32_e32 v177, v41
	v_pk_mul_f32 v[176:177], v[176:177], v[134:135]
	v_mul_f32_e32 v153, v160, v153
	v_sub_f32_e32 v155, v176, v177
	v_mov_b32_e32 v176, v41
	v_mov_b32_e32 v177, v45
	v_pk_mul_f32 v[176:177], v[176:177], v[134:135]
	v_mul_f32_e32 v155, v160, v155
	v_add_f32_e32 v159, v177, v176
	v_mov_b32_e32 v176, v46
	v_mov_b32_e32 v177, v42
	v_pk_mul_f32 v[176:177], v[176:177], v[128:129]
	v_mul_f32_e32 v159, v160, v159
	v_sub_f32_e32 v176, v176, v177
	v_mul_f32_e32 v178, v160, v176
	v_mov_b32_e32 v176, v42
	v_mov_b32_e32 v177, v46
	v_pk_mul_f32 v[176:177], v[176:177], v[128:129]
	s_nop 0
	v_add_f32_e32 v176, v177, v176
	v_mul_f32_e32 v179, v160, v176
	v_mov_b32_e32 v176, v47
	v_mov_b32_e32 v177, v43
	v_pk_mul_f32 v[176:177], v[176:177], v[130:131]
	s_nop 0
	v_sub_f32_e32 v176, v176, v177
	v_mul_f32_e32 v180, v160, v176
	v_mov_b32_e32 v176, v43
	v_mov_b32_e32 v177, v47
	v_pk_mul_f32 v[176:177], v[176:177], v[130:131]
	s_nop 0
	v_add_f32_e32 v176, v177, v176
	v_mul_f32_e32 v181, v160, v176
	v_cvt_pk_bf16_f32 v176, v151, v155
	v_cvt_pk_bf16_f32 v177, v178, v180
	v_cvt_pk_bf16_f32 v178, v153, v159
	v_cvt_pk_bf16_f32 v179, v179, v181
	global_store_dwordx2 v[172:173], v[176:177], off
	global_store_dwordx2 v[172:173], v[178:179], off offset:128
	v_mov_b32_e32 v176, v36
	v_mov_b32_e32 v177, v32
	v_pk_mul_f32 v[176:177], v[176:177], v[132:133]
	s_nop 0
	v_sub_f32_e32 v151, v176, v177
	v_mov_b32_e32 v176, v32
	v_mov_b32_e32 v177, v36
	v_pk_mul_f32 v[132:133], v[176:177], v[132:133]
	v_mul_f32_e32 v151, v160, v151
	v_add_f32_e32 v132, v133, v132
	v_mul_f32_e32 v153, v160, v132
	v_mov_b32_e32 v132, v37
	v_mov_b32_e32 v133, v33
	v_pk_mul_f32 v[132:133], v[132:133], v[134:135]
	v_mov_b32_e32 v176, v28
	v_sub_f32_e32 v132, v132, v133
	v_mul_f32_e32 v155, v160, v132
	v_mov_b32_e32 v132, v33
	v_mov_b32_e32 v133, v37
	v_pk_mul_f32 v[132:133], v[132:133], v[134:135]
	v_mov_b32_e32 v177, v24
	v_add_f32_e32 v132, v133, v132
	v_mul_f32_e32 v134, v160, v132
	v_mov_b32_e32 v132, v38
	v_mov_b32_e32 v133, v34
	v_pk_mul_f32 v[132:133], v[132:133], v[128:129]
	s_nop 0
	v_sub_f32_e32 v132, v132, v133
	v_mul_f32_e32 v135, v160, v132
	v_mov_b32_e32 v132, v34
	v_mov_b32_e32 v133, v38
	v_pk_mul_f32 v[128:129], v[132:133], v[128:129]
	s_nop 0
	v_add_f32_e32 v128, v129, v128
	v_mul_f32_e32 v132, v160, v128
	v_mov_b32_e32 v128, v39
	v_mov_b32_e32 v129, v35
	v_pk_mul_f32 v[128:129], v[128:129], v[130:131]
	s_nop 0
	v_sub_f32_e32 v128, v128, v129
	v_mul_f32_e32 v133, v160, v128
	v_mov_b32_e32 v128, v35
	v_mov_b32_e32 v129, v39
	v_pk_mul_f32 v[128:129], v[128:129], v[130:131]
	s_nop 0
	v_add_f32_e32 v128, v129, v128
	v_mul_f32_e32 v131, v160, v128
	v_cvt_pk_bf16_f32 v128, v151, v155
	v_cvt_pk_bf16_f32 v129, v135, v133
	v_cvt_pk_bf16_f32 v130, v153, v134
	v_cvt_pk_bf16_f32 v131, v132, v131
	global_store_dwordx2 v[172:173], v[128:129], off offset:256
	global_store_dwordx2 v[172:173], v[130:131], off offset:384
	v_add_u32_e32 v172, 0xa0, v158
	v_ashrrev_i32_e32 v173, 31, v172
	v_lshlrev_b64 v[128:129], 9, v[172:173]
	v_or_b32_e32 v129, v129, v147
	v_or_b32_e32 v128, v128, v146
	v_lshl_add_u64 v[132:133], s[22:23], 0, v[128:129]
	global_load_dwordx4 v[128:131], v[132:133], off offset:16
	s_nop 0
	global_load_dwordx4 v[132:135], v[132:133], off
	v_lshlrev_b64 v[172:173], 14, v[172:173]
	v_lshl_add_u64 v[172:173], s[46:47], 0, v[172:173]
	v_lshl_add_u64 v[172:173], v[172:173], 0, s[36:37]
	v_lshl_add_u64 v[172:173], v[172:173], 0, s[24:25]
	v_lshl_add_u64 v[172:173], v[172:173], 0, v[148:149]
	v_add_u32_e32 v158, 0xb0, v158
	s_waitcnt vmcnt(0)
; __device__ __forceinline__ unsigned cvtpk(float lo, float hi) { unsigned r; asm volatile("v_cvt_pk_bf16_f32 %0, %1, %2" : "=v"(r) : "v"(lo), "v"(hi)); return r; }
;   __device__ __forceinline__ void operator()(const f32x4 (&acc)[2][2][4][2], const pg8::Unit& u, int wr, int wc, int fr, int fq) const {
;     ...
;         for (int m = 0; m < 4; ++m) { const int row = row0 + ai * 128 + m * 16;
;           const f32x4* cs = (const f32x4*)(rope + ((size_t)row * 64 + 16 * wc + 4 * fq) * 2);
;           const f32x4 cs0 = cs[0], cs1 = cs[1];
;           const float c_[4] = {cs0[0], cs0[2], cs1[0], cs1[2]}, s_[4] = {cs0[1], cs0[3], cs1[1], cs1[3]};
;           bf16_t* rowp = O + (size_t)row * ldc + colt + 16 * wc + 4 * fq;
; #pragma unroll
;           for (int bj = 0; bj < 2; ++bj) { const f32x4 x1 = acc[ai][bj][m][0], x2 = acc[ai][bj][m][1]; float o1[4], o2[4];
; #pragma unroll
;             for (int j = 0; j < 4; ++j) { o1[j] = (x1[j] * c_[j] - x2[j] * s_[j]) * sc; o2[j] = (x1[j] * s_[j] + x2[j] * c_[j]) * sc; }
;             u32x2 w1 = {cvtpk(o1[0], o1[1]), cvtpk(o1[2], o1[3])}, w2 = {cvtpk(o2[0], o2[1]), cvtpk(o2[2], o2[3])};
;             *(u32x2*)(rowp + bj * 128) = w1; *(u32x2*)(rowp + bj * 128 + 64) = w2; } }
	v_pk_mul_f32 v[176:177], v[176:177], v[132:133]
	s_nop 0
	v_sub_f32_e32 v151, v176, v177
	v_mov_b32_e32 v176, v24
	v_mov_b32_e32 v177, v28
	v_pk_mul_f32 v[176:177], v[176:177], v[132:133]
	v_mul_f32_e32 v151, v160, v151
	v_add_f32_e32 v153, v177, v176
	v_mov_b32_e32 v176, v29
	v_mov_b32_e32 v177, v25
	v_pk_mul_f32 v[176:177], v[176:177], v[134:135]
	v_mul_f32_e32 v153, v160, v153
	v_sub_f32_e32 v155, v176, v177
	v_mov_b32_e32 v176, v25
	v_mov_b32_e32 v177, v29
	v_pk_mul_f32 v[176:177], v[176:177], v[134:135]
	v_mul_f32_e32 v155, v160, v155
	v_add_f32_e32 v159, v177, v176
	v_mov_b32_e32 v176, v30
	v_mov_b32_e32 v177, v26
	v_pk_mul_f32 v[176:177], v[176:177], v[128:129]
	v_mul_f32_e32 v159, v160, v159
	v_sub_f32_e32 v176, v176, v177
	v_mul_f32_e32 v178, v160, v176
	v_mov_b32_e32 v176, v26
	v_mov_b32_e32 v177, v30
	v_pk_mul_f32 v[176:177], v[176:177], v[128:129]
	s_nop 0
	v_add_f32_e32 v176, v177, v176
	v_mul_f32_e32 v179, v160, v176
	v_mov_b32_e32 v176, v31
	v_mov_b32_e32 v177, v27
	v_pk_mul_f32 v[176:177], v[176:177], v[130:131]
	s_nop 0
	v_sub_f32_e32 v176, v176, v177
	v_mul_f32_e32 v180, v160, v176
	v_mov_b32_e32 v176, v27
	v_mov_b32_e32 v177, v31
	v_pk_mul_f32 v[176:177], v[176:177], v[130:131]
	s_nop 0
	v_add_f32_e32 v176, v177, v176
	v_mul_f32_e32 v181, v160, v176
	v_cvt_pk_bf16_f32 v176, v151, v155
	v_cvt_pk_bf16_f32 v177, v178, v180
	v_cvt_pk_bf16_f32 v178, v153, v159
	v_cvt_pk_bf16_f32 v179, v179, v181
	global_store_dwordx2 v[172:173], v[176:177], off
	global_store_dwordx2 v[172:173], v[178:179], off offset:128
	v_mov_b32_e32 v176, v20
	v_mov_b32_e32 v177, v16
	v_pk_mul_f32 v[176:177], v[176:177], v[132:133]
	v_ashrrev_i32_e32 v159, 31, v158
	v_sub_f32_e32 v151, v176, v177
	v_mov_b32_e32 v176, v16
	v_mov_b32_e32 v177, v20
	v_pk_mul_f32 v[132:133], v[176:177], v[132:133]
	v_mul_f32_e32 v151, v160, v151
	v_add_f32_e32 v132, v133, v132
	v_mul_f32_e32 v153, v160, v132
	v_mov_b32_e32 v132, v21
	v_mov_b32_e32 v133, v17
	v_pk_mul_f32 v[132:133], v[132:133], v[134:135]
	s_nop 0
	v_sub_f32_e32 v132, v132, v133
	v_mul_f32_e32 v155, v160, v132
	v_mov_b32_e32 v132, v17
	v_mov_b32_e32 v133, v21
	v_pk_mul_f32 v[132:133], v[132:133], v[134:135]
	s_nop 0
	v_add_f32_e32 v132, v133, v132
	v_mul_f32_e32 v134, v160, v132
	v_mov_b32_e32 v132, v22
	v_mov_b32_e32 v133, v18
	v_pk_mul_f32 v[132:133], v[132:133], v[128:129]
	s_nop 0
	v_sub_f32_e32 v132, v132, v133
	v_mul_f32_e32 v135, v160, v132
	v_mov_b32_e32 v132, v18
	v_mov_b32_e32 v133, v22
	v_pk_mul_f32 v[128:129], v[132:133], v[128:129]
	s_nop 0
	v_add_f32_e32 v128, v129, v128
	v_mul_f32_e32 v132, v160, v128
	v_mov_b32_e32 v128, v23
	v_mov_b32_e32 v129, v19
	v_pk_mul_f32 v[128:129], v[128:129], v[130:131]
	s_nop 0
	v_sub_f32_e32 v128, v128, v129
	v_mul_f32_e32 v133, v160, v128
	v_mov_b32_e32 v128, v19
	v_mov_b32_e32 v129, v23
	v_pk_mul_f32 v[128:129], v[128:129], v[130:131]
	s_nop 0
	v_add_f32_e32 v128, v129, v128
	v_mul_f32_e32 v131, v160, v128
	v_cvt_pk_bf16_f32 v128, v151, v155
	v_cvt_pk_bf16_f32 v129, v135, v133
	v_cvt_pk_bf16_f32 v130, v153, v134
	v_cvt_pk_bf16_f32 v131, v132, v131
	global_store_dwordx2 v[172:173], v[128:129], off offset:256
	global_store_dwordx2 v[172:173], v[130:131], off offset:384
	v_lshlrev_b64 v[128:129], 9, v[158:159]
	v_or_b32_e32 v129, v129, v147
	v_or_b32_e32 v128, v128, v146
	v_lshl_add_u64 v[132:133], s[22:23], 0, v[128:129]
	global_load_dwordx4 v[128:131], v[132:133], off offset:16
	s_nop 0
	global_load_dwordx4 v[132:135], v[132:133], off
	v_lshlrev_b64 v[158:159], 14, v[158:159]
	v_lshl_add_u64 v[158:159], s[46:47], 0, v[158:159]
	v_lshl_add_u64 v[158:159], v[158:159], 0, s[36:37]
	v_mov_b32_e32 v172, v12
	v_mov_b32_e32 v173, v8
	v_lshl_add_u64 v[158:159], v[158:159], 0, s[24:25]
	v_lshl_add_u64 v[158:159], v[158:159], 0, v[148:149]
	s_mov_b64 s[36:37], 0
	s_waitcnt vmcnt(0)
	v_pk_mul_f32 v[172:173], v[172:173], v[132:133]
	s_nop 0
	v_sub_f32_e32 v149, v172, v173
	v_mov_b32_e32 v172, v8
	v_mov_b32_e32 v173, v12
	v_pk_mul_f32 v[172:173], v[172:173], v[132:133]
	v_mul_f32_e32 v149, v160, v149
	v_add_f32_e32 v151, v173, v172
	v_mov_b32_e32 v172, v13
	v_mov_b32_e32 v173, v9
	v_pk_mul_f32 v[172:173], v[172:173], v[134:135]
	v_mul_f32_e32 v151, v160, v151
	v_sub_f32_e32 v153, v172, v173
	v_mov_b32_e32 v172, v9
	v_mov_b32_e32 v173, v13
	v_pk_mul_f32 v[172:173], v[172:173], v[134:135]
	v_mul_f32_e32 v153, v160, v153
	v_add_f32_e32 v155, v173, v172
	v_mov_b32_e32 v172, v14
	v_mov_b32_e32 v173, v10
	v_pk_mul_f32 v[172:173], v[172:173], v[128:129]
	v_mul_f32_e32 v155, v160, v155
	v_sub_f32_e32 v172, v172, v173
	v_mul_f32_e32 v176, v160, v172
	v_mov_b32_e32 v172, v10
	v_mov_b32_e32 v173, v14
	v_pk_mul_f32 v[172:173], v[172:173], v[128:129]
	s_nop 0
	v_add_f32_e32 v172, v173, v172
	v_mul_f32_e32 v177, v160, v172
	v_mov_b32_e32 v172, v15
	v_mov_b32_e32 v173, v11
	v_pk_mul_f32 v[172:173], v[172:173], v[130:131]
	s_nop 0
	v_sub_f32_e32 v172, v172, v173
	v_mul_f32_e32 v178, v160, v172
	v_mov_b32_e32 v172, v11
	v_mov_b32_e32 v173, v15
	v_pk_mul_f32 v[172:173], v[172:173], v[130:131]
	s_nop 0
	v_add_f32_e32 v172, v173, v172
	v_mul_f32_e32 v179, v160, v172
	v_cvt_pk_bf16_f32 v172, v149, v153
	v_cvt_pk_bf16_f32 v173, v176, v178
	v_cvt_pk_bf16_f32 v176, v151, v155
	v_cvt_pk_bf16_f32 v177, v177, v179
	global_store_dwordx2 v[158:159], v[172:173], off
	global_store_dwordx2 v[158:159], v[176:177], off offset:128
	v_mov_b32_e32 v172, v4
	v_mov_b32_e32 v173, v0
	v_pk_mul_f32 v[172:173], v[172:173], v[132:133]
	s_nop 0
	v_sub_f32_e32 v149, v172, v173
	v_mov_b32_e32 v172, v0
	v_mov_b32_e32 v173, v4
	v_pk_mul_f32 v[132:133], v[172:173], v[132:133]
	v_mul_f32_e32 v149, v160, v149
	v_add_f32_e32 v132, v133, v132
	v_mul_f32_e32 v151, v160, v132
	v_mov_b32_e32 v132, v5
	v_mov_b32_e32 v133, v1
	v_pk_mul_f32 v[132:133], v[132:133], v[134:135]
	s_nop 0
	v_sub_f32_e32 v132, v132, v133
	v_mul_f32_e32 v153, v160, v132
	v_mov_b32_e32 v132, v1
	v_mov_b32_e32 v133, v5
	v_pk_mul_f32 v[132:133], v[132:133], v[134:135]
	s_nop 0
	v_add_f32_e32 v132, v133, v132
	v_mul_f32_e32 v134, v160, v132
	v_mov_b32_e32 v132, v6
	v_mov_b32_e32 v133, v2
	v_pk_mul_f32 v[132:133], v[132:133], v[128:129]
	s_nop 0
	v_sub_f32_e32 v132, v132, v133
	v_mul_f32_e32 v135, v160, v132
	v_mov_b32_e32 v132, v2
	v_mov_b32_e32 v133, v6
	v_pk_mul_f32 v[128:129], v[132:133], v[128:129]
	s_nop 0
	v_add_f32_e32 v128, v129, v128
	v_mul_f32_e32 v132, v160, v128
	v_mov_b32_e32 v128, v7
	v_mov_b32_e32 v129, v3
	v_pk_mul_f32 v[128:129], v[128:129], v[130:131]
	s_nop 0
	v_sub_f32_e32 v128, v128, v129
	v_mul_f32_e32 v133, v160, v128
	v_mov_b32_e32 v128, v3
	v_mov_b32_e32 v129, v7
	v_pk_mul_f32 v[128:129], v[128:129], v[130:131]
	s_nop 0
	v_add_f32_e32 v128, v129, v128
	v_mul_f32_e32 v131, v160, v128
	v_cvt_pk_bf16_f32 v128, v149, v153
	v_cvt_pk_bf16_f32 v129, v135, v133
	v_cvt_pk_bf16_f32 v130, v151, v134
	v_cvt_pk_bf16_f32 v131, v132, v131
	global_store_dwordx2 v[158:159], v[128:129], off offset:256
	global_store_dwordx2 v[158:159], v[130:131], off offset:384

; #define PG8_STAGE(bufoff, gbase, voff) do { _Pragma("unroll") for (int _i = 0; _i < 2; ++_i) \
;     __builtin_amdgcn_global_load_lds((const unsigned*)((const char*)(gbase) + (voff)[_i]), (LAS unsigned*)(lds + (bufoff) + ldsw + _i * 8192), 16, 0, 0); } while (0)
; #define PG8_LDA(dst, b, h) do { _Pragma("unroll") for (int m = 0; m < 4; ++m) _Pragma("unroll") for (int k = 0; k < 2; ++k) dst[m][k] = *(const LAS bf16x8*)(lds + PG8_SA(b, h) + aoff + m * 2048 + k * 1024); } while (0)
; #define PG8_LDB(dst, b, h) do { _Pragma("unroll") for (int n = 0; n < 2; ++n) _Pragma("unroll") for (int k = 0; k < 2; ++k) dst[n][k] = *(const LAS bf16x8*)(lds + PG8_SB(b, h) + boff + n * 2048 + k * 1024); } while (0)
; #define PG8_MMA(ai, bj, At, Bt) do { __builtin_amdgcn_s_setprio(1); _Pragma("unroll") for (int m = 0; m < 4; ++m) _Pragma("unroll") for (int n = 0; n < 2; ++n) _Pragma("unroll") for (int k = 0; k < 2; ++k) \
;     acc[ai][bj][m][n] = __builtin_amdgcn_mfma_f32_16x16x32_bf16(Bt[n][k], At[m][k], acc[ai][bj][m][n], 0, 0, 0); __builtin_amdgcn_s_setprio(0); } while (0)
; #define PG8_WAIT_L(n) asm volatile("s_waitcnt lgkmcnt(" #n ")" ::: "memory")
; #define PG8_BAR __builtin_amdgcn_s_barrier()
; #define PG8_SCHED __builtin_amdgcn_sched_barrier(0)
; template <class Epi, class Sched>
; __device__ __forceinline__ void gemm_phase(LAS unsigned char* lds, const Gemm g, const Sched& S, const Epi& E) {
;     ...
;       PG8_LDB(B0, 0, 0); PG8_SCHED; PG8_LDA(At, 0, 0); PG8_STAGE(PG8_SA(1, 1), a1 + hstepA, voffA);
;       PG8_WAIT_L(8); PG8_BAR; PG8_WAIT_L(0); PG8_MMA(0, 0, At, B0); PG8_BAR; PG8_SCHED;
;       PG8_LDB(B1, 0, 1); PG8_STAGE(PG8_SB(0, 0), b2, voffB);
;       PG8_BAR; PG8_WAIT_L(0); PG8_MMA(0, 1, At, B1); PG8_BAR;
;       PG8_LDA(At, 0, 1); PG8_STAGE(PG8_SA(0, 0), a2, voffA);
;       PG8_BAR; PG8_WAIT_L(0); PG8_MMA(1, 0, At, B0); PG8_BAR; PG8_SCHED;
.LBB0_195:
	s_add_u32 s5, s41, s12
	s_addc_u32 s6, s42, s13
	s_add_u32 s5, s5, 0x7800100
	s_addc_u32 s6, s6, 0
	s_add_u32 s7, s43, s12
	s_addc_u32 s8, s64, s13
	s_add_i32 s9, 0, 0x10000
	v_add_u32_e32 v150, s9, v136
	ds_read_b128 v[138:141], v150
	ds_read_b128 v[142:145], v150 offset:1024
	ds_read_b128 v[146:149], v150 offset:2048
	ds_read_b128 v[150:153], v150 offset:3072
	s_cmpk_eq_i32 s12, 0x700
	s_cselect_b32 s25, s31, s6
	s_cselect_b32 s24, s30, s5
	s_cselect_b32 s19, s29, s8
	s_cselect_b32 s18, s28, s7
	v_lshl_add_u64 v[158:159], v[132:133], 0, s[12:13]
	s_add_i32 m0, s14, 0xc000
	ds_read_b128 v[154:157], v137
	ds_read_b128 v[172:175], v137 offset:1024
	ds_read_b128 v[176:179], v137 offset:2048
	ds_read_b128 v[180:183], v137 offset:3072
	ds_read_b128 v[184:187], v137 offset:4096
	ds_read_b128 v[188:191], v137 offset:5120
	ds_read_b128 v[192:195], v137 offset:6144
	ds_read_b128 v[196:199], v137 offset:7168
	global_load_lds_dwordx4 v[158:159], off
	v_lshl_add_u64 v[158:159], v[134:135], 0, s[12:13]
	s_add_i32 m0, s14, 0xe000
	s_nop 0
	global_load_lds_dwordx4 v[158:159], off
	s_waitcnt lgkmcnt(8)
	s_barrier
	s_waitcnt lgkmcnt(0)
	s_waitcnt lgkmcnt(0)
	v_mfma_f32_16x16x32_bf16 v[124:127], v[138:141], v[154:157], v[124:127]
	v_mfma_f32_16x16x32_bf16 v[120:123], v[146:149], v[154:157], v[120:123]
	v_mfma_f32_16x16x32_bf16 v[112:115], v[138:141], v[176:179], v[112:115]
	v_mfma_f32_16x16x32_bf16 v[104:107], v[146:149], v[176:179], v[104:107]
	v_mfma_f32_16x16x32_bf16 v[96:99], v[138:141], v[184:187], v[96:99]
	v_mfma_f32_16x16x32_bf16 v[88:91], v[146:149], v[184:187], v[88:91]
	v_mfma_f32_16x16x32_bf16 v[80:83], v[138:141], v[192:195], v[80:83]
	v_mfma_f32_16x16x32_bf16 v[72:75], v[146:149], v[192:195], v[72:75]
	v_mfma_f32_16x16x32_bf16 v[124:127], v[142:145], v[172:175], v[124:127]
	v_mfma_f32_16x16x32_bf16 v[120:123], v[150:153], v[172:175], v[120:123]
	v_mfma_f32_16x16x32_bf16 v[112:115], v[142:145], v[180:183], v[112:115]
	v_mfma_f32_16x16x32_bf16 v[104:107], v[150:153], v[180:183], v[104:107]
	v_mfma_f32_16x16x32_bf16 v[96:99], v[142:145], v[188:191], v[96:99]
	v_mfma_f32_16x16x32_bf16 v[88:91], v[150:153], v[188:191], v[88:91]
	v_mfma_f32_16x16x32_bf16 v[80:83], v[142:145], v[196:199], v[80:83]
	v_mfma_f32_16x16x32_bf16 v[72:75], v[150:153], v[196:199], v[72:75]
	s_barrier
	s_add_i32 s5, 0, 0x14000
	v_add_u32_e32 v158, s5, v136
	s_add_i32 s6, s9, s1
	ds_read_b128 v[200:203], v158
	ds_read_b128 v[210:213], v158 offset:1024
	ds_read_b128 v[214:217], v158 offset:2048
	ds_read_b128 v[218:221], v158 offset:3072
	v_lshl_add_u64 v[158:159], s[18:19], 0, v[160:161]
	s_mov_b32 m0, s6
	v_lshl_add_u64 v[222:223], s[18:19], 0, v[130:131]
	global_load_lds_dwordx4 v[158:159], off
	s_add_i32 m0, s6, 0x2000
	s_nop 0
	global_load_lds_dwordx4 v[222:223], off
	s_barrier
	s_waitcnt lgkmcnt(0)
	s_waitcnt lgkmcnt(0)
	v_mfma_f32_16x16x32_bf16 v[116:119], v[200:203], v[154:157], v[116:119]
	v_mfma_f32_16x16x32_bf16 v[108:111], v[214:217], v[154:157], v[108:111]
	v_mfma_f32_16x16x32_bf16 v[100:103], v[200:203], v[176:179], v[100:103]
	v_mfma_f32_16x16x32_bf16 v[92:95], v[214:217], v[176:179], v[92:95]
	v_mfma_f32_16x16x32_bf16 v[84:87], v[200:203], v[184:187], v[84:87]
	v_mfma_f32_16x16x32_bf16 v[76:79], v[214:217], v[184:187], v[76:79]
	v_mfma_f32_16x16x32_bf16 v[68:71], v[200:203], v[192:195], v[68:71]
	v_mfma_f32_16x16x32_bf16 v[64:67], v[214:217], v[192:195], v[64:67]
	v_mfma_f32_16x16x32_bf16 v[116:119], v[210:213], v[172:175], v[116:119]
	v_mfma_f32_16x16x32_bf16 v[108:111], v[218:221], v[172:175], v[108:111]
	v_mfma_f32_16x16x32_bf16 v[100:103], v[210:213], v[180:183], v[100:103]
	v_mfma_f32_16x16x32_bf16 v[92:95], v[218:221], v[180:183], v[92:95]
	v_mfma_f32_16x16x32_bf16 v[84:87], v[210:213], v[188:191], v[84:87]
	v_mfma_f32_16x16x32_bf16 v[76:79], v[218:221], v[188:191], v[76:79]
	v_mfma_f32_16x16x32_bf16 v[68:71], v[210:213], v[196:199], v[68:71]
	v_mfma_f32_16x16x32_bf16 v[64:67], v[218:221], v[196:199], v[64:67]
	s_mov_b32 m0, s14
	v_lshl_add_u64 v[224:225], s[24:25], 0, v[160:161]
	s_barrier
	ds_read_b128 v[154:157], v137 offset:16384
	ds_read_b128 v[172:175], v137 offset:17408
	ds_read_b128 v[176:179], v137 offset:18432
	ds_read_b128 v[180:183], v137 offset:19456
	ds_read_b128 v[184:187], v137 offset:20480
	ds_read_b128 v[188:191], v137 offset:21504
	ds_read_b128 v[192:195], v137 offset:22528
	ds_read_b128 v[196:199], v137 offset:23552
	global_load_lds_dwordx4 v[224:225], off
	v_lshl_add_u64 v[226:227], s[24:25], 0, v[130:131]
	s_mov_b32 m0, s34
	s_nop 0
	global_load_lds_dwordx4 v[226:227], off
	s_barrier
	s_waitcnt lgkmcnt(0)
	s_waitcnt lgkmcnt(0)
	v_mfma_f32_16x16x32_bf16 v[60:63], v[138:141], v[154:157], v[60:63]
	v_mfma_f32_16x16x32_bf16 v[56:59], v[146:149], v[154:157], v[56:59]
	v_mfma_f32_16x16x32_bf16 v[52:55], v[138:141], v[176:179], v[52:55]
	v_mfma_f32_16x16x32_bf16 v[44:47], v[146:149], v[176:179], v[44:47]
	v_mfma_f32_16x16x32_bf16 v[36:39], v[138:141], v[184:187], v[36:39]
	v_mfma_f32_16x16x32_bf16 v[28:31], v[146:149], v[184:187], v[28:31]
	v_mfma_f32_16x16x32_bf16 v[20:23], v[138:141], v[192:195], v[20:23]
	v_mfma_f32_16x16x32_bf16 v[12:15], v[146:149], v[192:195], v[12:15]
	v_mfma_f32_16x16x32_bf16 v[60:63], v[142:145], v[172:175], v[60:63]
	v_mfma_f32_16x16x32_bf16 v[56:59], v[150:153], v[172:175], v[56:59]
	v_mfma_f32_16x16x32_bf16 v[52:55], v[142:145], v[180:183], v[52:55]
	v_mfma_f32_16x16x32_bf16 v[44:47], v[150:153], v[180:183], v[44:47]
	v_mfma_f32_16x16x32_bf16 v[36:39], v[142:145], v[188:191], v[36:39]
	v_mfma_f32_16x16x32_bf16 v[28:31], v[150:153], v[188:191], v[28:31]
	v_mfma_f32_16x16x32_bf16 v[20:23], v[142:145], v[196:199], v[20:23]
	v_mfma_f32_16x16x32_bf16 v[12:15], v[150:153], v[196:199], v[12:15]
	s_barrier
; #define PG8_STAGE(bufoff, gbase, voff) do { _Pragma("unroll") for (int _i = 0; _i < 2; ++_i) \
;     __builtin_amdgcn_global_load_lds((const unsigned*)((const char*)(gbase) + (voff)[_i]), (LAS unsigned*)(lds + (bufoff) + ldsw + _i * 8192), 16, 0, 0); } while (0)
; #define PG8_LDA(dst, b, h) do { _Pragma("unroll") for (int m = 0; m < 4; ++m) _Pragma("unroll") for (int k = 0; k < 2; ++k) dst[m][k] = *(const LAS bf16x8*)(lds + PG8_SA(b, h) + aoff + m * 2048 + k * 1024); } while (0)
; #define PG8_LDB(dst, b, h) do { _Pragma("unroll") for (int n = 0; n < 2; ++n) _Pragma("unroll") for (int k = 0; k < 2; ++k) dst[n][k] = *(const LAS bf16x8*)(lds + PG8_SB(b, h) + boff + n * 2048 + k * 1024); } while (0)
; #define PG8_MMA(ai, bj, At, Bt) do { __builtin_amdgcn_s_setprio(1); _Pragma("unroll") for (int m = 0; m < 4; ++m) _Pragma("unroll") for (int n = 0; n < 2; ++n) _Pragma("unroll") for (int k = 0; k < 2; ++k) \
;     acc[ai][bj][m][n] = __builtin_amdgcn_mfma_f32_16x16x32_bf16(Bt[n][k], At[m][k], acc[ai][bj][m][n], 0, 0, 0); __builtin_amdgcn_s_setprio(0); } while (0)
; #define PG8_WAIT_V(n) asm volatile("s_waitcnt vmcnt(" #n ")" ::: "memory")
; #define PG8_WAIT_L(n) asm volatile("s_waitcnt lgkmcnt(" #n ")" ::: "memory")
; #define PG8_BAR __builtin_amdgcn_s_barrier()
; #define PG8_SCHED __builtin_amdgcn_sched_barrier(0)
; template <class Epi, class Sched>
; __device__ __forceinline__ void gemm_phase(LAS unsigned char* lds, const Gemm g, const Sched& S, const Epi& E) {
;     ...
;       PG8_STAGE(PG8_SB(0, 1), b2 + hstepB, voffB);
;       PG8_WAIT_V(6); PG8_BAR; PG8_MMA(1, 1, At, B1); PG8_BAR;
;       PG8_LDB(B0, 1, 0); PG8_SCHED; PG8_LDA(At, 1, 0); PG8_STAGE(PG8_SA(0, 1), a2 + hstepA, voffA);
;       PG8_WAIT_L(8); PG8_BAR; PG8_WAIT_L(0); PG8_MMA(0, 0, At, B0); PG8_BAR; PG8_SCHED;
;       PG8_LDB(B1, 1, 1); PG8_STAGE(PG8_SB(1, 0), b3, voffB);
;       PG8_BAR; PG8_WAIT_L(0); PG8_MMA(0, 1, At, B1); PG8_BAR;
;       PG8_LDA(At, 1, 1); PG8_STAGE(PG8_SA(1, 0), a3, voffA);
;       PG8_BAR; PG8_WAIT_L(0); PG8_MMA(1, 0, At, B0); PG8_BAR; PG8_SCHED;
	s_add_u32 s6, s18, 0x40000
	s_addc_u32 s7, s19, 0
	s_add_i32 s5, s5, s1
	v_lshl_add_u64 v[138:139], s[6:7], 0, v[160:161]
	s_mov_b32 m0, s5
	s_nop 0
	global_load_lds_dwordx4 v[138:139], off
	v_lshl_add_u64 v[138:139], s[6:7], 0, v[130:131]
	s_add_i32 m0, s5, 0x2000
	s_nop 0
	global_load_lds_dwordx4 v[138:139], off
	s_waitcnt vmcnt(6)
	s_barrier
	v_mfma_f32_16x16x32_bf16 v[48:51], v[200:203], v[154:157], v[48:51]
	v_mfma_f32_16x16x32_bf16 v[40:43], v[214:217], v[154:157], v[40:43]
	v_mfma_f32_16x16x32_bf16 v[32:35], v[200:203], v[176:179], v[32:35]
	v_mfma_f32_16x16x32_bf16 v[24:27], v[214:217], v[176:179], v[24:27]
	v_mfma_f32_16x16x32_bf16 v[16:19], v[200:203], v[184:187], v[16:19]
	v_mfma_f32_16x16x32_bf16 v[8:11], v[214:217], v[184:187], v[8:11]
	v_mfma_f32_16x16x32_bf16 v[4:7], v[200:203], v[192:195], v[4:7]
	v_mfma_f32_16x16x32_bf16 v[0:3], v[214:217], v[192:195], v[0:3]
	v_mfma_f32_16x16x32_bf16 v[48:51], v[210:213], v[172:175], v[48:51]
	v_mfma_f32_16x16x32_bf16 v[40:43], v[218:221], v[172:175], v[40:43]
	v_mfma_f32_16x16x32_bf16 v[32:35], v[210:213], v[180:183], v[32:35]
	v_mfma_f32_16x16x32_bf16 v[24:27], v[218:221], v[180:183], v[24:27]
	v_mfma_f32_16x16x32_bf16 v[16:19], v[210:213], v[188:191], v[16:19]
	v_mfma_f32_16x16x32_bf16 v[8:11], v[218:221], v[188:191], v[8:11]
	v_mfma_f32_16x16x32_bf16 v[4:7], v[210:213], v[196:199], v[4:7]
	v_mfma_f32_16x16x32_bf16 v[0:3], v[218:221], v[196:199], v[0:3]
	s_add_i32 s5, 0, 0x18000
	v_add_u32_e32 v150, s5, v136
	s_barrier
	ds_read_b128 v[138:141], v150
	ds_read_b128 v[142:145], v150 offset:1024
	ds_read_b128 v[146:149], v150 offset:2048
	ds_read_b128 v[150:153], v150 offset:3072
	s_add_u32 s6, s24, 0x40000
	s_addc_u32 s7, s25, 0
	s_mov_b32 m0, s35
	v_lshl_add_u64 v[200:201], s[6:7], 0, v[160:161]
	ds_read_b128 v[154:157], v137 offset:32768
	ds_read_b128 v[172:175], v137 offset:33792
	ds_read_b128 v[176:179], v137 offset:34816
	ds_read_b128 v[180:183], v137 offset:35840
	ds_read_b128 v[184:187], v137 offset:36864
	ds_read_b128 v[188:191], v137 offset:37888
	ds_read_b128 v[192:195], v137 offset:38912
	ds_read_b128 v[196:199], v137 offset:39936
	global_load_lds_dwordx4 v[200:201], off
	v_lshl_add_u64 v[200:201], s[6:7], 0, v[130:131]
	s_mov_b32 m0, s36
	s_nop 0
	global_load_lds_dwordx4 v[200:201], off
	s_waitcnt lgkmcnt(8)
	s_barrier
	s_waitcnt lgkmcnt(0)
	s_waitcnt lgkmcnt(0)
	v_mfma_f32_16x16x32_bf16 v[124:127], v[138:141], v[154:157], v[124:127]
	v_mfma_f32_16x16x32_bf16 v[120:123], v[146:149], v[154:157], v[120:123]
	v_mfma_f32_16x16x32_bf16 v[112:115], v[138:141], v[176:179], v[112:115]
	v_mfma_f32_16x16x32_bf16 v[104:107], v[146:149], v[176:179], v[104:107]
	v_mfma_f32_16x16x32_bf16 v[96:99], v[138:141], v[184:187], v[96:99]
	v_mfma_f32_16x16x32_bf16 v[88:91], v[146:149], v[184:187], v[88:91]
	v_mfma_f32_16x16x32_bf16 v[80:83], v[138:141], v[192:195], v[80:83]
	v_mfma_f32_16x16x32_bf16 v[72:75], v[146:149], v[192:195], v[72:75]
	v_mfma_f32_16x16x32_bf16 v[124:127], v[142:145], v[172:175], v[124:127]
	v_mfma_f32_16x16x32_bf16 v[120:123], v[150:153], v[172:175], v[120:123]
	v_mfma_f32_16x16x32_bf16 v[112:115], v[142:145], v[180:183], v[112:115]
	v_mfma_f32_16x16x32_bf16 v[104:107], v[150:153], v[180:183], v[104:107]
	v_mfma_f32_16x16x32_bf16 v[96:99], v[142:145], v[188:191], v[96:99]
	v_mfma_f32_16x16x32_bf16 v[88:91], v[150:153], v[188:191], v[88:91]
	v_mfma_f32_16x16x32_bf16 v[80:83], v[142:145], v[196:199], v[80:83]
	v_mfma_f32_16x16x32_bf16 v[72:75], v[150:153], v[196:199], v[72:75]
	s_barrier
	s_add_i32 s8, 0, 0x1c000
	s_add_i32 s5, s5, s1
	v_add_u32_e32 v209, s8, v136
	v_lshl_add_u64 v[158:159], v[158:159], 0, s[10:11]
	s_mov_b32 m0, s5
	ds_read_b128 v[200:203], v209
	ds_read_b128 v[210:213], v209 offset:1024
	ds_read_b128 v[214:217], v209 offset:2048
	ds_read_b128 v[218:221], v209 offset:3072
	global_load_lds_dwordx4 v[158:159], off
	v_lshl_add_u64 v[158:159], v[222:223], 0, s[10:11]
	s_add_i32 m0, s5, 0x2000
	s_nop 0
	global_load_lds_dwordx4 v[158:159], off
	s_barrier
	s_waitcnt lgkmcnt(0)
	s_waitcnt lgkmcnt(0)
	v_mfma_f32_16x16x32_bf16 v[116:119], v[200:203], v[154:157], v[116:119]
	v_mfma_f32_16x16x32_bf16 v[108:111], v[214:217], v[154:157], v[108:111]
	v_mfma_f32_16x16x32_bf16 v[100:103], v[200:203], v[176:179], v[100:103]
	v_mfma_f32_16x16x32_bf16 v[92:95], v[214:217], v[176:179], v[92:95]
	v_mfma_f32_16x16x32_bf16 v[84:87], v[200:203], v[184:187], v[84:87]
	v_mfma_f32_16x16x32_bf16 v[76:79], v[214:217], v[184:187], v[76:79]
	v_mfma_f32_16x16x32_bf16 v[68:71], v[200:203], v[192:195], v[68:71]
	v_mfma_f32_16x16x32_bf16 v[64:67], v[214:217], v[192:195], v[64:67]
	v_mfma_f32_16x16x32_bf16 v[116:119], v[210:213], v[172:175], v[116:119]
	v_mfma_f32_16x16x32_bf16 v[108:111], v[218:221], v[172:175], v[108:111]
	v_mfma_f32_16x16x32_bf16 v[100:103], v[210:213], v[180:183], v[100:103]
	v_mfma_f32_16x16x32_bf16 v[92:95], v[218:221], v[180:183], v[92:95]
	v_mfma_f32_16x16x32_bf16 v[84:87], v[210:213], v[188:191], v[84:87]
	v_mfma_f32_16x16x32_bf16 v[76:79], v[218:221], v[188:191], v[76:79]
	v_mfma_f32_16x16x32_bf16 v[68:71], v[210:213], v[196:199], v[68:71]
	v_mfma_f32_16x16x32_bf16 v[64:67], v[218:221], v[196:199], v[64:67]
	s_mov_b32 m0, s39
	v_lshl_add_u64 v[158:159], v[224:225], 0, s[10:11]
	s_barrier
	ds_read_b128 v[154:157], v137 offset:49152
	ds_read_b128 v[172:175], v137 offset:50176
	ds_read_b128 v[176:179], v137 offset:51200
	ds_read_b128 v[180:183], v137 offset:52224
	ds_read_b128 v[184:187], v137 offset:53248
	ds_read_b128 v[188:191], v137 offset:54272
	ds_read_b128 v[192:195], v137 offset:55296
	ds_read_b128 v[196:199], v137 offset:56320
	global_load_lds_dwordx4 v[158:159], off
	v_lshl_add_u64 v[158:159], v[226:227], 0, s[10:11]
	s_mov_b32 m0, s40
	s_nop 0
	global_load_lds_dwordx4 v[158:159], off
	s_barrier
; #define PG8_STAGE(bufoff, gbase, voff) do { _Pragma("unroll") for (int _i = 0; _i < 2; ++_i) \
;     __builtin_amdgcn_global_load_lds((const unsigned*)((const char*)(gbase) + (voff)[_i]), (LAS unsigned*)(lds + (bufoff) + ldsw + _i * 8192), 16, 0, 0); } while (0)
; #define PG8_MMA(ai, bj, At, Bt) do { __builtin_amdgcn_s_setprio(1); _Pragma("unroll") for (int m = 0; m < 4; ++m) _Pragma("unroll") for (int n = 0; n < 2; ++n) _Pragma("unroll") for (int k = 0; k < 2; ++k) \
;     acc[ai][bj][m][n] = __builtin_amdgcn_mfma_f32_16x16x32_bf16(Bt[n][k], At[m][k], acc[ai][bj][m][n], 0, 0, 0); __builtin_amdgcn_s_setprio(0); } while (0)
; #define PG8_WAIT_V(n) asm volatile("s_waitcnt vmcnt(" #n ")" ::: "memory")
; #define PG8_WAIT_L(n) asm volatile("s_waitcnt lgkmcnt(" #n ")" ::: "memory")
; #define PG8_BAR __builtin_amdgcn_s_barrier()
; #define PG8_SCHED __builtin_amdgcn_sched_barrier(0)
; template <class Epi, class Sched>
; __device__ __forceinline__ void gemm_phase(LAS unsigned char* lds, const Gemm g, const Sched& S, const Epi& E) {
;     ...
;       PG8_BAR; PG8_WAIT_L(0); PG8_MMA(1, 0, At, B0); PG8_BAR; PG8_SCHED;
;       PG8_STAGE(PG8_SB(1, 1), b3 + hstepB, voffB);
;       PG8_WAIT_V(6); PG8_BAR; PG8_MMA(1, 1, At, B1); PG8_BAR;
;     }
	s_waitcnt lgkmcnt(0)
	s_waitcnt lgkmcnt(0)
	v_mfma_f32_16x16x32_bf16 v[60:63], v[138:141], v[154:157], v[60:63]
	v_mfma_f32_16x16x32_bf16 v[56:59], v[146:149], v[154:157], v[56:59]
	v_mfma_f32_16x16x32_bf16 v[52:55], v[138:141], v[176:179], v[52:55]
	v_mfma_f32_16x16x32_bf16 v[44:47], v[146:149], v[176:179], v[44:47]
	v_mfma_f32_16x16x32_bf16 v[36:39], v[138:141], v[184:187], v[36:39]
	v_mfma_f32_16x16x32_bf16 v[28:31], v[146:149], v[184:187], v[28:31]
	v_mfma_f32_16x16x32_bf16 v[20:23], v[138:141], v[192:195], v[20:23]
	v_mfma_f32_16x16x32_bf16 v[12:15], v[146:149], v[192:195], v[12:15]
	v_mfma_f32_16x16x32_bf16 v[60:63], v[142:145], v[172:175], v[60:63]
	v_mfma_f32_16x16x32_bf16 v[56:59], v[150:153], v[172:175], v[56:59]
	v_mfma_f32_16x16x32_bf16 v[52:55], v[142:145], v[180:183], v[52:55]
	v_mfma_f32_16x16x32_bf16 v[44:47], v[150:153], v[180:183], v[44:47]
	v_mfma_f32_16x16x32_bf16 v[36:39], v[142:145], v[188:191], v[36:39]
	v_mfma_f32_16x16x32_bf16 v[28:31], v[150:153], v[188:191], v[28:31]
	v_mfma_f32_16x16x32_bf16 v[20:23], v[142:145], v[196:199], v[20:23]
	v_mfma_f32_16x16x32_bf16 v[12:15], v[150:153], v[196:199], v[12:15]
	s_barrier
	s_add_u32 s6, s18, 0x40080
	s_addc_u32 s7, s19, 0
	s_add_i32 s5, s8, s1
	v_lshl_add_u64 v[138:139], s[6:7], 0, v[160:161]
	s_mov_b32 m0, s5
	s_nop 0
	global_load_lds_dwordx4 v[138:139], off
	v_lshl_add_u64 v[138:139], s[6:7], 0, v[130:131]
	s_add_i32 m0, s5, 0x2000
	s_nop 0
	global_load_lds_dwordx4 v[138:139], off
	s_waitcnt vmcnt(6)
	s_barrier
	v_mfma_f32_16x16x32_bf16 v[48:51], v[200:203], v[154:157], v[48:51]
	v_mfma_f32_16x16x32_bf16 v[40:43], v[214:217], v[154:157], v[40:43]
	v_mfma_f32_16x16x32_bf16 v[32:35], v[200:203], v[176:179], v[32:35]
	v_mfma_f32_16x16x32_bf16 v[24:27], v[214:217], v[176:179], v[24:27]
	v_mfma_f32_16x16x32_bf16 v[16:19], v[200:203], v[184:187], v[16:19]
	v_mfma_f32_16x16x32_bf16 v[8:11], v[214:217], v[184:187], v[8:11]
	v_mfma_f32_16x16x32_bf16 v[4:7], v[200:203], v[192:195], v[4:7]
	v_mfma_f32_16x16x32_bf16 v[0:3], v[214:217], v[192:195], v[0:3]
	v_mfma_f32_16x16x32_bf16 v[48:51], v[210:213], v[172:175], v[48:51]
	v_mfma_f32_16x16x32_bf16 v[40:43], v[218:221], v[172:175], v[40:43]
	v_mfma_f32_16x16x32_bf16 v[32:35], v[210:213], v[180:183], v[32:35]
	v_mfma_f32_16x16x32_bf16 v[24:27], v[218:221], v[180:183], v[24:27]
	v_mfma_f32_16x16x32_bf16 v[16:19], v[210:213], v[188:191], v[16:19]
	v_mfma_f32_16x16x32_bf16 v[8:11], v[218:221], v[188:191], v[8:11]
	v_mfma_f32_16x16x32_bf16 v[4:7], v[210:213], v[196:199], v[4:7]
	v_mfma_f32_16x16x32_bf16 v[0:3], v[218:221], v[196:199], v[0:3]
	s_add_i32 s4, s4, 2
	s_add_u32 s12, s12, 0x100
	s_addc_u32 s13, s13, 0
	s_cmp_gt_u32 s4, 13
	s_barrier
	s_cbranch_scc0 .LBB0_195
; __device__ __forceinline__ unsigned cvtpk(float lo, float hi) { unsigned r; asm volatile("v_cvt_pk_bf16_f32 %0, %1, %2" : "=v"(r) : "v"(lo), "v"(hi)); return r; }
; __device__ __forceinline__ float silu_f(float x) { return x * __builtin_amdgcn_rcpf(1.f + __builtin_amdgcn_exp2f(-x * LOG2E)); }
;   __device__ __forceinline__ void operator()(const f32x4 (&acc)[2][2][4][2], const pg8::Unit& u, int wr, int wc, int fr, int fq) const {
;     ...
;     } else if (kd == EK_PLAIN || kd == EK_SILU) {
; #pragma unroll
;       for (int ai = 0; ai < 2; ++ai)
; #pragma unroll
;         for (int m = 0; m < 4; ++m) { bf16_t* rowp = O + (size_t)(row0 + ai * 128 + m * 16) * ldc + colt + wc * 32 + 8 * fq;
; #pragma unroll
;           for (int bj = 0; bj < 2; ++bj) { f32x4 v0 = acc[ai][bj][m][0], v1 = acc[ai][bj][m][1];
;             if (kd == EK_SILU) {
; #pragma unroll
;               for (int j = 0; j < 4; ++j) { v0[j] = silu_f(v0[j]); v1[j] = silu_f(v1[j]); } }
;             u32x4 w; w.x = cvtpk(v0[0], v0[1]); w.y = cvtpk(v0[2], v0[3]); w.z = cvtpk(v1[0], v1[1]); w.w = cvtpk(v1[2], v1[3]);
;             *(u32x4*)(rowp + bj * 128) = w; } }
	v_readlane_b32 s1, v253, 17
	s_add_i32 s38, s38, s1
	v_or_b32_e32 v132, s38, v129
	v_ashrrev_i32_e32 v133, 31, v132
	v_readlane_b32 s4, v253, 19
	v_lshlrev_b64 v[130:131], 12, v[132:133]
	v_readlane_b32 s5, v253, 20
	s_lshl_b32 s14, s37, 6
	v_mov_b32_e32 v129, v161
	v_lshl_add_u64 v[130:131], s[4:5], 0, v[130:131]
	v_lshl_add_u64 v[130:131], v[130:131], 0, s[14:15]
	v_lshl_add_u64 v[130:131], v[130:131], 0, v[128:129]
	v_cvt_pk_bf16_f32 v124, v124, v125
	v_cvt_pk_bf16_f32 v125, v126, v127
	v_cvt_pk_bf16_f32 v126, v120, v121
	v_cvt_pk_bf16_f32 v127, v122, v123
	global_store_dwordx4 v[130:131], v[124:127], off
	v_cvt_pk_bf16_f32 v116, v116, v117
	v_cvt_pk_bf16_f32 v117, v118, v119
	v_cvt_pk_bf16_f32 v118, v108, v109
	v_or_b32_e32 v108, 16, v132
	v_ashrrev_i32_e32 v109, 31, v108
	v_lshlrev_b64 v[108:109], 12, v[108:109]
	v_lshl_add_u64 v[108:109], s[4:5], 0, v[108:109]
	v_lshl_add_u64 v[108:109], v[108:109], 0, s[14:15]
	v_cvt_pk_bf16_f32 v119, v110, v111
	global_store_dwordx4 v[130:131], v[116:119], off offset:256
	s_mov_b32 s1, 0x80000
	s_cmpk_lt_u32 s0, 0x100
	v_lshl_add_u64 v[116:117], v[108:109], 0, v[128:129]
	v_cvt_pk_bf16_f32 v108, v112, v113
	v_cvt_pk_bf16_f32 v109, v114, v115
	v_cvt_pk_bf16_f32 v110, v104, v105
	v_cvt_pk_bf16_f32 v111, v106, v107
	global_store_dwordx4 v[116:117], v[108:111], off
	v_cvt_pk_bf16_f32 v100, v100, v101
	v_cvt_pk_bf16_f32 v101, v102, v103
	v_cvt_pk_bf16_f32 v102, v92, v93
	v_or_b32_e32 v92, 32, v132
	v_ashrrev_i32_e32 v93, 31, v92
	v_lshlrev_b64 v[92:93], 12, v[92:93]
	v_lshl_add_u64 v[92:93], s[4:5], 0, v[92:93]
	v_lshl_add_u64 v[92:93], v[92:93], 0, s[14:15]
	v_cvt_pk_bf16_f32 v103, v94, v95
	global_store_dwordx4 v[116:117], v[100:103], off offset:256
	v_readlane_b32 s8, v255, 23
	s_movk_i32 s9, 0x4000
	v_lshl_add_u64 v[100:101], v[92:93], 0, v[128:129]
	v_cvt_pk_bf16_f32 v92, v96, v97
	v_cvt_pk_bf16_f32 v93, v98, v99
	v_cvt_pk_bf16_f32 v94, v88, v89
	v_cvt_pk_bf16_f32 v95, v90, v91
	global_store_dwordx4 v[100:101], v[92:95], off
	v_cvt_pk_bf16_f32 v84, v84, v85
	v_cvt_pk_bf16_f32 v85, v86, v87
	v_cvt_pk_bf16_f32 v86, v76, v77
	v_or_b32_e32 v76, 48, v132
	v_ashrrev_i32_e32 v77, 31, v76
	v_lshlrev_b64 v[76:77], 12, v[76:77]
	v_lshl_add_u64 v[76:77], s[4:5], 0, v[76:77]
	v_lshl_add_u64 v[76:77], v[76:77], 0, s[14:15]
	v_cvt_pk_bf16_f32 v87, v78, v79
	global_store_dwordx4 v[100:101], v[84:87], off offset:256
	s_mov_b64 s[4:5], 0x80000
	s_movk_i32 s40, 0x3000
	v_lshl_add_u64 v[84:85], v[76:77], 0, v[128:129]
	v_cvt_pk_bf16_f32 v76, v80, v81
	v_cvt_pk_bf16_f32 v77, v82, v83
	v_cvt_pk_bf16_f32 v78, v72, v73
	v_cvt_pk_bf16_f32 v79, v74, v75
	global_store_dwordx4 v[84:85], v[76:79], off
	v_cvt_pk_bf16_f32 v68, v68, v69
	v_cvt_pk_bf16_f32 v69, v70, v71
	v_cvt_pk_bf16_f32 v70, v64, v65
	v_cvt_pk_bf16_f32 v71, v66, v67
	global_store_dwordx4 v[84:85], v[68:71], off offset:256
	v_cvt_pk_bf16_f32 v60, v60, v61
	v_cvt_pk_bf16_f32 v61, v62, v63
	v_cvt_pk_bf16_f32 v62, v56, v57
	v_add_co_u32_e32 v56, vcc, s1, v130
	v_lshl_add_u64 v[64:65], v[130:131], 0, s[4:5]
	s_nop 0
	v_addc_co_u32_e32 v57, vcc, 0, v131, vcc
	s_mov_b32 s1, 0x90000
	v_cvt_pk_bf16_f32 v63, v58, v59
	global_store_dwordx4 v[56:57], v[60:63], off
	v_cvt_pk_bf16_f32 v48, v48, v49
	v_cvt_pk_bf16_f32 v49, v50, v51
	v_cvt_pk_bf16_f32 v50, v40, v41
	v_cvt_pk_bf16_f32 v51, v42, v43
	global_store_dwordx4 v[64:65], v[48:51], off offset:256
	s_mov_b64 s[4:5], 0x90000
	v_cvt_pk_bf16_f32 v40, v52, v53
	v_cvt_pk_bf16_f32 v41, v54, v55
	v_cvt_pk_bf16_f32 v42, v44, v45
	v_add_co_u32_e32 v44, vcc, s1, v130
	v_lshl_add_u64 v[48:49], v[130:131], 0, s[4:5]
	s_nop 0
	v_addc_co_u32_e32 v45, vcc, 0, v131, vcc
	s_mov_b32 s1, 0xa0000
	v_cvt_pk_bf16_f32 v43, v46, v47
	global_store_dwordx4 v[44:45], v[40:43], off
	v_cvt_pk_bf16_f32 v32, v32, v33
	v_cvt_pk_bf16_f32 v33, v34, v35
	v_cvt_pk_bf16_f32 v34, v24, v25
	v_cvt_pk_bf16_f32 v35, v26, v27
	global_store_dwordx4 v[48:49], v[32:35], off offset:256
	s_mov_b64 s[4:5], 0xa0000
	v_cvt_pk_bf16_f32 v24, v36, v37
	v_cvt_pk_bf16_f32 v25, v38, v39
	v_cvt_pk_bf16_f32 v26, v28, v29
	v_add_co_u32_e32 v28, vcc, s1, v130
	v_lshl_add_u64 v[32:33], v[130:131], 0, s[4:5]
	s_nop 0
	v_addc_co_u32_e32 v29, vcc, 0, v131, vcc
	s_mov_b32 s1, 0xb0000
	v_cvt_pk_bf16_f32 v27, v30, v31
	global_store_dwordx4 v[28:29], v[24:27], off
	v_cvt_pk_bf16_f32 v16, v16, v17
	v_cvt_pk_bf16_f32 v17, v18, v19
	v_cvt_pk_bf16_f32 v18, v8, v9
	v_cvt_pk_bf16_f32 v19, v10, v11
	global_store_dwordx4 v[32:33], v[16:19], off offset:256
	s_mov_b64 s[4:5], 0xb0000
	v_cvt_pk_bf16_f32 v8, v20, v21
	v_cvt_pk_bf16_f32 v9, v22, v23
	v_cvt_pk_bf16_f32 v10, v12, v13
	v_add_co_u32_e32 v12, vcc, s1, v130
	v_lshl_add_u64 v[16:17], v[130:131], 0, s[4:5]
	s_nop 0
	v_addc_co_u32_e32 v13, vcc, 0, v131, vcc
	v_cvt_pk_bf16_f32 v11, v14, v15
	global_store_dwordx4 v[12:13], v[8:11], off
	v_cvt_pk_bf16_f32 v4, v4, v5
	v_cvt_pk_bf16_f32 v5, v6, v7
	v_cvt_pk_bf16_f32 v6, v0, v1
	v_cvt_pk_bf16_f32 v7, v2, v3
	global_store_dwordx4 v[16:17], v[4:7], off offset:256
	s_waitcnt vmcnt(0)
	s_cbranch_scc0 .LBB0_198
	s_barrier

; #define PG8_STAGE(bufoff, gbase, voff) do { _Pragma("unroll") for (int _i = 0; _i < 2; ++_i) \
;     __builtin_amdgcn_global_load_lds((const unsigned*)((const char*)(gbase) + (voff)[_i]), (LAS unsigned*)(lds + (bufoff) + ldsw + _i * 8192), 16, 0, 0); } while (0)
; #define PG8_LDA(dst, b, h) do { _Pragma("unroll") for (int m = 0; m < 4; ++m) _Pragma("unroll") for (int k = 0; k < 2; ++k) dst[m][k] = *(const LAS bf16x8*)(lds + PG8_SA(b, h) + aoff + m * 2048 + k * 1024); } while (0)
; #define PG8_LDB(dst, b, h) do { _Pragma("unroll") for (int n = 0; n < 2; ++n) _Pragma("unroll") for (int k = 0; k < 2; ++k) dst[n][k] = *(const LAS bf16x8*)(lds + PG8_SB(b, h) + boff + n * 2048 + k * 1024); } while (0)
; #define PG8_MMA(ai, bj, At, Bt) do { __builtin_amdgcn_s_setprio(1); _Pragma("unroll") for (int m = 0; m < 4; ++m) _Pragma("unroll") for (int n = 0; n < 2; ++n) _Pragma("unroll") for (int k = 0; k < 2; ++k) \
;     acc[ai][bj][m][n] = __builtin_amdgcn_mfma_f32_16x16x32_bf16(Bt[n][k], At[m][k], acc[ai][bj][m][n], 0, 0, 0); __builtin_amdgcn_s_setprio(0); } while (0)
; #define PG8_WAIT_L(n) asm volatile("s_waitcnt lgkmcnt(" #n ")" ::: "memory")
; #define PG8_BAR __builtin_amdgcn_s_barrier()
; #define PG8_SCHED __builtin_amdgcn_sched_barrier(0)
; template <class Epi, class Sched>
; __device__ __forceinline__ void gemm_phase(LAS unsigned char* lds, const Gemm g, const Sched& S, const Epi& E) {
;     ...
;       const bool last = (t == nt - 2);
;       const char* a1 = cA + (size_t)(t + 1) * kstep;
;       const char* a2 = last ? nA : cA + (size_t)(t + 2) * kstep; const char* b2 = last ? nB : cB + (size_t)(t + 2) * kstep;
;       const char* a3 = a2 + kstep; const char* b3 = b2 + kstep;
;       PG8_LDB(B0, 0, 0); PG8_SCHED; PG8_LDA(At, 0, 0); PG8_STAGE(PG8_SA(1, 1), a1 + hstepA, voffA);
;       PG8_WAIT_L(8); PG8_BAR; PG8_WAIT_L(0); PG8_MMA(0, 0, At, B0); PG8_BAR; PG8_SCHED;
;       PG8_LDB(B1, 0, 1); PG8_STAGE(PG8_SB(0, 0), b2, voffB);
;       PG8_BAR; PG8_WAIT_L(0); PG8_MMA(0, 1, At, B1); PG8_BAR;
;       PG8_LDA(At, 0, 1); PG8_STAGE(PG8_SA(0, 0), a2, voffA);
;       PG8_BAR; PG8_WAIT_L(0); PG8_MMA(1, 0, At, B0); PG8_BAR; PG8_SCHED;
.LBB0_448:
	s_add_u32 s7, s40, 0xffe00080
	s_addc_u32 s8, s41, -1
	s_add_i32 s9, 0, 0x10000
	v_add_u32_e32 v142, s9, v145
	ds_read_b128 v[138:141], v142
	ds_read_b128 v[148:151], v142 offset:1024
	ds_read_b128 v[152:155], v142 offset:2048
	ds_read_b128 v[156:159], v142 offset:3072
	s_cmp_eq_u32 s6, 44
	s_cselect_b32 s85, s25, s8
	s_cselect_b32 s84, vcc_lo, s7
	s_cselect_b32 s65, s35, s5
	s_cselect_b32 s64, s34, s4
	v_lshl_add_u64 v[142:143], s[40:41], 0, v[134:135]
	s_add_i32 m0, s14, 0xc000
	ds_read_b128 v[172:175], v147
	ds_read_b128 v[176:179], v147 offset:1024
	ds_read_b128 v[180:183], v147 offset:2048
	ds_read_b128 v[184:187], v147 offset:3072
	ds_read_b128 v[188:191], v147 offset:4096
	ds_read_b128 v[192:195], v147 offset:5120
	ds_read_b128 v[196:199], v147 offset:6144
	ds_read_b128 v[200:203], v147 offset:7168
	global_load_lds_dwordx4 v[142:143], off
	v_lshl_add_u64 v[142:143], s[40:41], 0, v[136:137]
	s_add_i32 m0, s14, 0xe000
	s_nop 0
	global_load_lds_dwordx4 v[142:143], off
	s_waitcnt lgkmcnt(8)
	s_barrier
	s_waitcnt lgkmcnt(0)
	s_waitcnt lgkmcnt(0)
	v_mfma_f32_16x16x32_bf16 v[124:127], v[138:141], v[172:175], v[124:127]
	v_mfma_f32_16x16x32_bf16 v[120:123], v[152:155], v[172:175], v[120:123]
	v_mfma_f32_16x16x32_bf16 v[108:111], v[138:141], v[180:183], v[108:111]
	v_mfma_f32_16x16x32_bf16 v[104:107], v[152:155], v[180:183], v[104:107]
	v_mfma_f32_16x16x32_bf16 v[92:95], v[138:141], v[188:191], v[92:95]
	v_mfma_f32_16x16x32_bf16 v[88:91], v[152:155], v[188:191], v[88:91]
	v_mfma_f32_16x16x32_bf16 v[76:79], v[138:141], v[196:199], v[76:79]
	v_mfma_f32_16x16x32_bf16 v[72:75], v[152:155], v[196:199], v[72:75]
	v_mfma_f32_16x16x32_bf16 v[124:127], v[148:151], v[176:179], v[124:127]
	v_mfma_f32_16x16x32_bf16 v[120:123], v[156:159], v[176:179], v[120:123]
	v_mfma_f32_16x16x32_bf16 v[108:111], v[148:151], v[184:187], v[108:111]
	v_mfma_f32_16x16x32_bf16 v[104:107], v[156:159], v[184:187], v[104:107]
	v_mfma_f32_16x16x32_bf16 v[92:95], v[148:151], v[192:195], v[92:95]
	v_mfma_f32_16x16x32_bf16 v[88:91], v[156:159], v[192:195], v[88:91]
	v_mfma_f32_16x16x32_bf16 v[76:79], v[148:151], v[200:203], v[76:79]
	v_mfma_f32_16x16x32_bf16 v[72:75], v[156:159], v[200:203], v[72:75]
	s_barrier
	s_add_i32 s7, 0, 0x14000
	v_add_u32_e32 v142, s7, v145
	s_add_i32 s8, s9, s1
	ds_read_b128 v[210:213], v142
	ds_read_b128 v[214:217], v142 offset:1024
	ds_read_b128 v[218:221], v142 offset:2048
	ds_read_b128 v[222:225], v142 offset:3072
	v_lshl_add_u64 v[142:143], s[64:65], 0, v[160:161]
	s_mov_b32 m0, s8
	v_lshl_add_u64 v[226:227], s[64:65], 0, v[128:129]
	global_load_lds_dwordx4 v[142:143], off
	s_add_i32 m0, s8, 0x2000
	s_nop 0
	global_load_lds_dwordx4 v[226:227], off
	s_barrier
	s_waitcnt lgkmcnt(0)
	s_waitcnt lgkmcnt(0)
	v_mfma_f32_16x16x32_bf16 v[116:119], v[210:213], v[172:175], v[116:119]
	v_mfma_f32_16x16x32_bf16 v[112:115], v[218:221], v[172:175], v[112:115]
	v_mfma_f32_16x16x32_bf16 v[100:103], v[210:213], v[180:183], v[100:103]
	v_mfma_f32_16x16x32_bf16 v[96:99], v[218:221], v[180:183], v[96:99]
	v_mfma_f32_16x16x32_bf16 v[84:87], v[210:213], v[188:191], v[84:87]
	v_mfma_f32_16x16x32_bf16 v[80:83], v[218:221], v[188:191], v[80:83]
	v_mfma_f32_16x16x32_bf16 v[68:71], v[210:213], v[196:199], v[68:71]
	v_mfma_f32_16x16x32_bf16 v[64:67], v[218:221], v[196:199], v[64:67]
	v_mfma_f32_16x16x32_bf16 v[116:119], v[214:217], v[176:179], v[116:119]
	v_mfma_f32_16x16x32_bf16 v[112:115], v[222:225], v[176:179], v[112:115]
	v_mfma_f32_16x16x32_bf16 v[100:103], v[214:217], v[184:187], v[100:103]
	v_mfma_f32_16x16x32_bf16 v[96:99], v[222:225], v[184:187], v[96:99]
	v_mfma_f32_16x16x32_bf16 v[84:87], v[214:217], v[192:195], v[84:87]
	v_mfma_f32_16x16x32_bf16 v[80:83], v[222:225], v[192:195], v[80:83]
	v_mfma_f32_16x16x32_bf16 v[68:71], v[214:217], v[200:203], v[68:71]
	v_mfma_f32_16x16x32_bf16 v[64:67], v[222:225], v[200:203], v[64:67]
	s_mov_b32 m0, s14
	v_lshl_add_u64 v[228:229], s[84:85], 0, v[132:133]
	s_barrier
	ds_read_b128 v[172:175], v147 offset:16384
	ds_read_b128 v[176:179], v147 offset:17408
	ds_read_b128 v[180:183], v147 offset:18432
	ds_read_b128 v[184:187], v147 offset:19456
	ds_read_b128 v[188:191], v147 offset:20480
	ds_read_b128 v[192:195], v147 offset:21504
	ds_read_b128 v[196:199], v147 offset:22528
	ds_read_b128 v[200:203], v147 offset:23552
	global_load_lds_dwordx4 v[228:229], off
	v_lshl_add_u64 v[230:231], s[84:85], 0, v[130:131]
	s_mov_b32 m0, s62
	s_nop 0
	global_load_lds_dwordx4 v[230:231], off
	s_barrier
	s_waitcnt lgkmcnt(0)
	s_waitcnt lgkmcnt(0)
	v_mfma_f32_16x16x32_bf16 v[60:63], v[138:141], v[172:175], v[60:63]
	v_mfma_f32_16x16x32_bf16 v[56:59], v[152:155], v[172:175], v[56:59]
	v_mfma_f32_16x16x32_bf16 v[44:47], v[138:141], v[180:183], v[44:47]
	v_mfma_f32_16x16x32_bf16 v[40:43], v[152:155], v[180:183], v[40:43]
	v_mfma_f32_16x16x32_bf16 v[28:31], v[138:141], v[188:191], v[28:31]
	v_mfma_f32_16x16x32_bf16 v[24:27], v[152:155], v[188:191], v[24:27]
	v_mfma_f32_16x16x32_bf16 v[12:15], v[138:141], v[196:199], v[12:15]
	v_mfma_f32_16x16x32_bf16 v[8:11], v[152:155], v[196:199], v[8:11]
	v_mfma_f32_16x16x32_bf16 v[60:63], v[148:151], v[176:179], v[60:63]
	v_mfma_f32_16x16x32_bf16 v[56:59], v[156:159], v[176:179], v[56:59]
	v_mfma_f32_16x16x32_bf16 v[44:47], v[148:151], v[184:187], v[44:47]
	v_mfma_f32_16x16x32_bf16 v[40:43], v[156:159], v[184:187], v[40:43]
	v_mfma_f32_16x16x32_bf16 v[28:31], v[148:151], v[192:195], v[28:31]
	v_mfma_f32_16x16x32_bf16 v[24:27], v[156:159], v[192:195], v[24:27]
	v_mfma_f32_16x16x32_bf16 v[12:15], v[148:151], v[200:203], v[12:15]
	v_mfma_f32_16x16x32_bf16 v[8:11], v[156:159], v[200:203], v[8:11]
	s_barrier
; #define PG8_STAGE(bufoff, gbase, voff) do { _Pragma("unroll") for (int _i = 0; _i < 2; ++_i) \
;     __builtin_amdgcn_global_load_lds((const unsigned*)((const char*)(gbase) + (voff)[_i]), (LAS unsigned*)(lds + (bufoff) + ldsw + _i * 8192), 16, 0, 0); } while (0)
; #define PG8_LDA(dst, b, h) do { _Pragma("unroll") for (int m = 0; m < 4; ++m) _Pragma("unroll") for (int k = 0; k < 2; ++k) dst[m][k] = *(const LAS bf16x8*)(lds + PG8_SA(b, h) + aoff + m * 2048 + k * 1024); } while (0)
; #define PG8_LDB(dst, b, h) do { _Pragma("unroll") for (int n = 0; n < 2; ++n) _Pragma("unroll") for (int k = 0; k < 2; ++k) dst[n][k] = *(const LAS bf16x8*)(lds + PG8_SB(b, h) + boff + n * 2048 + k * 1024); } while (0)
; #define PG8_MMA(ai, bj, At, Bt) do { __builtin_amdgcn_s_setprio(1); _Pragma("unroll") for (int m = 0; m < 4; ++m) _Pragma("unroll") for (int n = 0; n < 2; ++n) _Pragma("unroll") for (int k = 0; k < 2; ++k) \
;     acc[ai][bj][m][n] = __builtin_amdgcn_mfma_f32_16x16x32_bf16(Bt[n][k], At[m][k], acc[ai][bj][m][n], 0, 0, 0); __builtin_amdgcn_s_setprio(0); } while (0)
; #define PG8_WAIT_V(n) asm volatile("s_waitcnt vmcnt(" #n ")" ::: "memory")
; #define PG8_WAIT_L(n) asm volatile("s_waitcnt lgkmcnt(" #n ")" ::: "memory")
; #define PG8_BAR __builtin_amdgcn_s_barrier()
; #define PG8_SCHED __builtin_amdgcn_sched_barrier(0)
; template <class Epi, class Sched>
; __device__ __forceinline__ void gemm_phase(LAS unsigned char* lds, const Gemm g, const Sched& S, const Epi& E) {
;     ...
;       PG8_STAGE(PG8_SB(0, 1), b2 + hstepB, voffB);
;       PG8_WAIT_V(6); PG8_BAR; PG8_MMA(1, 1, At, B1); PG8_BAR;
;       PG8_LDB(B0, 1, 0); PG8_SCHED; PG8_LDA(At, 1, 0); PG8_STAGE(PG8_SA(0, 1), a2 + hstepA, voffA);
;       PG8_WAIT_L(8); PG8_BAR; PG8_WAIT_L(0); PG8_MMA(0, 0, At, B0); PG8_BAR; PG8_SCHED;
;       PG8_LDB(B1, 1, 1); PG8_STAGE(PG8_SB(1, 0), b3, voffB);
;       PG8_BAR; PG8_WAIT_L(0); PG8_MMA(0, 1, At, B1); PG8_BAR;
;       PG8_LDA(At, 1, 1); PG8_STAGE(PG8_SA(1, 0), a3, voffA);
;       PG8_BAR; PG8_WAIT_L(0); PG8_MMA(1, 0, At, B0); PG8_BAR; PG8_SCHED;
	s_add_u32 s8, s64, 0xc0000
	s_addc_u32 s9, s65, 0
	s_add_i32 s7, s7, s1
	v_lshl_add_u64 v[138:139], s[8:9], 0, v[160:161]
	s_mov_b32 m0, s7
	s_nop 0
	global_load_lds_dwordx4 v[138:139], off
	v_lshl_add_u64 v[138:139], s[8:9], 0, v[128:129]
	s_add_i32 m0, s7, 0x2000
	s_nop 0
	global_load_lds_dwordx4 v[138:139], off
	s_waitcnt vmcnt(6)
	s_barrier
	v_mfma_f32_16x16x32_bf16 v[52:55], v[210:213], v[172:175], v[52:55]
	v_mfma_f32_16x16x32_bf16 v[48:51], v[218:221], v[172:175], v[48:51]
	v_mfma_f32_16x16x32_bf16 v[36:39], v[210:213], v[180:183], v[36:39]
	v_mfma_f32_16x16x32_bf16 v[32:35], v[218:221], v[180:183], v[32:35]
	v_mfma_f32_16x16x32_bf16 v[20:23], v[210:213], v[188:191], v[20:23]
	v_mfma_f32_16x16x32_bf16 v[16:19], v[218:221], v[188:191], v[16:19]
	v_mfma_f32_16x16x32_bf16 v[4:7], v[210:213], v[196:199], v[4:7]
	v_mfma_f32_16x16x32_bf16 v[0:3], v[218:221], v[196:199], v[0:3]
	v_mfma_f32_16x16x32_bf16 v[52:55], v[214:217], v[176:179], v[52:55]
	v_mfma_f32_16x16x32_bf16 v[48:51], v[222:225], v[176:179], v[48:51]
	v_mfma_f32_16x16x32_bf16 v[36:39], v[214:217], v[184:187], v[36:39]
	v_mfma_f32_16x16x32_bf16 v[32:35], v[222:225], v[184:187], v[32:35]
	v_mfma_f32_16x16x32_bf16 v[20:23], v[214:217], v[192:195], v[20:23]
	v_mfma_f32_16x16x32_bf16 v[16:19], v[222:225], v[192:195], v[16:19]
	v_mfma_f32_16x16x32_bf16 v[4:7], v[214:217], v[200:203], v[4:7]
	v_mfma_f32_16x16x32_bf16 v[0:3], v[222:225], v[200:203], v[0:3]
	s_add_i32 s7, 0, 0x18000
	v_add_u32_e32 v156, s7, v145
	s_barrier
	ds_read_b128 v[138:141], v156
	ds_read_b128 v[148:151], v156 offset:1024
	ds_read_b128 v[152:155], v156 offset:2048
	ds_read_b128 v[156:159], v156 offset:3072
	s_add_u32 s8, s84, 0x200000
	s_addc_u32 s9, s85, 0
	s_mov_b32 m0, s63
	v_lshl_add_u64 v[210:211], s[8:9], 0, v[132:133]
	ds_read_b128 v[172:175], v147 offset:32768
	ds_read_b128 v[176:179], v147 offset:33792
	ds_read_b128 v[180:183], v147 offset:34816
	ds_read_b128 v[184:187], v147 offset:35840
	ds_read_b128 v[188:191], v147 offset:36864
	ds_read_b128 v[192:195], v147 offset:37888
	ds_read_b128 v[196:199], v147 offset:38912
	ds_read_b128 v[200:203], v147 offset:39936
	global_load_lds_dwordx4 v[210:211], off
	v_lshl_add_u64 v[210:211], s[8:9], 0, v[130:131]
	s_mov_b32 m0, s93
	s_nop 0
	global_load_lds_dwordx4 v[210:211], off
	s_waitcnt lgkmcnt(8)
	s_barrier
	s_waitcnt lgkmcnt(0)
	s_waitcnt lgkmcnt(0)
	v_mfma_f32_16x16x32_bf16 v[124:127], v[138:141], v[172:175], v[124:127]
	v_mfma_f32_16x16x32_bf16 v[120:123], v[152:155], v[172:175], v[120:123]
	v_mfma_f32_16x16x32_bf16 v[108:111], v[138:141], v[180:183], v[108:111]
	v_mfma_f32_16x16x32_bf16 v[104:107], v[152:155], v[180:183], v[104:107]
	v_mfma_f32_16x16x32_bf16 v[92:95], v[138:141], v[188:191], v[92:95]
	v_mfma_f32_16x16x32_bf16 v[88:91], v[152:155], v[188:191], v[88:91]
	v_mfma_f32_16x16x32_bf16 v[76:79], v[138:141], v[196:199], v[76:79]
	v_mfma_f32_16x16x32_bf16 v[72:75], v[152:155], v[196:199], v[72:75]
	v_mfma_f32_16x16x32_bf16 v[124:127], v[148:151], v[176:179], v[124:127]
	v_mfma_f32_16x16x32_bf16 v[120:123], v[156:159], v[176:179], v[120:123]
	v_mfma_f32_16x16x32_bf16 v[108:111], v[148:151], v[184:187], v[108:111]
	v_mfma_f32_16x16x32_bf16 v[104:107], v[156:159], v[184:187], v[104:107]
	v_mfma_f32_16x16x32_bf16 v[92:95], v[148:151], v[192:195], v[92:95]
	v_mfma_f32_16x16x32_bf16 v[88:91], v[156:159], v[192:195], v[88:91]
	v_mfma_f32_16x16x32_bf16 v[76:79], v[148:151], v[200:203], v[76:79]
	v_mfma_f32_16x16x32_bf16 v[72:75], v[156:159], v[200:203], v[72:75]
	s_barrier
	s_add_i32 s84, 0, 0x1c000
	s_add_i32 s7, s7, s1
	v_add_u32_e32 v209, s84, v145
	v_lshl_add_u64 v[142:143], v[142:143], 0, s[10:11]
	s_mov_b32 m0, s7
	ds_read_b128 v[210:213], v209
	ds_read_b128 v[214:217], v209 offset:1024
	ds_read_b128 v[218:221], v209 offset:2048
	ds_read_b128 v[222:225], v209 offset:3072
	global_load_lds_dwordx4 v[142:143], off
	v_lshl_add_u64 v[142:143], v[226:227], 0, s[10:11]
	s_add_i32 m0, s7, 0x2000
	s_nop 0
	global_load_lds_dwordx4 v[142:143], off
	s_barrier
	s_waitcnt lgkmcnt(0)
	s_waitcnt lgkmcnt(0)
	v_mfma_f32_16x16x32_bf16 v[116:119], v[210:213], v[172:175], v[116:119]
	v_mfma_f32_16x16x32_bf16 v[112:115], v[218:221], v[172:175], v[112:115]
	v_mfma_f32_16x16x32_bf16 v[100:103], v[210:213], v[180:183], v[100:103]
	v_mfma_f32_16x16x32_bf16 v[96:99], v[218:221], v[180:183], v[96:99]
	v_mfma_f32_16x16x32_bf16 v[84:87], v[210:213], v[188:191], v[84:87]
	v_mfma_f32_16x16x32_bf16 v[80:83], v[218:221], v[188:191], v[80:83]
	v_mfma_f32_16x16x32_bf16 v[68:71], v[210:213], v[196:199], v[68:71]
	v_mfma_f32_16x16x32_bf16 v[64:67], v[218:221], v[196:199], v[64:67]
	v_mfma_f32_16x16x32_bf16 v[116:119], v[214:217], v[176:179], v[116:119]
	v_mfma_f32_16x16x32_bf16 v[112:115], v[222:225], v[176:179], v[112:115]
	v_mfma_f32_16x16x32_bf16 v[100:103], v[214:217], v[184:187], v[100:103]
	v_mfma_f32_16x16x32_bf16 v[96:99], v[222:225], v[184:187], v[96:99]
	v_mfma_f32_16x16x32_bf16 v[84:87], v[214:217], v[192:195], v[84:87]
	v_mfma_f32_16x16x32_bf16 v[80:83], v[222:225], v[192:195], v[80:83]
	v_mfma_f32_16x16x32_bf16 v[68:71], v[214:217], v[200:203], v[68:71]
	v_mfma_f32_16x16x32_bf16 v[64:67], v[222:225], v[200:203], v[64:67]
	s_mov_b32 m0, s94
	v_lshl_add_u64 v[142:143], v[228:229], 0, s[10:11]
	s_barrier
	ds_read_b128 v[172:175], v147 offset:49152
	ds_read_b128 v[176:179], v147 offset:50176
	ds_read_b128 v[180:183], v147 offset:51200
	ds_read_b128 v[184:187], v147 offset:52224
	ds_read_b128 v[188:191], v147 offset:53248
	ds_read_b128 v[192:195], v147 offset:54272
	ds_read_b128 v[196:199], v147 offset:55296
	ds_read_b128 v[200:203], v147 offset:56320
	global_load_lds_dwordx4 v[142:143], off
	v_lshl_add_u64 v[142:143], v[230:231], 0, s[10:11]
	s_mov_b32 m0, s95
	s_nop 0
	global_load_lds_dwordx4 v[142:143], off
	s_barrier
; #define PG8_STAGE(bufoff, gbase, voff) do { _Pragma("unroll") for (int _i = 0; _i < 2; ++_i) \
;     __builtin_amdgcn_global_load_lds((const unsigned*)((const char*)(gbase) + (voff)[_i]), (LAS unsigned*)(lds + (bufoff) + ldsw + _i * 8192), 16, 0, 0); } while (0)
; #define PG8_MMA(ai, bj, At, Bt) do { __builtin_amdgcn_s_setprio(1); _Pragma("unroll") for (int m = 0; m < 4; ++m) _Pragma("unroll") for (int n = 0; n < 2; ++n) _Pragma("unroll") for (int k = 0; k < 2; ++k) \
;     acc[ai][bj][m][n] = __builtin_amdgcn_mfma_f32_16x16x32_bf16(Bt[n][k], At[m][k], acc[ai][bj][m][n], 0, 0, 0); __builtin_amdgcn_s_setprio(0); } while (0)
; #define PG8_WAIT_V(n) asm volatile("s_waitcnt vmcnt(" #n ")" ::: "memory")
; #define PG8_WAIT_L(n) asm volatile("s_waitcnt lgkmcnt(" #n ")" ::: "memory")
; #define PG8_BAR __builtin_amdgcn_s_barrier()
; #define PG8_SCHED __builtin_amdgcn_sched_barrier(0)
; template <class Epi, class Sched>
; __device__ __forceinline__ void gemm_phase(LAS unsigned char* lds, const Gemm g, const Sched& S, const Epi& E) {
;     ...
;       PG8_BAR; PG8_WAIT_L(0); PG8_MMA(1, 0, At, B0); PG8_BAR; PG8_SCHED;
;       PG8_STAGE(PG8_SB(1, 1), b3 + hstepB, voffB);
;       PG8_WAIT_V(6); PG8_BAR; PG8_MMA(1, 1, At, B1); PG8_BAR;
;     }
;   __device__ __forceinline__ void operator()(const f32x4 (&acc)[2][2][4][2], const pg8::Unit& u, int wr, int wc, int fr, int fq) const {
;     const int row0 = u.pm * 256 + wr * 64 + fr, col0 = u.pn * 256 + wc * 32 + 8 * fq;
; #pragma unroll
;     for (int ai = 0; ai < 2; ++ai)
; #pragma unroll
;       for (int m = 0; m < 4; ++m) { const size_t ro = (size_t)(row0 + ai * 128 + m * 16) * DM + col0;
; #pragma unroll
;         for (int bj = 0; bj < 2; ++bj)
; #pragma unroll
;           for (int n = 0; n < 2; ++n) { const f32x4 bv = *(const f32x4*)(base + ro + bj * 128 + 4 * n); *(f32x4*)(out + ro + bj * 128 + 4 * n) = acc[ai][bj][m][n] + bv; } }
	s_waitcnt lgkmcnt(0)
	s_waitcnt lgkmcnt(0)
	v_mfma_f32_16x16x32_bf16 v[60:63], v[138:141], v[172:175], v[60:63]
	v_mfma_f32_16x16x32_bf16 v[56:59], v[152:155], v[172:175], v[56:59]
	v_mfma_f32_16x16x32_bf16 v[44:47], v[138:141], v[180:183], v[44:47]
	v_mfma_f32_16x16x32_bf16 v[40:43], v[152:155], v[180:183], v[40:43]
	v_mfma_f32_16x16x32_bf16 v[28:31], v[138:141], v[188:191], v[28:31]
	v_mfma_f32_16x16x32_bf16 v[24:27], v[152:155], v[188:191], v[24:27]
	v_mfma_f32_16x16x32_bf16 v[12:15], v[138:141], v[196:199], v[12:15]
	v_mfma_f32_16x16x32_bf16 v[8:11], v[152:155], v[196:199], v[8:11]
	v_mfma_f32_16x16x32_bf16 v[60:63], v[148:151], v[176:179], v[60:63]
	v_mfma_f32_16x16x32_bf16 v[56:59], v[156:159], v[176:179], v[56:59]
	v_mfma_f32_16x16x32_bf16 v[44:47], v[148:151], v[184:187], v[44:47]
	v_mfma_f32_16x16x32_bf16 v[40:43], v[156:159], v[184:187], v[40:43]
	v_mfma_f32_16x16x32_bf16 v[28:31], v[148:151], v[192:195], v[28:31]
	v_mfma_f32_16x16x32_bf16 v[24:27], v[156:159], v[192:195], v[24:27]
	v_mfma_f32_16x16x32_bf16 v[12:15], v[148:151], v[200:203], v[12:15]
	v_mfma_f32_16x16x32_bf16 v[8:11], v[156:159], v[200:203], v[8:11]
	s_barrier
	s_add_u32 s8, s64, 0xc0080
	s_addc_u32 s9, s65, 0
	s_add_i32 s7, s84, s1
	v_lshl_add_u64 v[138:139], s[8:9], 0, v[160:161]
	s_mov_b32 m0, s7
	s_nop 0
	global_load_lds_dwordx4 v[138:139], off
	v_lshl_add_u64 v[138:139], s[8:9], 0, v[128:129]
	s_add_i32 m0, s7, 0x2000
	s_nop 0
	global_load_lds_dwordx4 v[138:139], off
	s_waitcnt vmcnt(6)
	s_barrier
	v_mfma_f32_16x16x32_bf16 v[52:55], v[210:213], v[172:175], v[52:55]
	v_mfma_f32_16x16x32_bf16 v[48:51], v[218:221], v[172:175], v[48:51]
	v_mfma_f32_16x16x32_bf16 v[36:39], v[210:213], v[180:183], v[36:39]
	v_mfma_f32_16x16x32_bf16 v[32:35], v[218:221], v[180:183], v[32:35]
	v_mfma_f32_16x16x32_bf16 v[20:23], v[210:213], v[188:191], v[20:23]
	v_mfma_f32_16x16x32_bf16 v[16:19], v[218:221], v[188:191], v[16:19]
	v_mfma_f32_16x16x32_bf16 v[4:7], v[210:213], v[196:199], v[4:7]
	v_mfma_f32_16x16x32_bf16 v[0:3], v[218:221], v[196:199], v[0:3]
	v_mfma_f32_16x16x32_bf16 v[52:55], v[214:217], v[176:179], v[52:55]
	v_mfma_f32_16x16x32_bf16 v[48:51], v[222:225], v[176:179], v[48:51]
	v_mfma_f32_16x16x32_bf16 v[36:39], v[214:217], v[184:187], v[36:39]
	v_mfma_f32_16x16x32_bf16 v[32:35], v[222:225], v[184:187], v[32:35]
	v_mfma_f32_16x16x32_bf16 v[20:23], v[214:217], v[192:195], v[20:23]
	v_mfma_f32_16x16x32_bf16 v[16:19], v[222:225], v[192:195], v[16:19]
	v_mfma_f32_16x16x32_bf16 v[4:7], v[214:217], v[200:203], v[4:7]
	v_mfma_f32_16x16x32_bf16 v[0:3], v[222:225], v[200:203], v[0:3]
	s_add_i32 s6, s6, 2
	s_add_u32 s40, s40, 0x100
	s_addc_u32 s41, s41, 0
	s_add_u32 s4, s4, 0x100
	s_addc_u32 s5, s5, 0
	s_cmp_gt_u32 s6, 45
	s_barrier
	s_cbranch_scc0 .LBB0_448
	v_lshl_add_u32 v142, s43, 8, v144
	v_lshl_or_b32 v140, s97, 8, v146
	v_ashrrev_i32_e32 v143, 31, v142
	v_ashrrev_i32_e32 v141, 31, v140
	v_lshlrev_b64 v[138:139], 10, v[142:143]
	v_lshl_add_u64 v[138:139], v[138:139], 0, v[140:141]
	v_lshlrev_b64 v[138:139], 2, v[138:139]
	v_lshl_add_u64 v[152:153], s[18:19], 0, v[138:139]
	global_load_dwordx4 v[148:151], v[152:153], off
	s_mov_b64 s[4:5], 0x80000
	s_and_b64 vcc, exec, s[38:39]
	s_mov_b32 s97, s42
	s_mov_b32 s43, s24
	s_mov_b64 s[64:65], s[34:35]
	s_mov_b64 s[84:85], s[36:37]
	s_waitcnt vmcnt(0)
	v_pk_add_f32 v[126:127], v[126:127], v[150:151]
	v_pk_add_f32 v[124:125], v[124:125], v[148:149]
	v_lshl_add_u64 v[148:149], s[12:13], 0, v[138:139]
	global_store_dwordx4 v[148:149], v[124:127], off
	global_load_dwordx4 v[124:127], v[152:153], off offset:16
	s_waitcnt vmcnt(0)
	v_pk_add_f32 v[122:123], v[122:123], v[126:127]
	v_pk_add_f32 v[120:121], v[120:121], v[124:125]
	global_store_dwordx4 v[148:149], v[120:123], off offset:16
	global_load_dwordx4 v[120:123], v[152:153], off offset:512
	s_waitcnt vmcnt(0)
	v_pk_add_f32 v[118:119], v[118:119], v[122:123]
	v_pk_add_f32 v[116:117], v[116:117], v[120:121]
	global_store_dwordx4 v[148:149], v[116:119], off offset:512
	global_load_dwordx4 v[116:119], v[152:153], off offset:528
	s_waitcnt vmcnt(0)
	v_pk_add_f32 v[114:115], v[114:115], v[118:119]
	v_pk_add_f32 v[112:113], v[112:113], v[116:117]
	global_store_dwordx4 v[148:149], v[112:115], off offset:528
	s_nop 1
	v_or_b32_e32 v112, 16, v142
	v_ashrrev_i32_e32 v113, 31, v112
	v_lshlrev_b64 v[112:113], 10, v[112:113]
	v_lshl_add_u64 v[112:113], v[112:113], 0, v[140:141]
	v_lshlrev_b64 v[116:117], 2, v[112:113]
	v_lshl_add_u64 v[118:119], s[18:19], 0, v[116:117]
	global_load_dwordx4 v[112:115], v[118:119], off
	s_waitcnt vmcnt(0)
	v_pk_add_f32 v[110:111], v[110:111], v[114:115]
	v_pk_add_f32 v[108:109], v[108:109], v[112:113]
	v_lshl_add_u64 v[112:113], s[12:13], 0, v[116:117]
	global_store_dwordx4 v[112:113], v[108:111], off
	global_load_dwordx4 v[108:111], v[118:119], off offset:16
	s_waitcnt vmcnt(0)
	v_pk_add_f32 v[106:107], v[106:107], v[110:111]
	v_pk_add_f32 v[104:105], v[104:105], v[108:109]
	global_store_dwordx4 v[112:113], v[104:107], off offset:16
	global_load_dwordx4 v[104:107], v[118:119], off offset:512
	s_waitcnt vmcnt(0)
	v_pk_add_f32 v[102:103], v[102:103], v[106:107]
	v_pk_add_f32 v[100:101], v[100:101], v[104:105]
	global_store_dwordx4 v[112:113], v[100:103], off offset:512
	global_load_dwordx4 v[100:103], v[118:119], off offset:528
	s_waitcnt vmcnt(0)
	v_pk_add_f32 v[98:99], v[98:99], v[102:103]
	v_pk_add_f32 v[96:97], v[96:97], v[100:101]
	global_store_dwordx4 v[112:113], v[96:99], off offset:528
	s_nop 1
	v_or_b32_e32 v96, 32, v142
	v_ashrrev_i32_e32 v97, 31, v96
	v_lshlrev_b64 v[96:97], 10, v[96:97]
	v_lshl_add_u64 v[96:97], v[96:97], 0, v[140:141]
	v_lshlrev_b64 v[100:101], 2, v[96:97]
	v_lshl_add_u64 v[102:103], s[18:19], 0, v[100:101]
	global_load_dwordx4 v[96:99], v[102:103], off
	s_waitcnt vmcnt(0)
;   __device__ __forceinline__ void operator()(const f32x4 (&acc)[2][2][4][2], const pg8::Unit& u, int wr, int wc, int fr, int fq) const {
;     const int row0 = u.pm * 256 + wr * 64 + fr, col0 = u.pn * 256 + wc * 32 + 8 * fq;
; #pragma unroll
;     for (int ai = 0; ai < 2; ++ai)
; #pragma unroll
;       for (int m = 0; m < 4; ++m) { const size_t ro = (size_t)(row0 + ai * 128 + m * 16) * DM + col0;
; #pragma unroll
;         for (int bj = 0; bj < 2; ++bj)
; #pragma unroll
;           for (int n = 0; n < 2; ++n) { const f32x4 bv = *(const f32x4*)(base + ro + bj * 128 + 4 * n); *(f32x4*)(out + ro + bj * 128 + 4 * n) = acc[ai][bj][m][n] + bv; } }
	v_pk_add_f32 v[94:95], v[94:95], v[98:99]
	v_pk_add_f32 v[92:93], v[92:93], v[96:97]
	v_lshl_add_u64 v[96:97], s[12:13], 0, v[100:101]
	global_store_dwordx4 v[96:97], v[92:95], off
	global_load_dwordx4 v[92:95], v[102:103], off offset:16
	s_waitcnt vmcnt(0)
	v_pk_add_f32 v[90:91], v[90:91], v[94:95]
	v_pk_add_f32 v[88:89], v[88:89], v[92:93]
	global_store_dwordx4 v[96:97], v[88:91], off offset:16
	global_load_dwordx4 v[88:91], v[102:103], off offset:512
	s_waitcnt vmcnt(0)
	v_pk_add_f32 v[86:87], v[86:87], v[90:91]
	v_pk_add_f32 v[84:85], v[84:85], v[88:89]
	global_store_dwordx4 v[96:97], v[84:87], off offset:512
	global_load_dwordx4 v[84:87], v[102:103], off offset:528
	s_waitcnt vmcnt(0)
	v_pk_add_f32 v[82:83], v[82:83], v[86:87]
	v_pk_add_f32 v[80:81], v[80:81], v[84:85]
	global_store_dwordx4 v[96:97], v[80:83], off offset:528
	s_nop 1
	v_or_b32_e32 v80, 48, v142
	v_ashrrev_i32_e32 v81, 31, v80
	v_lshlrev_b64 v[80:81], 10, v[80:81]
	v_lshl_add_u64 v[80:81], v[80:81], 0, v[140:141]
	v_lshlrev_b64 v[84:85], 2, v[80:81]
	v_lshl_add_u64 v[86:87], s[18:19], 0, v[84:85]
	global_load_dwordx4 v[80:83], v[86:87], off
	s_waitcnt vmcnt(0)
	v_pk_add_f32 v[78:79], v[78:79], v[82:83]
	v_pk_add_f32 v[76:77], v[76:77], v[80:81]
	v_lshl_add_u64 v[80:81], s[12:13], 0, v[84:85]
	global_store_dwordx4 v[80:81], v[76:79], off
	global_load_dwordx4 v[76:79], v[86:87], off offset:16
	s_waitcnt vmcnt(0)
	v_pk_add_f32 v[74:75], v[74:75], v[78:79]
	v_pk_add_f32 v[72:73], v[72:73], v[76:77]
	global_store_dwordx4 v[80:81], v[72:75], off offset:16
	global_load_dwordx4 v[72:75], v[86:87], off offset:512
	s_waitcnt vmcnt(0)
	v_pk_add_f32 v[70:71], v[70:71], v[74:75]
	v_pk_add_f32 v[68:69], v[68:69], v[72:73]
	global_store_dwordx4 v[80:81], v[68:71], off offset:512
	global_load_dwordx4 v[68:71], v[86:87], off offset:528
	s_waitcnt vmcnt(0)
	v_pk_add_f32 v[66:67], v[66:67], v[70:71]
	v_pk_add_f32 v[64:65], v[64:65], v[68:69]
	v_lshl_add_u64 v[68:69], v[138:139], 0, s[4:5]
	global_store_dwordx4 v[80:81], v[64:67], off offset:528
	v_lshl_add_u64 v[70:71], s[18:19], 0, v[68:69]
	global_load_dwordx4 v[64:67], v[70:71], off
	s_mov_b64 s[4:5], 0x90000
	s_waitcnt vmcnt(0)
	v_pk_add_f32 v[62:63], v[62:63], v[66:67]
	v_pk_add_f32 v[60:61], v[60:61], v[64:65]
	v_lshl_add_u64 v[64:65], s[12:13], 0, v[68:69]
	global_store_dwordx4 v[64:65], v[60:63], off
	global_load_dwordx4 v[60:63], v[70:71], off offset:16
	s_waitcnt vmcnt(0)
	v_pk_add_f32 v[58:59], v[58:59], v[62:63]
	v_pk_add_f32 v[56:57], v[56:57], v[60:61]
	global_store_dwordx4 v[64:65], v[56:59], off offset:16
	global_load_dwordx4 v[56:59], v[70:71], off offset:512
	s_waitcnt vmcnt(0)
	v_pk_add_f32 v[54:55], v[54:55], v[58:59]
	v_pk_add_f32 v[52:53], v[52:53], v[56:57]
	global_store_dwordx4 v[64:65], v[52:55], off offset:512
	global_load_dwordx4 v[52:55], v[70:71], off offset:528
	s_waitcnt vmcnt(0)
	v_pk_add_f32 v[50:51], v[50:51], v[54:55]
	v_pk_add_f32 v[48:49], v[48:49], v[52:53]
	v_lshl_add_u64 v[52:53], v[138:139], 0, s[4:5]
	global_store_dwordx4 v[64:65], v[48:51], off offset:528
	v_lshl_add_u64 v[54:55], s[18:19], 0, v[52:53]
	global_load_dwordx4 v[48:51], v[54:55], off
	s_mov_b64 s[4:5], 0xa0000
	s_waitcnt vmcnt(0)
	v_pk_add_f32 v[46:47], v[46:47], v[50:51]
	v_pk_add_f32 v[44:45], v[44:45], v[48:49]
	v_lshl_add_u64 v[48:49], s[12:13], 0, v[52:53]
	global_store_dwordx4 v[48:49], v[44:47], off
	global_load_dwordx4 v[44:47], v[54:55], off offset:16
	s_waitcnt vmcnt(0)
	v_pk_add_f32 v[42:43], v[42:43], v[46:47]
	v_pk_add_f32 v[40:41], v[40:41], v[44:45]
	global_store_dwordx4 v[48:49], v[40:43], off offset:16
	global_load_dwordx4 v[40:43], v[54:55], off offset:512
	s_waitcnt vmcnt(0)
	v_pk_add_f32 v[38:39], v[38:39], v[42:43]
	v_pk_add_f32 v[36:37], v[36:37], v[40:41]
	global_store_dwordx4 v[48:49], v[36:39], off offset:512
	global_load_dwordx4 v[36:39], v[54:55], off offset:528
	s_waitcnt vmcnt(0)
	v_pk_add_f32 v[34:35], v[34:35], v[38:39]
	v_pk_add_f32 v[32:33], v[32:33], v[36:37]
	v_lshl_add_u64 v[36:37], v[138:139], 0, s[4:5]
	global_store_dwordx4 v[48:49], v[32:35], off offset:528
	v_lshl_add_u64 v[38:39], s[18:19], 0, v[36:37]
	global_load_dwordx4 v[32:35], v[38:39], off
	s_mov_b64 s[4:5], 0xb0000
	s_waitcnt vmcnt(0)
	v_pk_add_f32 v[30:31], v[30:31], v[34:35]
	v_pk_add_f32 v[28:29], v[28:29], v[32:33]
	v_lshl_add_u64 v[32:33], s[12:13], 0, v[36:37]
	global_store_dwordx4 v[32:33], v[28:31], off
	global_load_dwordx4 v[28:31], v[38:39], off offset:16
	s_waitcnt vmcnt(0)
	v_pk_add_f32 v[26:27], v[26:27], v[30:31]
	v_pk_add_f32 v[24:25], v[24:25], v[28:29]
	global_store_dwordx4 v[32:33], v[24:27], off offset:16
	global_load_dwordx4 v[24:27], v[38:39], off offset:512
	s_waitcnt vmcnt(0)
	v_pk_add_f32 v[22:23], v[22:23], v[26:27]
	v_pk_add_f32 v[20:21], v[20:21], v[24:25]
	global_store_dwordx4 v[32:33], v[20:23], off offset:512
	global_load_dwordx4 v[20:23], v[38:39], off offset:528
	s_waitcnt vmcnt(0)
	v_pk_add_f32 v[18:19], v[18:19], v[22:23]
	v_pk_add_f32 v[16:17], v[16:17], v[20:21]
	v_lshl_add_u64 v[20:21], v[138:139], 0, s[4:5]
	global_store_dwordx4 v[32:33], v[16:19], off offset:528
	v_lshl_add_u64 v[22:23], s[18:19], 0, v[20:21]
	global_load_dwordx4 v[16:19], v[22:23], off
	s_waitcnt vmcnt(0)
	v_pk_add_f32 v[14:15], v[14:15], v[18:19]
	v_pk_add_f32 v[12:13], v[12:13], v[16:17]
	v_lshl_add_u64 v[16:17], s[12:13], 0, v[20:21]
	global_store_dwordx4 v[16:17], v[12:15], off
	global_load_dwordx4 v[12:15], v[22:23], off offset:16
	s_waitcnt vmcnt(0)
	v_pk_add_f32 v[10:11], v[10:11], v[14:15]
	v_pk_add_f32 v[8:9], v[8:9], v[12:13]
	global_store_dwordx4 v[16:17], v[8:11], off offset:16
	global_load_dwordx4 v[8:11], v[22:23], off offset:512
	s_waitcnt vmcnt(0)
	v_pk_add_f32 v[6:7], v[6:7], v[10:11]
	v_pk_add_f32 v[4:5], v[4:5], v[8:9]
	global_store_dwordx4 v[16:17], v[4:7], off offset:512
	global_load_dwordx4 v[4:7], v[22:23], off offset:528
	s_waitcnt vmcnt(0)
	v_pk_add_f32 v[2:3], v[2:3], v[6:7]
	v_pk_add_f32 v[0:1], v[0:1], v[4:5]
	global_store_dwordx4 v[16:17], v[0:3], off offset:528
	s_cbranch_vccz .LBB0_439
	s_waitcnt vmcnt(0)
	v_readlane_b32 s96, v255, 16
	s_cmpk_gt_u32 s0, 0xff
	v_readlane_b32 s94, v255, 14
	v_readlane_b32 s97, v255, 17
	v_readlane_b32 s95, v255, 15
	s_cbranch_scc1 .LBB0_452
	s_barrier

; #define PG8_STAGE(bufoff, gbase, voff) do { _Pragma("unroll") for (int _i = 0; _i < 2; ++_i) \
;     __builtin_amdgcn_global_load_lds((const unsigned*)((const char*)(gbase) + (voff)[_i]), (LAS unsigned*)(lds + (bufoff) + ldsw + _i * 8192), 16, 0, 0); } while (0)
; #define PG8_LDA(dst, b, h) do { _Pragma("unroll") for (int m = 0; m < 4; ++m) _Pragma("unroll") for (int k = 0; k < 2; ++k) dst[m][k] = *(const LAS bf16x8*)(lds + PG8_SA(b, h) + aoff + m * 2048 + k * 1024); } while (0)
; #define PG8_LDB(dst, b, h) do { _Pragma("unroll") for (int n = 0; n < 2; ++n) _Pragma("unroll") for (int k = 0; k < 2; ++k) dst[n][k] = *(const LAS bf16x8*)(lds + PG8_SB(b, h) + boff + n * 2048 + k * 1024); } while (0)
; #define PG8_MMA(ai, bj, At, Bt) do { __builtin_amdgcn_s_setprio(1); _Pragma("unroll") for (int m = 0; m < 4; ++m) _Pragma("unroll") for (int n = 0; n < 2; ++n) _Pragma("unroll") for (int k = 0; k < 2; ++k) \
;     acc[ai][bj][m][n] = __builtin_amdgcn_mfma_f32_16x16x32_bf16(Bt[n][k], At[m][k], acc[ai][bj][m][n], 0, 0, 0); __builtin_amdgcn_s_setprio(0); } while (0)
; #define PG8_WAIT_L(n) asm volatile("s_waitcnt lgkmcnt(" #n ")" ::: "memory")
; #define PG8_BAR __builtin_amdgcn_s_barrier()
; #define PG8_SCHED __builtin_amdgcn_sched_barrier(0)
; template <class Epi, class Sched>
; __device__ __forceinline__ void gemm_phase(LAS unsigned char* lds, const Gemm g, const Sched& S, const Epi& E) {
;     ...
;       const bool last = (t == nt - 2);
;       const char* a1 = cA + (size_t)(t + 1) * kstep;
;       const char* a2 = last ? nA : cA + (size_t)(t + 2) * kstep; const char* b2 = last ? nB : cB + (size_t)(t + 2) * kstep;
;       const char* a3 = a2 + kstep; const char* b3 = b2 + kstep;
;       PG8_LDB(B0, 0, 0); PG8_SCHED; PG8_LDA(At, 0, 0); PG8_STAGE(PG8_SA(1, 1), a1 + hstepA, voffA);
;       PG8_WAIT_L(8); PG8_BAR; PG8_WAIT_L(0); PG8_MMA(0, 0, At, B0); PG8_BAR; PG8_SCHED;
;       PG8_LDB(B1, 0, 1); PG8_STAGE(PG8_SB(0, 0), b2, voffB);
;       PG8_BAR; PG8_WAIT_L(0); PG8_MMA(0, 1, At, B1); PG8_BAR;
;       PG8_LDA(At, 0, 1); PG8_STAGE(PG8_SA(0, 0), a2, voffA);
;       PG8_BAR; PG8_WAIT_L(0); PG8_MMA(1, 0, At, B0); PG8_BAR; PG8_SCHED;
.LBB0_527:
	s_add_u32 s7, s12, 0xfffc0080
	s_addc_u32 s8, s13, -1
	s_add_i32 s9, 0, 0x10000
	v_add_u32_e32 v0, s9, v141
	ds_read_b128 v[130:133], v0
	ds_read_b128 v[156:159], v0 offset:1024
	ds_read_b128 v[160:163], v0 offset:2048
	ds_read_b128 v[168:171], v0 offset:3072
	s_cmp_eq_u32 s6, 12
	s_cselect_b32 s65, s1, s8
	s_cselect_b32 s64, s37, s7
	s_cselect_b32 s41, s42, s5
	s_cselect_b32 s40, s43, s4
	v_lshl_add_u64 v[164:165], s[12:13], 0, v[152:153]
	s_add_i32 m0, s56, 0xc000
	ds_read_b128 v[172:175], v166
	ds_read_b128 v[176:179], v166 offset:1024
	ds_read_b128 v[180:183], v166 offset:2048
	ds_read_b128 v[184:187], v166 offset:3072
	ds_read_b128 v[188:191], v166 offset:4096
	ds_read_b128 v[192:195], v166 offset:5120
	ds_read_b128 v[196:199], v166 offset:6144
	ds_read_b128 v[200:203], v166 offset:7168
	global_load_lds_dwordx4 v[164:165], off
	v_lshl_add_u64 v[164:165], s[12:13], 0, v[154:155]
	s_add_i32 m0, s56, 0xe000
	s_nop 0
	global_load_lds_dwordx4 v[164:165], off
	s_waitcnt lgkmcnt(8)
	s_barrier
	s_waitcnt lgkmcnt(0)
	s_waitcnt lgkmcnt(0)
	v_mfma_f32_16x16x32_bf16 v[126:129], v[130:133], v[172:175], v[126:129]
	v_mfma_f32_16x16x32_bf16 v[122:125], v[160:163], v[172:175], v[122:125]
	v_mfma_f32_16x16x32_bf16 v[118:121], v[130:133], v[180:183], v[118:121]
	v_mfma_f32_16x16x32_bf16 v[110:113], v[160:163], v[180:183], v[110:113]
	v_mfma_f32_16x16x32_bf16 v[102:105], v[130:133], v[188:191], v[102:105]
	v_mfma_f32_16x16x32_bf16 v[94:97], v[160:163], v[188:191], v[94:97]
	v_mfma_f32_16x16x32_bf16 v[86:89], v[130:133], v[196:199], v[86:89]
	v_mfma_f32_16x16x32_bf16 v[78:81], v[160:163], v[196:199], v[78:81]
	v_mfma_f32_16x16x32_bf16 v[126:129], v[156:159], v[176:179], v[126:129]
	v_mfma_f32_16x16x32_bf16 v[122:125], v[168:171], v[176:179], v[122:125]
	v_mfma_f32_16x16x32_bf16 v[118:121], v[156:159], v[184:187], v[118:121]
	v_mfma_f32_16x16x32_bf16 v[110:113], v[168:171], v[184:187], v[110:113]
	v_mfma_f32_16x16x32_bf16 v[102:105], v[156:159], v[192:195], v[102:105]
	v_mfma_f32_16x16x32_bf16 v[94:97], v[168:171], v[192:195], v[94:97]
	v_mfma_f32_16x16x32_bf16 v[86:89], v[156:159], v[200:203], v[86:89]
	v_mfma_f32_16x16x32_bf16 v[78:81], v[168:171], v[200:203], v[78:81]
	s_barrier
	s_add_i32 s7, 0, 0x14000
	s_add_i32 s8, s9, s53
	v_add_u32_e32 v0, s7, v141
	v_lshl_add_u64 v[164:165], s[40:41], 0, v[136:137]
	s_mov_b32 m0, s8
	ds_read_b128 v[204:207], v0
	ds_read_b128 v[208:211], v0 offset:1024
	ds_read_b128 v[218:221], v0 offset:2048
	ds_read_b128 v[222:225], v0 offset:3072
	global_load_lds_dwordx4 v[164:165], off
	v_lshl_add_u64 v[212:213], s[40:41], 0, v[134:135]
	s_add_i32 m0, s8, 0x2000
	s_nop 0
	global_load_lds_dwordx4 v[212:213], off
	s_barrier
	s_waitcnt lgkmcnt(0)
	s_waitcnt lgkmcnt(0)
	v_mfma_f32_16x16x32_bf16 v[114:117], v[204:207], v[172:175], v[114:117]
	v_mfma_f32_16x16x32_bf16 v[106:109], v[218:221], v[172:175], v[106:109]
	v_mfma_f32_16x16x32_bf16 v[98:101], v[204:207], v[180:183], v[98:101]
	v_mfma_f32_16x16x32_bf16 v[90:93], v[218:221], v[180:183], v[90:93]
	v_mfma_f32_16x16x32_bf16 v[82:85], v[204:207], v[188:191], v[82:85]
	v_mfma_f32_16x16x32_bf16 v[74:77], v[218:221], v[188:191], v[74:77]
	v_mfma_f32_16x16x32_bf16 v[70:73], v[204:207], v[196:199], v[70:73]
	v_mfma_f32_16x16x32_bf16 v[66:69], v[218:221], v[196:199], v[66:69]
	v_mfma_f32_16x16x32_bf16 v[114:117], v[208:211], v[176:179], v[114:117]
	v_mfma_f32_16x16x32_bf16 v[106:109], v[222:225], v[176:179], v[106:109]
	v_mfma_f32_16x16x32_bf16 v[98:101], v[208:211], v[184:187], v[98:101]
	v_mfma_f32_16x16x32_bf16 v[90:93], v[222:225], v[184:187], v[90:93]
	v_mfma_f32_16x16x32_bf16 v[82:85], v[208:211], v[192:195], v[82:85]
	v_mfma_f32_16x16x32_bf16 v[74:77], v[222:225], v[192:195], v[74:77]
	v_mfma_f32_16x16x32_bf16 v[70:73], v[208:211], v[200:203], v[70:73]
	v_mfma_f32_16x16x32_bf16 v[66:69], v[222:225], v[200:203], v[66:69]
	s_mov_b32 m0, s56
	v_lshl_add_u64 v[214:215], s[64:65], 0, v[136:137]
	s_barrier
	ds_read_b128 v[172:175], v166 offset:16384
	ds_read_b128 v[176:179], v166 offset:17408
	ds_read_b128 v[180:183], v166 offset:18432
	ds_read_b128 v[184:187], v166 offset:19456
	ds_read_b128 v[188:191], v166 offset:20480
	ds_read_b128 v[192:195], v166 offset:21504
	ds_read_b128 v[196:199], v166 offset:22528
	ds_read_b128 v[200:203], v166 offset:23552
	global_load_lds_dwordx4 v[214:215], off
	v_lshl_add_u64 v[226:227], s[64:65], 0, v[134:135]
	s_mov_b32 m0, s57
	s_nop 0
	global_load_lds_dwordx4 v[226:227], off
	s_barrier
	s_waitcnt lgkmcnt(0)
	s_waitcnt lgkmcnt(0)
	v_mfma_f32_16x16x32_bf16 v[62:65], v[130:133], v[172:175], v[62:65]
	v_mfma_f32_16x16x32_bf16 v[58:61], v[160:163], v[172:175], v[58:61]
	v_mfma_f32_16x16x32_bf16 v[54:57], v[130:133], v[180:183], v[54:57]
	v_mfma_f32_16x16x32_bf16 v[46:49], v[160:163], v[180:183], v[46:49]
	v_mfma_f32_16x16x32_bf16 v[38:41], v[130:133], v[188:191], v[38:41]
	v_mfma_f32_16x16x32_bf16 v[30:33], v[160:163], v[188:191], v[30:33]
	v_mfma_f32_16x16x32_bf16 v[22:25], v[130:133], v[196:199], v[22:25]
	v_mfma_f32_16x16x32_bf16 v[14:17], v[160:163], v[196:199], v[14:17]
	v_mfma_f32_16x16x32_bf16 v[62:65], v[156:159], v[176:179], v[62:65]
	v_mfma_f32_16x16x32_bf16 v[58:61], v[168:171], v[176:179], v[58:61]
	v_mfma_f32_16x16x32_bf16 v[54:57], v[156:159], v[184:187], v[54:57]
	v_mfma_f32_16x16x32_bf16 v[46:49], v[168:171], v[184:187], v[46:49]
	v_mfma_f32_16x16x32_bf16 v[38:41], v[156:159], v[192:195], v[38:41]
	v_mfma_f32_16x16x32_bf16 v[30:33], v[168:171], v[192:195], v[30:33]
	v_mfma_f32_16x16x32_bf16 v[22:25], v[156:159], v[200:203], v[22:25]
	v_mfma_f32_16x16x32_bf16 v[14:17], v[168:171], v[200:203], v[14:17]
	s_barrier
; #define PG8_STAGE(bufoff, gbase, voff) do { _Pragma("unroll") for (int _i = 0; _i < 2; ++_i) \
;     __builtin_amdgcn_global_load_lds((const unsigned*)((const char*)(gbase) + (voff)[_i]), (LAS unsigned*)(lds + (bufoff) + ldsw + _i * 8192), 16, 0, 0); } while (0)
; #define PG8_LDA(dst, b, h) do { _Pragma("unroll") for (int m = 0; m < 4; ++m) _Pragma("unroll") for (int k = 0; k < 2; ++k) dst[m][k] = *(const LAS bf16x8*)(lds + PG8_SA(b, h) + aoff + m * 2048 + k * 1024); } while (0)
; #define PG8_LDB(dst, b, h) do { _Pragma("unroll") for (int n = 0; n < 2; ++n) _Pragma("unroll") for (int k = 0; k < 2; ++k) dst[n][k] = *(const LAS bf16x8*)(lds + PG8_SB(b, h) + boff + n * 2048 + k * 1024); } while (0)
; #define PG8_MMA(ai, bj, At, Bt) do { __builtin_amdgcn_s_setprio(1); _Pragma("unroll") for (int m = 0; m < 4; ++m) _Pragma("unroll") for (int n = 0; n < 2; ++n) _Pragma("unroll") for (int k = 0; k < 2; ++k) \
;     acc[ai][bj][m][n] = __builtin_amdgcn_mfma_f32_16x16x32_bf16(Bt[n][k], At[m][k], acc[ai][bj][m][n], 0, 0, 0); __builtin_amdgcn_s_setprio(0); } while (0)
; #define PG8_WAIT_V(n) asm volatile("s_waitcnt vmcnt(" #n ")" ::: "memory")
; #define PG8_WAIT_L(n) asm volatile("s_waitcnt lgkmcnt(" #n ")" ::: "memory")
; #define PG8_BAR __builtin_amdgcn_s_barrier()
; #define PG8_SCHED __builtin_amdgcn_sched_barrier(0)
; template <class Epi, class Sched>
; __device__ __forceinline__ void gemm_phase(LAS unsigned char* lds, const Gemm g, const Sched& S, const Epi& E) {
;     ...
;       PG8_STAGE(PG8_SB(0, 1), b2 + hstepB, voffB);
;       PG8_WAIT_V(6); PG8_BAR; PG8_MMA(1, 1, At, B1); PG8_BAR;
;       PG8_LDB(B0, 1, 0); PG8_SCHED; PG8_LDA(At, 1, 0); PG8_STAGE(PG8_SA(0, 1), a2 + hstepA, voffA);
;       PG8_WAIT_L(8); PG8_BAR; PG8_WAIT_L(0); PG8_MMA(0, 0, At, B0); PG8_BAR; PG8_SCHED;
;       PG8_LDB(B1, 1, 1); PG8_STAGE(PG8_SB(1, 0), b3, voffB);
;       PG8_BAR; PG8_WAIT_L(0); PG8_MMA(0, 1, At, B1); PG8_BAR;
;       PG8_LDA(At, 1, 1); PG8_STAGE(PG8_SA(1, 0), a3, voffA);
	s_add_u32 s8, s40, 0x40000
	s_addc_u32 s9, s41, 0
	s_add_i32 s7, s7, s53
	v_lshl_add_u64 v[130:131], s[8:9], 0, v[136:137]
	s_mov_b32 m0, s7
	s_nop 0
	global_load_lds_dwordx4 v[130:131], off
	v_lshl_add_u64 v[130:131], s[8:9], 0, v[134:135]
	s_add_i32 m0, s7, 0x2000
	s_nop 0
	global_load_lds_dwordx4 v[130:131], off
	s_waitcnt vmcnt(6)
	s_barrier
	v_mfma_f32_16x16x32_bf16 v[50:53], v[204:207], v[172:175], v[50:53]
	v_mfma_f32_16x16x32_bf16 v[42:45], v[218:221], v[172:175], v[42:45]
	v_mfma_f32_16x16x32_bf16 v[34:37], v[204:207], v[180:183], v[34:37]
	v_mfma_f32_16x16x32_bf16 v[26:29], v[218:221], v[180:183], v[26:29]
	v_mfma_f32_16x16x32_bf16 v[18:21], v[204:207], v[188:191], v[18:21]
	v_mfma_f32_16x16x32_bf16 v[10:13], v[218:221], v[188:191], v[10:13]
	v_mfma_f32_16x16x32_bf16 v[6:9], v[204:207], v[196:199], v[6:9]
	v_mfma_f32_16x16x32_bf16 v[2:5], v[218:221], v[196:199], v[2:5]
	v_mfma_f32_16x16x32_bf16 v[50:53], v[208:211], v[176:179], v[50:53]
	v_mfma_f32_16x16x32_bf16 v[42:45], v[222:225], v[176:179], v[42:45]
	v_mfma_f32_16x16x32_bf16 v[34:37], v[208:211], v[184:187], v[34:37]
	v_mfma_f32_16x16x32_bf16 v[26:29], v[222:225], v[184:187], v[26:29]
	v_mfma_f32_16x16x32_bf16 v[18:21], v[208:211], v[192:195], v[18:21]
	v_mfma_f32_16x16x32_bf16 v[10:13], v[222:225], v[192:195], v[10:13]
	v_mfma_f32_16x16x32_bf16 v[6:9], v[208:211], v[200:203], v[6:9]
	v_mfma_f32_16x16x32_bf16 v[2:5], v[222:225], v[200:203], v[2:5]
	s_add_i32 s7, 0, 0x18000
	v_add_u32_e32 v0, s7, v141
	s_barrier
	ds_read_b128 v[130:133], v0
	ds_read_b128 v[156:159], v0 offset:1024
	ds_read_b128 v[160:163], v0 offset:2048
	ds_read_b128 v[168:171], v0 offset:3072
	s_add_u32 s8, s64, 0x40000
	s_addc_u32 s9, s65, 0
	s_mov_b32 m0, s60
	v_lshl_add_u64 v[204:205], s[8:9], 0, v[136:137]
	ds_read_b128 v[172:175], v166 offset:32768
	ds_read_b128 v[176:179], v166 offset:33792
	ds_read_b128 v[180:183], v166 offset:34816
	ds_read_b128 v[184:187], v166 offset:35840
	ds_read_b128 v[188:191], v166 offset:36864
	ds_read_b128 v[192:195], v166 offset:37888
	ds_read_b128 v[196:199], v166 offset:38912
	ds_read_b128 v[200:203], v166 offset:39936
	global_load_lds_dwordx4 v[204:205], off
	v_lshl_add_u64 v[204:205], s[8:9], 0, v[134:135]
	s_mov_b32 m0, s61
	s_nop 0
	global_load_lds_dwordx4 v[204:205], off
	s_waitcnt lgkmcnt(8)
	s_barrier
	s_waitcnt lgkmcnt(0)
	s_waitcnt lgkmcnt(0)
	v_mfma_f32_16x16x32_bf16 v[126:129], v[130:133], v[172:175], v[126:129]
	v_mfma_f32_16x16x32_bf16 v[122:125], v[160:163], v[172:175], v[122:125]
	v_mfma_f32_16x16x32_bf16 v[118:121], v[130:133], v[180:183], v[118:121]
	v_mfma_f32_16x16x32_bf16 v[110:113], v[160:163], v[180:183], v[110:113]
	v_mfma_f32_16x16x32_bf16 v[102:105], v[130:133], v[188:191], v[102:105]
	v_mfma_f32_16x16x32_bf16 v[94:97], v[160:163], v[188:191], v[94:97]
	v_mfma_f32_16x16x32_bf16 v[86:89], v[130:133], v[196:199], v[86:89]
	v_mfma_f32_16x16x32_bf16 v[78:81], v[160:163], v[196:199], v[78:81]
	v_mfma_f32_16x16x32_bf16 v[126:129], v[156:159], v[176:179], v[126:129]
	v_mfma_f32_16x16x32_bf16 v[122:125], v[168:171], v[176:179], v[122:125]
	v_mfma_f32_16x16x32_bf16 v[118:121], v[156:159], v[184:187], v[118:121]
	v_mfma_f32_16x16x32_bf16 v[110:113], v[168:171], v[184:187], v[110:113]
	v_mfma_f32_16x16x32_bf16 v[102:105], v[156:159], v[192:195], v[102:105]
	v_mfma_f32_16x16x32_bf16 v[94:97], v[168:171], v[192:195], v[94:97]
	v_mfma_f32_16x16x32_bf16 v[86:89], v[156:159], v[200:203], v[86:89]
	v_mfma_f32_16x16x32_bf16 v[78:81], v[168:171], v[200:203], v[78:81]
	s_barrier
	s_add_i32 s45, 0, 0x1c000
	s_add_i32 s7, s7, s53
	v_add_u32_e32 v0, s45, v141
	v_lshl_add_u64 v[164:165], v[164:165], 0, s[50:51]
	s_mov_b32 m0, s7
	ds_read_b128 v[204:207], v0
	ds_read_b128 v[208:211], v0 offset:1024
	ds_read_b128 v[218:221], v0 offset:2048
	ds_read_b128 v[222:225], v0 offset:3072
	global_load_lds_dwordx4 v[164:165], off
	v_lshl_add_u64 v[164:165], v[212:213], 0, s[50:51]
	s_add_i32 m0, s7, 0x2000
	s_nop 0
	global_load_lds_dwordx4 v[164:165], off
	s_barrier
	s_waitcnt lgkmcnt(0)
	s_waitcnt lgkmcnt(0)
	v_mfma_f32_16x16x32_bf16 v[114:117], v[204:207], v[172:175], v[114:117]
	v_mfma_f32_16x16x32_bf16 v[106:109], v[218:221], v[172:175], v[106:109]
	v_mfma_f32_16x16x32_bf16 v[98:101], v[204:207], v[180:183], v[98:101]
	v_mfma_f32_16x16x32_bf16 v[90:93], v[218:221], v[180:183], v[90:93]
	v_mfma_f32_16x16x32_bf16 v[82:85], v[204:207], v[188:191], v[82:85]
	v_mfma_f32_16x16x32_bf16 v[74:77], v[218:221], v[188:191], v[74:77]
	v_mfma_f32_16x16x32_bf16 v[70:73], v[204:207], v[196:199], v[70:73]
	v_mfma_f32_16x16x32_bf16 v[66:69], v[218:221], v[196:199], v[66:69]
	v_mfma_f32_16x16x32_bf16 v[114:117], v[208:211], v[176:179], v[114:117]
	v_mfma_f32_16x16x32_bf16 v[106:109], v[222:225], v[176:179], v[106:109]
	v_mfma_f32_16x16x32_bf16 v[98:101], v[208:211], v[184:187], v[98:101]
	v_mfma_f32_16x16x32_bf16 v[90:93], v[222:225], v[184:187], v[90:93]
	v_mfma_f32_16x16x32_bf16 v[82:85], v[208:211], v[192:195], v[82:85]
	v_mfma_f32_16x16x32_bf16 v[74:77], v[222:225], v[192:195], v[74:77]
	v_mfma_f32_16x16x32_bf16 v[70:73], v[208:211], v[200:203], v[70:73]
	v_mfma_f32_16x16x32_bf16 v[66:69], v[222:225], v[200:203], v[66:69]
	s_mov_b32 m0, s28
	v_lshl_add_u64 v[164:165], v[214:215], 0, s[50:51]
	s_barrier
; __device__ __forceinline__ unsigned cvtpk(float lo, float hi) { unsigned r; asm volatile("v_cvt_pk_bf16_f32 %0, %1, %2" : "=v"(r) : "v"(lo), "v"(hi)); return r; }
; #define PG8_STAGE(bufoff, gbase, voff) do { _Pragma("unroll") for (int _i = 0; _i < 2; ++_i) \
;     __builtin_amdgcn_global_load_lds((const unsigned*)((const char*)(gbase) + (voff)[_i]), (LAS unsigned*)(lds + (bufoff) + ldsw + _i * 8192), 16, 0, 0); } while (0)
; #define PG8_LDA(dst, b, h) do { _Pragma("unroll") for (int m = 0; m < 4; ++m) _Pragma("unroll") for (int k = 0; k < 2; ++k) dst[m][k] = *(const LAS bf16x8*)(lds + PG8_SA(b, h) + aoff + m * 2048 + k * 1024); } while (0)
; #define PG8_WAIT_V(n) asm volatile("s_waitcnt vmcnt(" #n ")" ::: "memory")
; #define PG8_WAIT_L(n) asm volatile("s_waitcnt lgkmcnt(" #n ")" ::: "memory")
; template <class Epi, class Sched>
; __device__ __forceinline__ void gemm_phase(LAS unsigned char* lds, const Gemm g, const Sched& S, const Epi& E) {
;     ...
;       PG8_LDA(At, 1, 1); PG8_STAGE(PG8_SA(1, 0), a3, voffA);
;       PG8_BAR; PG8_WAIT_L(0); PG8_MMA(1, 0, At, B0); PG8_BAR; PG8_SCHED;
;       PG8_STAGE(PG8_SB(1, 1), b3 + hstepB, voffB);
;       PG8_WAIT_V(6); PG8_BAR; PG8_MMA(1, 1, At, B1); PG8_BAR;
;   __device__ __forceinline__ void operator()(const f32x4 (&acc)[2][2][4][2], const pg8::Unit& u, int wr, int wc, int fr, int fq) const {
;     ...
;     } else {
; #pragma unroll
;       for (int ai = 0; ai < 2; ++ai)
; #pragma unroll
;         for (int m = 0; m < 4; ++m) { const int row = row0 + ai * 128 + m * 16;
;           bf16_t* rowp = O + (size_t)row * ldc + colt + 32 * wc + 4 * fq;
;           if (wc == 0) {
;             const f32x4* cs = (const f32x4*)(rope + ((size_t)row * 16 + 4 * fq) * 2);
;             const f32x4 cs0 = cs[0], cs1 = cs[1];
;             const float c_[4] = {cs0[0], cs0[2], cs1[0], cs1[2]}, s_[4] = {cs0[1], cs0[3], cs1[1], cs1[3]};
; #pragma unroll
;             for (int bj = 0; bj < 2; ++bj) { const f32x4 x1 = acc[ai][bj][m][0], x2 = acc[ai][bj][m][1]; float o1[4], o2[4];
; #pragma unroll
;               for (int j = 0; j < 4; ++j) { o1[j] = x1[j] * c_[j] - x2[j] * s_[j]; o2[j] = x1[j] * s_[j] + x2[j] * c_[j]; }
;               u32x2 w1 = {cvtpk(o1[0], o1[1]), cvtpk(o1[2], o1[3])}, w2 = {cvtpk(o2[0], o2[1]), cvtpk(o2[2], o2[3])};
;               *(u32x2*)(rowp + bj * 128) = w1; *(u32x2*)(rowp + bj * 128 + 16) = w2; }
	ds_read_b128 v[172:175], v166 offset:49152
	ds_read_b128 v[176:179], v166 offset:50176
	ds_read_b128 v[180:183], v166 offset:51200
	ds_read_b128 v[184:187], v166 offset:52224
	ds_read_b128 v[188:191], v166 offset:53248
	ds_read_b128 v[192:195], v166 offset:54272
	ds_read_b128 v[196:199], v166 offset:55296
	ds_read_b128 v[200:203], v166 offset:56320
	global_load_lds_dwordx4 v[164:165], off
	v_lshl_add_u64 v[164:165], v[226:227], 0, s[50:51]
	s_mov_b32 m0, s29
	s_nop 0
	global_load_lds_dwordx4 v[164:165], off
	s_barrier
	s_waitcnt lgkmcnt(0)
	s_waitcnt lgkmcnt(0)
	v_mfma_f32_16x16x32_bf16 v[62:65], v[130:133], v[172:175], v[62:65]
	v_mfma_f32_16x16x32_bf16 v[58:61], v[160:163], v[172:175], v[58:61]
	v_mfma_f32_16x16x32_bf16 v[54:57], v[130:133], v[180:183], v[54:57]
	v_mfma_f32_16x16x32_bf16 v[46:49], v[160:163], v[180:183], v[46:49]
	v_mfma_f32_16x16x32_bf16 v[38:41], v[130:133], v[188:191], v[38:41]
	v_mfma_f32_16x16x32_bf16 v[30:33], v[160:163], v[188:191], v[30:33]
	v_mfma_f32_16x16x32_bf16 v[22:25], v[130:133], v[196:199], v[22:25]
	v_mfma_f32_16x16x32_bf16 v[14:17], v[160:163], v[196:199], v[14:17]
	v_mfma_f32_16x16x32_bf16 v[62:65], v[156:159], v[176:179], v[62:65]
	v_mfma_f32_16x16x32_bf16 v[58:61], v[168:171], v[176:179], v[58:61]
	v_mfma_f32_16x16x32_bf16 v[54:57], v[156:159], v[184:187], v[54:57]
	v_mfma_f32_16x16x32_bf16 v[46:49], v[168:171], v[184:187], v[46:49]
	v_mfma_f32_16x16x32_bf16 v[38:41], v[156:159], v[192:195], v[38:41]
	v_mfma_f32_16x16x32_bf16 v[30:33], v[168:171], v[192:195], v[30:33]
	v_mfma_f32_16x16x32_bf16 v[22:25], v[156:159], v[200:203], v[22:25]
	v_mfma_f32_16x16x32_bf16 v[14:17], v[168:171], v[200:203], v[14:17]
	s_barrier
	s_add_u32 s8, s40, 0x40080
	s_addc_u32 s9, s41, 0
	s_add_i32 s7, s45, s53
	v_lshl_add_u64 v[130:131], s[8:9], 0, v[136:137]
	s_mov_b32 m0, s7
	s_nop 0
	global_load_lds_dwordx4 v[130:131], off
	v_lshl_add_u64 v[130:131], s[8:9], 0, v[134:135]
	s_add_i32 m0, s7, 0x2000
	s_nop 0
	global_load_lds_dwordx4 v[130:131], off
	s_waitcnt vmcnt(6)
	s_barrier
	v_mfma_f32_16x16x32_bf16 v[50:53], v[204:207], v[172:175], v[50:53]
	v_mfma_f32_16x16x32_bf16 v[42:45], v[218:221], v[172:175], v[42:45]
	v_mfma_f32_16x16x32_bf16 v[34:37], v[204:207], v[180:183], v[34:37]
	v_mfma_f32_16x16x32_bf16 v[26:29], v[218:221], v[180:183], v[26:29]
	v_mfma_f32_16x16x32_bf16 v[18:21], v[204:207], v[188:191], v[18:21]
	v_mfma_f32_16x16x32_bf16 v[10:13], v[218:221], v[188:191], v[10:13]
	v_mfma_f32_16x16x32_bf16 v[6:9], v[204:207], v[196:199], v[6:9]
	v_mfma_f32_16x16x32_bf16 v[2:5], v[218:221], v[196:199], v[2:5]
	v_mfma_f32_16x16x32_bf16 v[50:53], v[208:211], v[176:179], v[50:53]
	v_mfma_f32_16x16x32_bf16 v[42:45], v[222:225], v[176:179], v[42:45]
	v_mfma_f32_16x16x32_bf16 v[34:37], v[208:211], v[184:187], v[34:37]
	v_mfma_f32_16x16x32_bf16 v[26:29], v[222:225], v[184:187], v[26:29]
	v_mfma_f32_16x16x32_bf16 v[18:21], v[208:211], v[192:195], v[18:21]
	v_mfma_f32_16x16x32_bf16 v[10:13], v[222:225], v[192:195], v[10:13]
	v_mfma_f32_16x16x32_bf16 v[6:9], v[208:211], v[200:203], v[6:9]
	v_mfma_f32_16x16x32_bf16 v[2:5], v[222:225], v[200:203], v[2:5]
	s_add_i32 s6, s6, 2
	s_add_u32 s12, s12, 0x100
	s_addc_u32 s13, s13, 0
	s_add_u32 s4, s4, 0x100
	s_addc_u32 s5, s5, 0
	s_cmp_gt_u32 s6, 13
	s_barrier
	s_cbranch_scc0 .LBB0_527
	s_lshl_b32 s0, s0, 8
	s_add_i32 s0, s0, s94
	s_lshl_b32 s1, s10, 8
	s_and_b32 s4, s10, -8
	s_cmp_lg_u32 s4, 16
	s_mov_b64 s[12:13], -1
	s_cbranch_scc0 .LBB0_589
	s_add_i32 s4, s1, 0xfffff800
	s_cmp_gt_i32 s10, 23
	s_cselect_b32 s12, s4, s1
	s_sub_i32 s4, s10, 36
	s_cmp_lt_u32 s4, -4
	s_cselect_b64 s[4:5], -1, 0
	v_or_b32_e32 v156, s0, v139
	v_cndmask_b32_e64 v0, 0, 1, s[4:5]
	s_cmp_gt_u32 s10, 23
	v_readfirstlane_b32 s4, v0
	v_ashrrev_i32_e32 v157, 31, v156
	s_cselect_b32 s4, s4, 5
	s_cmp_gt_i32 s10, 15
	v_lshlrev_b64 v[130:131], 14, v[156:157]
	s_cselect_b32 s37, s4, 4
	s_ashr_i32 s13, s12, 31
	v_lshl_add_u64 v[130:131], s[46:47], 0, v[130:131]
	s_lshl_b32 s10, s95, 1
	v_lshl_add_u64 v[130:131], s[12:13], 1, v[130:131]
	s_cmp_gt_u32 s37, 1
	v_lshl_add_u64 v[158:159], v[130:131], 0, s[10:11]
	s_mov_b64 s[40:41], -1
	s_cbranch_scc0 .LBB0_555
	v_lshlrev_b32_e32 v0, 1, v140
	v_cndmask_b32_e64 v130, 0, 1, s[34:35]
	v_cmp_ne_u32_e64 s[40:41], 1, v130
	s_andn2_b64 vcc, exec, s[34:35]
	v_lshl_add_u64 v[160:161], v[158:159], 0, v[0:1]
	s_cbranch_vccnz .LBB0_592
	v_cvt_pk_bf16_f32 v130, v126, v127
	v_cvt_pk_bf16_f32 v131, v128, v129
	v_cvt_pk_bf16_f32 v132, v122, v123
	v_cvt_pk_bf16_f32 v133, v124, v125
	global_store_dwordx2 v[160:161], v[130:131], off
	global_store_dwordx2 v[160:161], v[132:133], off offset:32
	v_cvt_pk_bf16_f32 v130, v114, v115
	v_cvt_pk_bf16_f32 v131, v116, v117
	v_cvt_pk_bf16_f32 v132, v106, v107
	v_cvt_pk_bf16_f32 v133, v108, v109
	s_cbranch_execnz .LBB0_533

; #define PG8_STAGE(bufoff, gbase, voff) do { _Pragma("unroll") for (int _i = 0; _i < 2; ++_i) \
;     __builtin_amdgcn_global_load_lds((const unsigned*)((const char*)(gbase) + (voff)[_i]), (LAS unsigned*)(lds + (bufoff) + ldsw + _i * 8192), 16, 0, 0); } while (0)
; #define PG8_LDA(dst, b, h) do { _Pragma("unroll") for (int m = 0; m < 4; ++m) _Pragma("unroll") for (int k = 0; k < 2; ++k) dst[m][k] = *(const LAS bf16x8*)(lds + PG8_SA(b, h) + aoff + m * 2048 + k * 1024); } while (0)
; #define PG8_LDB(dst, b, h) do { _Pragma("unroll") for (int n = 0; n < 2; ++n) _Pragma("unroll") for (int k = 0; k < 2; ++k) dst[n][k] = *(const LAS bf16x8*)(lds + PG8_SB(b, h) + boff + n * 2048 + k * 1024); } while (0)
; #define PG8_MMA(ai, bj, At, Bt) do { __builtin_amdgcn_s_setprio(1); _Pragma("unroll") for (int m = 0; m < 4; ++m) _Pragma("unroll") for (int n = 0; n < 2; ++n) _Pragma("unroll") for (int k = 0; k < 2; ++k) \
;     acc[ai][bj][m][n] = __builtin_amdgcn_mfma_f32_16x16x32_bf16(Bt[n][k], At[m][k], acc[ai][bj][m][n], 0, 0, 0); __builtin_amdgcn_s_setprio(0); } while (0)
; #define PG8_WAIT_L(n) asm volatile("s_waitcnt lgkmcnt(" #n ")" ::: "memory")
; #define PG8_BAR __builtin_amdgcn_s_barrier()
; #define PG8_SCHED __builtin_amdgcn_sched_barrier(0)
; template <class Epi, class Sched>
; __device__ __forceinline__ void gemm_phase(LAS unsigned char* lds, const Gemm g, const Sched& S, const Epi& E) {
;     ...
;       const bool last = (t == nt - 2);
;       const char* a1 = cA + (size_t)(t + 1) * kstep;
;       const char* a2 = last ? nA : cA + (size_t)(t + 2) * kstep; const char* b2 = last ? nB : cB + (size_t)(t + 2) * kstep;
;       const char* a3 = a2 + kstep; const char* b3 = b2 + kstep;
;       PG8_LDB(B0, 0, 0); PG8_SCHED; PG8_LDA(At, 0, 0); PG8_STAGE(PG8_SA(1, 1), a1 + hstepA, voffA);
;       PG8_WAIT_L(8); PG8_BAR; PG8_WAIT_L(0); PG8_MMA(0, 0, At, B0); PG8_BAR; PG8_SCHED;
;       PG8_LDB(B1, 0, 1); PG8_STAGE(PG8_SB(0, 0), b2, voffB);
;       PG8_BAR; PG8_WAIT_L(0); PG8_MMA(0, 1, At, B1); PG8_BAR;
;       PG8_LDA(At, 0, 1); PG8_STAGE(PG8_SA(0, 0), a2, voffA);
;       PG8_BAR; PG8_WAIT_L(0); PG8_MMA(1, 0, At, B0); PG8_BAR; PG8_SCHED;
.LBB0_762:
	s_add_u32 s7, s40, 0xffe00080
	s_addc_u32 s8, s41, -1
	s_add_i32 s9, 0, 0x10000
	v_add_u32_e32 v140, s9, v143
	ds_read_b128 v[146:149], v140
	ds_read_b128 v[150:153], v140 offset:1024
	ds_read_b128 v[154:157], v140 offset:2048
	ds_read_b128 v[158:161], v140 offset:3072
	s_cmp_eq_u32 s6, 44
	s_cselect_b32 s49, s25, s8
	s_cselect_b32 s48, s61, s7
	s_cselect_b32 s45, s35, s5
	s_cselect_b32 s44, s34, s4
	v_lshl_add_u64 v[140:141], s[40:41], 0, v[136:137]
	s_add_i32 m0, s10, 0xc000
	ds_read_b128 v[162:165], v145
	ds_read_b128 v[166:169], v145 offset:1024
	ds_read_b128 v[170:173], v145 offset:2048
	ds_read_b128 v[174:177], v145 offset:3072
	ds_read_b128 v[178:181], v145 offset:4096
	ds_read_b128 v[182:185], v145 offset:5120
	ds_read_b128 v[186:189], v145 offset:6144
	ds_read_b128 v[190:193], v145 offset:7168
	global_load_lds_dwordx4 v[140:141], off
	v_lshl_add_u64 v[140:141], s[40:41], 0, v[138:139]
	s_add_i32 m0, s10, 0xe000
	s_nop 0
	global_load_lds_dwordx4 v[140:141], off
	s_waitcnt lgkmcnt(8)
	s_barrier
	s_waitcnt lgkmcnt(0)
	s_waitcnt lgkmcnt(0)
	v_mfma_f32_16x16x32_bf16 v[126:129], v[146:149], v[162:165], v[126:129]
	v_mfma_f32_16x16x32_bf16 v[122:125], v[154:157], v[162:165], v[122:125]
	v_mfma_f32_16x16x32_bf16 v[110:113], v[146:149], v[170:173], v[110:113]
	v_mfma_f32_16x16x32_bf16 v[106:109], v[154:157], v[170:173], v[106:109]
	v_mfma_f32_16x16x32_bf16 v[102:105], v[146:149], v[178:181], v[102:105]
	v_mfma_f32_16x16x32_bf16 v[98:101], v[154:157], v[178:181], v[98:101]
	v_mfma_f32_16x16x32_bf16 v[86:89], v[146:149], v[186:189], v[86:89]
	v_mfma_f32_16x16x32_bf16 v[82:85], v[154:157], v[186:189], v[82:85]
	v_mfma_f32_16x16x32_bf16 v[126:129], v[150:153], v[166:169], v[126:129]
	v_mfma_f32_16x16x32_bf16 v[122:125], v[158:161], v[166:169], v[122:125]
	v_mfma_f32_16x16x32_bf16 v[110:113], v[150:153], v[174:177], v[110:113]
	v_mfma_f32_16x16x32_bf16 v[106:109], v[158:161], v[174:177], v[106:109]
	v_mfma_f32_16x16x32_bf16 v[102:105], v[150:153], v[182:185], v[102:105]
	v_mfma_f32_16x16x32_bf16 v[98:101], v[158:161], v[182:185], v[98:101]
	v_mfma_f32_16x16x32_bf16 v[86:89], v[150:153], v[190:193], v[86:89]
	v_mfma_f32_16x16x32_bf16 v[82:85], v[158:161], v[190:193], v[82:85]
	s_barrier
	s_add_i32 s7, 0, 0x14000
	v_add_u32_e32 v140, s7, v143
	s_add_i32 s8, s9, s1
	ds_read_b128 v[194:197], v140
	ds_read_b128 v[198:201], v140 offset:1024
	ds_read_b128 v[202:205], v140 offset:2048
	ds_read_b128 v[206:209], v140 offset:3072
	v_lshl_add_u64 v[140:141], s[44:45], 0, v[0:1]
	s_mov_b32 m0, s8
	v_lshl_add_u64 v[210:211], s[44:45], 0, v[130:131]
	global_load_lds_dwordx4 v[140:141], off
	s_add_i32 m0, s8, 0x2000
	s_nop 0
	global_load_lds_dwordx4 v[210:211], off
	s_barrier
	s_waitcnt lgkmcnt(0)
	s_waitcnt lgkmcnt(0)
	v_mfma_f32_16x16x32_bf16 v[118:121], v[194:197], v[162:165], v[118:121]
	v_mfma_f32_16x16x32_bf16 v[114:117], v[202:205], v[162:165], v[114:117]
	v_mfma_f32_16x16x32_bf16 v[94:97], v[194:197], v[170:173], v[94:97]
	v_mfma_f32_16x16x32_bf16 v[90:93], v[202:205], v[170:173], v[90:93]
	v_mfma_f32_16x16x32_bf16 v[78:81], v[194:197], v[178:181], v[78:81]
	v_mfma_f32_16x16x32_bf16 v[74:77], v[202:205], v[178:181], v[74:77]
	v_mfma_f32_16x16x32_bf16 v[70:73], v[194:197], v[186:189], v[70:73]
	v_mfma_f32_16x16x32_bf16 v[66:69], v[202:205], v[186:189], v[66:69]
	v_mfma_f32_16x16x32_bf16 v[118:121], v[198:201], v[166:169], v[118:121]
	v_mfma_f32_16x16x32_bf16 v[114:117], v[206:209], v[166:169], v[114:117]
	v_mfma_f32_16x16x32_bf16 v[94:97], v[198:201], v[174:177], v[94:97]
	v_mfma_f32_16x16x32_bf16 v[90:93], v[206:209], v[174:177], v[90:93]
	v_mfma_f32_16x16x32_bf16 v[78:81], v[198:201], v[182:185], v[78:81]
	v_mfma_f32_16x16x32_bf16 v[74:77], v[206:209], v[182:185], v[74:77]
	v_mfma_f32_16x16x32_bf16 v[70:73], v[198:201], v[190:193], v[70:73]
	v_mfma_f32_16x16x32_bf16 v[66:69], v[206:209], v[190:193], v[66:69]
	s_mov_b32 m0, s10
	v_lshl_add_u64 v[212:213], s[48:49], 0, v[134:135]
	s_barrier
	ds_read_b128 v[162:165], v145 offset:16384
	ds_read_b128 v[166:169], v145 offset:17408
	ds_read_b128 v[170:173], v145 offset:18432
	ds_read_b128 v[174:177], v145 offset:19456
	ds_read_b128 v[178:181], v145 offset:20480
	ds_read_b128 v[182:185], v145 offset:21504
	ds_read_b128 v[186:189], v145 offset:22528
	ds_read_b128 v[190:193], v145 offset:23552
	global_load_lds_dwordx4 v[212:213], off
	v_lshl_add_u64 v[214:215], s[48:49], 0, v[132:133]
	s_mov_b32 m0, s28
	s_nop 0
	global_load_lds_dwordx4 v[214:215], off
	s_barrier
	s_waitcnt lgkmcnt(0)
	s_waitcnt lgkmcnt(0)
	v_mfma_f32_16x16x32_bf16 v[62:65], v[146:149], v[162:165], v[62:65]
	v_mfma_f32_16x16x32_bf16 v[58:61], v[154:157], v[162:165], v[58:61]
	v_mfma_f32_16x16x32_bf16 v[46:49], v[146:149], v[170:173], v[46:49]
	v_mfma_f32_16x16x32_bf16 v[42:45], v[154:157], v[170:173], v[42:45]
	v_mfma_f32_16x16x32_bf16 v[30:33], v[146:149], v[178:181], v[30:33]
	v_mfma_f32_16x16x32_bf16 v[26:29], v[154:157], v[178:181], v[26:29]
	v_mfma_f32_16x16x32_bf16 v[14:17], v[146:149], v[186:189], v[14:17]
	v_mfma_f32_16x16x32_bf16 v[10:13], v[154:157], v[186:189], v[10:13]
	v_mfma_f32_16x16x32_bf16 v[62:65], v[150:153], v[166:169], v[62:65]
	v_mfma_f32_16x16x32_bf16 v[58:61], v[158:161], v[166:169], v[58:61]
	v_mfma_f32_16x16x32_bf16 v[46:49], v[150:153], v[174:177], v[46:49]
	v_mfma_f32_16x16x32_bf16 v[42:45], v[158:161], v[174:177], v[42:45]
	v_mfma_f32_16x16x32_bf16 v[30:33], v[150:153], v[182:185], v[30:33]
	v_mfma_f32_16x16x32_bf16 v[26:29], v[158:161], v[182:185], v[26:29]
	v_mfma_f32_16x16x32_bf16 v[14:17], v[150:153], v[190:193], v[14:17]
	v_mfma_f32_16x16x32_bf16 v[10:13], v[158:161], v[190:193], v[10:13]
	s_barrier
; #define PG8_STAGE(bufoff, gbase, voff) do { _Pragma("unroll") for (int _i = 0; _i < 2; ++_i) \
;     __builtin_amdgcn_global_load_lds((const unsigned*)((const char*)(gbase) + (voff)[_i]), (LAS unsigned*)(lds + (bufoff) + ldsw + _i * 8192), 16, 0, 0); } while (0)
; #define PG8_LDA(dst, b, h) do { _Pragma("unroll") for (int m = 0; m < 4; ++m) _Pragma("unroll") for (int k = 0; k < 2; ++k) dst[m][k] = *(const LAS bf16x8*)(lds + PG8_SA(b, h) + aoff + m * 2048 + k * 1024); } while (0)
; #define PG8_LDB(dst, b, h) do { _Pragma("unroll") for (int n = 0; n < 2; ++n) _Pragma("unroll") for (int k = 0; k < 2; ++k) dst[n][k] = *(const LAS bf16x8*)(lds + PG8_SB(b, h) + boff + n * 2048 + k * 1024); } while (0)
; #define PG8_MMA(ai, bj, At, Bt) do { __builtin_amdgcn_s_setprio(1); _Pragma("unroll") for (int m = 0; m < 4; ++m) _Pragma("unroll") for (int n = 0; n < 2; ++n) _Pragma("unroll") for (int k = 0; k < 2; ++k) \
;     acc[ai][bj][m][n] = __builtin_amdgcn_mfma_f32_16x16x32_bf16(Bt[n][k], At[m][k], acc[ai][bj][m][n], 0, 0, 0); __builtin_amdgcn_s_setprio(0); } while (0)
; #define PG8_WAIT_V(n) asm volatile("s_waitcnt vmcnt(" #n ")" ::: "memory")
; #define PG8_WAIT_L(n) asm volatile("s_waitcnt lgkmcnt(" #n ")" ::: "memory")
; #define PG8_BAR __builtin_amdgcn_s_barrier()
; #define PG8_SCHED __builtin_amdgcn_sched_barrier(0)
; template <class Epi, class Sched>
; __device__ __forceinline__ void gemm_phase(LAS unsigned char* lds, const Gemm g, const Sched& S, const Epi& E) {
;     ...
;       PG8_STAGE(PG8_SB(0, 1), b2 + hstepB, voffB);
;       PG8_WAIT_V(6); PG8_BAR; PG8_MMA(1, 1, At, B1); PG8_BAR;
;       PG8_LDB(B0, 1, 0); PG8_SCHED; PG8_LDA(At, 1, 0); PG8_STAGE(PG8_SA(0, 1), a2 + hstepA, voffA);
;       PG8_WAIT_L(8); PG8_BAR; PG8_WAIT_L(0); PG8_MMA(0, 0, At, B0); PG8_BAR; PG8_SCHED;
;       PG8_LDB(B1, 1, 1); PG8_STAGE(PG8_SB(1, 0), b3, voffB);
;       PG8_BAR; PG8_WAIT_L(0); PG8_MMA(0, 1, At, B1); PG8_BAR;
;       PG8_LDA(At, 1, 1); PG8_STAGE(PG8_SA(1, 0), a3, voffA);
	s_add_u32 s8, s44, 0xc0000
	s_addc_u32 s9, s45, 0
	s_add_i32 s7, s7, s1
	v_lshl_add_u64 v[146:147], s[8:9], 0, v[0:1]
	s_mov_b32 m0, s7
	s_nop 0
	global_load_lds_dwordx4 v[146:147], off
	v_lshl_add_u64 v[146:147], s[8:9], 0, v[130:131]
	s_add_i32 m0, s7, 0x2000
	s_nop 0
	global_load_lds_dwordx4 v[146:147], off
	s_waitcnt vmcnt(6)
	s_barrier
	v_mfma_f32_16x16x32_bf16 v[54:57], v[194:197], v[162:165], v[54:57]
	v_mfma_f32_16x16x32_bf16 v[50:53], v[202:205], v[162:165], v[50:53]
	v_mfma_f32_16x16x32_bf16 v[38:41], v[194:197], v[170:173], v[38:41]
	v_mfma_f32_16x16x32_bf16 v[34:37], v[202:205], v[170:173], v[34:37]
	v_mfma_f32_16x16x32_bf16 v[22:25], v[194:197], v[178:181], v[22:25]
	v_mfma_f32_16x16x32_bf16 v[18:21], v[202:205], v[178:181], v[18:21]
	v_mfma_f32_16x16x32_bf16 v[6:9], v[194:197], v[186:189], v[6:9]
	v_mfma_f32_16x16x32_bf16 v[2:5], v[202:205], v[186:189], v[2:5]
	v_mfma_f32_16x16x32_bf16 v[54:57], v[198:201], v[166:169], v[54:57]
	v_mfma_f32_16x16x32_bf16 v[50:53], v[206:209], v[166:169], v[50:53]
	v_mfma_f32_16x16x32_bf16 v[38:41], v[198:201], v[174:177], v[38:41]
	v_mfma_f32_16x16x32_bf16 v[34:37], v[206:209], v[174:177], v[34:37]
	v_mfma_f32_16x16x32_bf16 v[22:25], v[198:201], v[182:185], v[22:25]
	v_mfma_f32_16x16x32_bf16 v[18:21], v[206:209], v[182:185], v[18:21]
	v_mfma_f32_16x16x32_bf16 v[6:9], v[198:201], v[190:193], v[6:9]
	v_mfma_f32_16x16x32_bf16 v[2:5], v[206:209], v[190:193], v[2:5]
	s_add_i32 s7, 0, 0x18000
	v_add_u32_e32 v158, s7, v143
	s_barrier
	ds_read_b128 v[146:149], v158
	ds_read_b128 v[150:153], v158 offset:1024
	ds_read_b128 v[154:157], v158 offset:2048
	ds_read_b128 v[158:161], v158 offset:3072
	s_add_u32 s8, s48, 0x200000
	s_addc_u32 s9, s49, 0
	s_mov_b32 m0, s29
	v_lshl_add_u64 v[194:195], s[8:9], 0, v[134:135]
	ds_read_b128 v[162:165], v145 offset:32768
	ds_read_b128 v[166:169], v145 offset:33792
	ds_read_b128 v[170:173], v145 offset:34816
	ds_read_b128 v[174:177], v145 offset:35840
	ds_read_b128 v[178:181], v145 offset:36864
	ds_read_b128 v[182:185], v145 offset:37888
	ds_read_b128 v[186:189], v145 offset:38912
	ds_read_b128 v[190:193], v145 offset:39936
	global_load_lds_dwordx4 v[194:195], off
	v_lshl_add_u64 v[194:195], s[8:9], 0, v[132:133]
	s_mov_b32 m0, s52
	s_nop 0
	global_load_lds_dwordx4 v[194:195], off
	s_waitcnt lgkmcnt(8)
	s_barrier
	s_waitcnt lgkmcnt(0)
	s_waitcnt lgkmcnt(0)
	v_mfma_f32_16x16x32_bf16 v[126:129], v[146:149], v[162:165], v[126:129]
	v_mfma_f32_16x16x32_bf16 v[122:125], v[154:157], v[162:165], v[122:125]
	v_mfma_f32_16x16x32_bf16 v[110:113], v[146:149], v[170:173], v[110:113]
	v_mfma_f32_16x16x32_bf16 v[106:109], v[154:157], v[170:173], v[106:109]
	v_mfma_f32_16x16x32_bf16 v[102:105], v[146:149], v[178:181], v[102:105]
	v_mfma_f32_16x16x32_bf16 v[98:101], v[154:157], v[178:181], v[98:101]
	v_mfma_f32_16x16x32_bf16 v[86:89], v[146:149], v[186:189], v[86:89]
	v_mfma_f32_16x16x32_bf16 v[82:85], v[154:157], v[186:189], v[82:85]
	v_mfma_f32_16x16x32_bf16 v[126:129], v[150:153], v[166:169], v[126:129]
	v_mfma_f32_16x16x32_bf16 v[122:125], v[158:161], v[166:169], v[122:125]
	v_mfma_f32_16x16x32_bf16 v[110:113], v[150:153], v[174:177], v[110:113]
	v_mfma_f32_16x16x32_bf16 v[106:109], v[158:161], v[174:177], v[106:109]
	v_mfma_f32_16x16x32_bf16 v[102:105], v[150:153], v[182:185], v[102:105]
	v_mfma_f32_16x16x32_bf16 v[98:101], v[158:161], v[182:185], v[98:101]
	v_mfma_f32_16x16x32_bf16 v[86:89], v[150:153], v[190:193], v[86:89]
	v_mfma_f32_16x16x32_bf16 v[82:85], v[158:161], v[190:193], v[82:85]
	s_barrier
	s_add_i32 s48, 0, 0x1c000
	s_add_i32 s7, s7, s1
	v_add_u32_e32 v206, s48, v143
	v_lshl_add_u64 v[140:141], v[140:141], 0, s[50:51]
	s_mov_b32 m0, s7
	ds_read_b128 v[194:197], v206
	ds_read_b128 v[198:201], v206 offset:1024
	ds_read_b128 v[202:205], v206 offset:2048
	ds_read_b128 v[206:209], v206 offset:3072
	global_load_lds_dwordx4 v[140:141], off
	v_lshl_add_u64 v[140:141], v[210:211], 0, s[50:51]
	s_add_i32 m0, s7, 0x2000
	s_nop 0
	global_load_lds_dwordx4 v[140:141], off
	s_barrier
	s_waitcnt lgkmcnt(0)
	s_waitcnt lgkmcnt(0)
	v_mfma_f32_16x16x32_bf16 v[118:121], v[194:197], v[162:165], v[118:121]
	v_mfma_f32_16x16x32_bf16 v[114:117], v[202:205], v[162:165], v[114:117]
	v_mfma_f32_16x16x32_bf16 v[94:97], v[194:197], v[170:173], v[94:97]
	v_mfma_f32_16x16x32_bf16 v[90:93], v[202:205], v[170:173], v[90:93]
	v_mfma_f32_16x16x32_bf16 v[78:81], v[194:197], v[178:181], v[78:81]
	v_mfma_f32_16x16x32_bf16 v[74:77], v[202:205], v[178:181], v[74:77]
	v_mfma_f32_16x16x32_bf16 v[70:73], v[194:197], v[186:189], v[70:73]
	v_mfma_f32_16x16x32_bf16 v[66:69], v[202:205], v[186:189], v[66:69]
	v_mfma_f32_16x16x32_bf16 v[118:121], v[198:201], v[166:169], v[118:121]
	v_mfma_f32_16x16x32_bf16 v[114:117], v[206:209], v[166:169], v[114:117]
	v_mfma_f32_16x16x32_bf16 v[94:97], v[198:201], v[174:177], v[94:97]
	v_mfma_f32_16x16x32_bf16 v[90:93], v[206:209], v[174:177], v[90:93]
	v_mfma_f32_16x16x32_bf16 v[78:81], v[198:201], v[182:185], v[78:81]
	v_mfma_f32_16x16x32_bf16 v[74:77], v[206:209], v[182:185], v[74:77]
	v_mfma_f32_16x16x32_bf16 v[70:73], v[198:201], v[190:193], v[70:73]
	v_mfma_f32_16x16x32_bf16 v[66:69], v[206:209], v[190:193], v[66:69]
	s_mov_b32 m0, s53
	v_lshl_add_u64 v[140:141], v[212:213], 0, s[50:51]
	s_barrier
	ds_read_b128 v[162:165], v145 offset:49152
	ds_read_b128 v[166:169], v145 offset:50176
	ds_read_b128 v[170:173], v145 offset:51200
	ds_read_b128 v[174:177], v145 offset:52224
	ds_read_b128 v[178:181], v145 offset:53248
	ds_read_b128 v[182:185], v145 offset:54272
	ds_read_b128 v[186:189], v145 offset:55296
	ds_read_b128 v[190:193], v145 offset:56320
	global_load_lds_dwordx4 v[140:141], off
	v_lshl_add_u64 v[140:141], v[214:215], 0, s[50:51]
	s_mov_b32 m0, s56
	s_nop 0
	global_load_lds_dwordx4 v[140:141], off
	s_barrier
; #define PG8_STAGE(bufoff, gbase, voff) do { _Pragma("unroll") for (int _i = 0; _i < 2; ++_i) \
;     __builtin_amdgcn_global_load_lds((const unsigned*)((const char*)(gbase) + (voff)[_i]), (LAS unsigned*)(lds + (bufoff) + ldsw + _i * 8192), 16, 0, 0); } while (0)
; #define PG8_MMA(ai, bj, At, Bt) do { __builtin_amdgcn_s_setprio(1); _Pragma("unroll") for (int m = 0; m < 4; ++m) _Pragma("unroll") for (int n = 0; n < 2; ++n) _Pragma("unroll") for (int k = 0; k < 2; ++k) \
;     acc[ai][bj][m][n] = __builtin_amdgcn_mfma_f32_16x16x32_bf16(Bt[n][k], At[m][k], acc[ai][bj][m][n], 0, 0, 0); __builtin_amdgcn_s_setprio(0); } while (0)
; #define PG8_WAIT_V(n) asm volatile("s_waitcnt vmcnt(" #n ")" ::: "memory")
; #define PG8_WAIT_L(n) asm volatile("s_waitcnt lgkmcnt(" #n ")" ::: "memory")
; #define PG8_BAR __builtin_amdgcn_s_barrier()
; #define PG8_SCHED __builtin_amdgcn_sched_barrier(0)
; template <class Epi, class Sched>
; __device__ __forceinline__ void gemm_phase(LAS unsigned char* lds, const Gemm g, const Sched& S, const Epi& E) {
;     ...
;       PG8_BAR; PG8_WAIT_L(0); PG8_MMA(1, 0, At, B0); PG8_BAR; PG8_SCHED;
;       PG8_STAGE(PG8_SB(1, 1), b3 + hstepB, voffB);
;       PG8_WAIT_V(6); PG8_BAR; PG8_MMA(1, 1, At, B1); PG8_BAR;
;     }
;   __device__ __forceinline__ void operator()(const f32x4 (&acc)[2][2][4][2], const pg8::Unit& u, int wr, int wc, int fr, int fq) const {
;     const int row0 = u.pm * 256 + wr * 64 + fr, col0 = u.pn * 256 + wc * 32 + 8 * fq;
; #pragma unroll
;     for (int ai = 0; ai < 2; ++ai)
; #pragma unroll
;       for (int m = 0; m < 4; ++m) { const size_t ro = (size_t)(row0 + ai * 128 + m * 16) * DM + col0;
; #pragma unroll
;         for (int bj = 0; bj < 2; ++bj)
; #pragma unroll
;           for (int n = 0; n < 2; ++n) { const f32x4 bv = *(const f32x4*)(base + ro + bj * 128 + 4 * n); *(f32x4*)(out + ro + bj * 128 + 4 * n) = acc[ai][bj][m][n] + bv; } }
	s_waitcnt lgkmcnt(0)
	s_waitcnt lgkmcnt(0)
	v_mfma_f32_16x16x32_bf16 v[62:65], v[146:149], v[162:165], v[62:65]
	v_mfma_f32_16x16x32_bf16 v[58:61], v[154:157], v[162:165], v[58:61]
	v_mfma_f32_16x16x32_bf16 v[46:49], v[146:149], v[170:173], v[46:49]
	v_mfma_f32_16x16x32_bf16 v[42:45], v[154:157], v[170:173], v[42:45]
	v_mfma_f32_16x16x32_bf16 v[30:33], v[146:149], v[178:181], v[30:33]
	v_mfma_f32_16x16x32_bf16 v[26:29], v[154:157], v[178:181], v[26:29]
	v_mfma_f32_16x16x32_bf16 v[14:17], v[146:149], v[186:189], v[14:17]
	v_mfma_f32_16x16x32_bf16 v[10:13], v[154:157], v[186:189], v[10:13]
	v_mfma_f32_16x16x32_bf16 v[62:65], v[150:153], v[166:169], v[62:65]
	v_mfma_f32_16x16x32_bf16 v[58:61], v[158:161], v[166:169], v[58:61]
	v_mfma_f32_16x16x32_bf16 v[46:49], v[150:153], v[174:177], v[46:49]
	v_mfma_f32_16x16x32_bf16 v[42:45], v[158:161], v[174:177], v[42:45]
	v_mfma_f32_16x16x32_bf16 v[30:33], v[150:153], v[182:185], v[30:33]
	v_mfma_f32_16x16x32_bf16 v[26:29], v[158:161], v[182:185], v[26:29]
	v_mfma_f32_16x16x32_bf16 v[14:17], v[150:153], v[190:193], v[14:17]
	v_mfma_f32_16x16x32_bf16 v[10:13], v[158:161], v[190:193], v[10:13]
	s_barrier
	s_add_u32 s8, s44, 0xc0080
	s_addc_u32 s9, s45, 0
	s_add_i32 s7, s48, s1
	v_lshl_add_u64 v[140:141], s[8:9], 0, v[0:1]
	s_mov_b32 m0, s7
	s_nop 0
	global_load_lds_dwordx4 v[140:141], off
	v_lshl_add_u64 v[140:141], s[8:9], 0, v[130:131]
	s_add_i32 m0, s7, 0x2000
	s_nop 0
	global_load_lds_dwordx4 v[140:141], off
	s_waitcnt vmcnt(6)
	s_barrier
	v_mfma_f32_16x16x32_bf16 v[54:57], v[194:197], v[162:165], v[54:57]
	v_mfma_f32_16x16x32_bf16 v[50:53], v[202:205], v[162:165], v[50:53]
	v_mfma_f32_16x16x32_bf16 v[38:41], v[194:197], v[170:173], v[38:41]
	v_mfma_f32_16x16x32_bf16 v[34:37], v[202:205], v[170:173], v[34:37]
	v_mfma_f32_16x16x32_bf16 v[22:25], v[194:197], v[178:181], v[22:25]
	v_mfma_f32_16x16x32_bf16 v[18:21], v[202:205], v[178:181], v[18:21]
	v_mfma_f32_16x16x32_bf16 v[6:9], v[194:197], v[186:189], v[6:9]
	v_mfma_f32_16x16x32_bf16 v[2:5], v[202:205], v[186:189], v[2:5]
	v_mfma_f32_16x16x32_bf16 v[54:57], v[198:201], v[166:169], v[54:57]
	v_mfma_f32_16x16x32_bf16 v[50:53], v[206:209], v[166:169], v[50:53]
	v_mfma_f32_16x16x32_bf16 v[38:41], v[198:201], v[174:177], v[38:41]
	v_mfma_f32_16x16x32_bf16 v[34:37], v[206:209], v[174:177], v[34:37]
	v_mfma_f32_16x16x32_bf16 v[22:25], v[198:201], v[182:185], v[22:25]
	v_mfma_f32_16x16x32_bf16 v[18:21], v[206:209], v[182:185], v[18:21]
	v_mfma_f32_16x16x32_bf16 v[6:9], v[198:201], v[190:193], v[6:9]
	v_mfma_f32_16x16x32_bf16 v[2:5], v[206:209], v[190:193], v[2:5]
	s_add_i32 s6, s6, 2
	s_add_u32 s40, s40, 0x100
	s_addc_u32 s41, s41, 0
	s_add_u32 s4, s4, 0x100
	s_addc_u32 s5, s5, 0
	s_cmp_gt_u32 s6, 45
	s_barrier
	s_cbranch_scc0 .LBB0_762
	v_lshl_add_u32 v154, s43, 8, v142
	v_lshl_or_b32 v140, s42, 8, v144
	v_ashrrev_i32_e32 v155, 31, v154
	v_ashrrev_i32_e32 v141, 31, v140
	v_lshlrev_b64 v[146:147], 12, v[154:155]
	v_lshl_add_u64 v[146:147], s[12:13], 0, v[146:147]
	v_lshlrev_b64 v[156:157], 2, v[140:141]
	v_lshl_add_u64 v[140:141], v[146:147], 0, v[156:157]
	global_load_dwordx4 v[146:149], v[140:141], off offset:16
	global_load_dwordx4 v[150:153], v[140:141], off
	s_mov_b64 s[4:5], 0x80000
	s_mov_b32 s42, s60
	s_mov_b32 s43, s24
	s_mov_b64 s[44:45], s[34:35]
	s_mov_b64 s[48:49], s[36:37]
	s_waitcnt vmcnt(0)
	v_pk_add_f32 v[124:125], v[124:125], v[148:149]
	v_pk_add_f32 v[128:129], v[128:129], v[152:153]
	v_pk_add_f32 v[126:127], v[126:127], v[150:151]
	v_pk_add_f32 v[122:123], v[122:123], v[146:147]
	global_store_dwordx4 v[140:141], v[126:129], off
	global_store_dwordx4 v[140:141], v[122:125], off offset:16
	global_load_dwordx4 v[122:125], v[140:141], off offset:528
	s_nop 0
	global_load_dwordx4 v[126:129], v[140:141], off offset:512
	s_waitcnt vmcnt(0)
	v_pk_add_f32 v[116:117], v[116:117], v[124:125]
	v_pk_add_f32 v[114:115], v[114:115], v[122:123]
	global_store_dwordx4 v[140:141], v[114:117], off offset:528
	v_pk_add_f32 v[120:121], v[120:121], v[128:129]
	v_pk_add_f32 v[118:119], v[118:119], v[126:127]
	v_or_b32_e32 v114, 16, v154
	v_ashrrev_i32_e32 v115, 31, v114
	v_lshlrev_b64 v[114:115], 12, v[114:115]
	v_lshl_add_u64 v[114:115], s[12:13], 0, v[114:115]
	global_store_dwordx4 v[140:141], v[118:121], off offset:512
	v_lshl_add_u64 v[122:123], v[114:115], 0, v[156:157]
	global_load_dwordx4 v[114:117], v[122:123], off offset:16
	global_load_dwordx4 v[118:121], v[122:123], off
	s_waitcnt vmcnt(0)
	v_pk_add_f32 v[108:109], v[108:109], v[116:117]
	v_pk_add_f32 v[112:113], v[112:113], v[120:121]
	v_pk_add_f32 v[110:111], v[110:111], v[118:119]
	v_pk_add_f32 v[106:107], v[106:107], v[114:115]
	global_store_dwordx4 v[122:123], v[110:113], off
	global_store_dwordx4 v[122:123], v[106:109], off offset:16
	global_load_dwordx4 v[106:109], v[122:123], off offset:528
	s_nop 0
	global_load_dwordx4 v[110:113], v[122:123], off offset:512
	s_waitcnt vmcnt(0)
	v_pk_add_f32 v[92:93], v[92:93], v[108:109]
	v_pk_add_f32 v[90:91], v[90:91], v[106:107]
	global_store_dwordx4 v[122:123], v[90:93], off offset:528
	v_pk_add_f32 v[96:97], v[96:97], v[112:113]
	v_pk_add_f32 v[94:95], v[94:95], v[110:111]
	v_or_b32_e32 v90, 32, v154
	v_ashrrev_i32_e32 v91, 31, v90
	v_lshlrev_b64 v[90:91], 12, v[90:91]
	v_lshl_add_u64 v[90:91], s[12:13], 0, v[90:91]
	global_store_dwordx4 v[122:123], v[94:97], off offset:512
	v_lshl_add_u64 v[106:107], v[90:91], 0, v[156:157]
	global_load_dwordx4 v[90:93], v[106:107], off offset:16
	global_load_dwordx4 v[94:97], v[106:107], off
	s_waitcnt vmcnt(0)
;   __device__ __forceinline__ void operator()(const f32x4 (&acc)[2][2][4][2], const pg8::Unit& u, int wr, int wc, int fr, int fq) const {
;     const int row0 = u.pm * 256 + wr * 64 + fr, col0 = u.pn * 256 + wc * 32 + 8 * fq;
; #pragma unroll
;     for (int ai = 0; ai < 2; ++ai)
; #pragma unroll
;       for (int m = 0; m < 4; ++m) { const size_t ro = (size_t)(row0 + ai * 128 + m * 16) * DM + col0;
; #pragma unroll
;         for (int bj = 0; bj < 2; ++bj)
; #pragma unroll
;           for (int n = 0; n < 2; ++n) { const f32x4 bv = *(const f32x4*)(base + ro + bj * 128 + 4 * n); *(f32x4*)(out + ro + bj * 128 + 4 * n) = acc[ai][bj][m][n] + bv; } }
	v_pk_add_f32 v[92:93], v[100:101], v[92:93]
	v_pk_add_f32 v[96:97], v[104:105], v[96:97]
	v_pk_add_f32 v[94:95], v[102:103], v[94:95]
	v_pk_add_f32 v[90:91], v[98:99], v[90:91]
	global_store_dwordx4 v[106:107], v[94:97], off
	global_store_dwordx4 v[106:107], v[90:93], off offset:16
	global_load_dwordx4 v[90:93], v[106:107], off offset:528
	s_nop 0
	global_load_dwordx4 v[94:97], v[106:107], off offset:512
	s_waitcnt vmcnt(0)
	v_pk_add_f32 v[76:77], v[76:77], v[92:93]
	v_pk_add_f32 v[74:75], v[74:75], v[90:91]
	global_store_dwordx4 v[106:107], v[74:77], off offset:528
	v_pk_add_f32 v[80:81], v[80:81], v[96:97]
	v_pk_add_f32 v[78:79], v[78:79], v[94:95]
	v_or_b32_e32 v74, 48, v154
	v_ashrrev_i32_e32 v75, 31, v74
	v_lshlrev_b64 v[74:75], 12, v[74:75]
	v_lshl_add_u64 v[74:75], s[12:13], 0, v[74:75]
	global_store_dwordx4 v[106:107], v[78:81], off offset:512
	v_lshl_add_u64 v[90:91], v[74:75], 0, v[156:157]
	global_load_dwordx4 v[74:77], v[90:91], off offset:16
	global_load_dwordx4 v[78:81], v[90:91], off
	s_waitcnt vmcnt(0)
	v_pk_add_f32 v[76:77], v[84:85], v[76:77]
	v_pk_add_f32 v[80:81], v[88:89], v[80:81]
	v_pk_add_f32 v[78:79], v[86:87], v[78:79]
	v_pk_add_f32 v[74:75], v[82:83], v[74:75]
	global_store_dwordx4 v[90:91], v[78:81], off
	global_store_dwordx4 v[90:91], v[74:77], off offset:16
	global_load_dwordx4 v[74:77], v[90:91], off offset:528
	s_nop 0
	global_load_dwordx4 v[78:81], v[90:91], off offset:512
	s_waitcnt vmcnt(0)
	v_pk_add_f32 v[66:67], v[66:67], v[74:75]
	v_lshl_add_u64 v[74:75], v[140:141], 0, s[4:5]
	s_mov_b32 s4, 0x80000
	v_pk_add_f32 v[72:73], v[72:73], v[80:81]
	v_pk_add_f32 v[70:71], v[70:71], v[78:79]
	v_pk_add_f32 v[68:69], v[68:69], v[76:77]
	v_add_co_u32_e32 v76, vcc, s4, v140
	global_store_dwordx4 v[90:91], v[70:73], off offset:512
	global_store_dwordx4 v[90:91], v[66:69], off offset:528
	v_addc_co_u32_e32 v77, vcc, 0, v141, vcc
	global_load_dwordx4 v[66:69], v[76:77], off
	global_load_dwordx4 v[70:73], v[74:75], off offset:16
	s_mov_b64 s[4:5], 0x90000
	s_waitcnt vmcnt(0)
	v_pk_add_f32 v[64:65], v[64:65], v[68:69]
	v_pk_add_f32 v[62:63], v[62:63], v[66:67]
	v_pk_add_f32 v[60:61], v[60:61], v[72:73]
	v_pk_add_f32 v[58:59], v[58:59], v[70:71]
	global_store_dwordx4 v[76:77], v[62:65], off
	global_store_dwordx4 v[74:75], v[58:61], off offset:16
	global_load_dwordx4 v[58:61], v[74:75], off offset:528
	s_nop 0
	global_load_dwordx4 v[62:65], v[74:75], off offset:512
	s_waitcnt vmcnt(0)
	v_pk_add_f32 v[50:51], v[50:51], v[58:59]
	v_lshl_add_u64 v[58:59], v[140:141], 0, s[4:5]
	s_mov_b32 s4, 0x90000
	v_pk_add_f32 v[56:57], v[56:57], v[64:65]
	v_pk_add_f32 v[54:55], v[54:55], v[62:63]
	v_pk_add_f32 v[52:53], v[52:53], v[60:61]
	v_add_co_u32_e32 v60, vcc, s4, v140
	global_store_dwordx4 v[74:75], v[54:57], off offset:512
	global_store_dwordx4 v[74:75], v[50:53], off offset:528
	v_addc_co_u32_e32 v61, vcc, 0, v141, vcc
	global_load_dwordx4 v[50:53], v[60:61], off
	global_load_dwordx4 v[54:57], v[58:59], off offset:16
	s_mov_b64 s[4:5], 0xa0000
	s_waitcnt vmcnt(0)
	v_pk_add_f32 v[48:49], v[48:49], v[52:53]
	v_pk_add_f32 v[46:47], v[46:47], v[50:51]
	v_pk_add_f32 v[44:45], v[44:45], v[56:57]
	v_pk_add_f32 v[42:43], v[42:43], v[54:55]
	global_store_dwordx4 v[60:61], v[46:49], off
	global_store_dwordx4 v[58:59], v[42:45], off offset:16
	global_load_dwordx4 v[42:45], v[58:59], off offset:528
	s_nop 0
	global_load_dwordx4 v[46:49], v[58:59], off offset:512
	s_waitcnt vmcnt(0)
	v_pk_add_f32 v[34:35], v[34:35], v[42:43]
	v_lshl_add_u64 v[42:43], v[140:141], 0, s[4:5]
	s_mov_b32 s4, 0xa0000
	v_pk_add_f32 v[40:41], v[40:41], v[48:49]
	v_pk_add_f32 v[38:39], v[38:39], v[46:47]
	v_pk_add_f32 v[36:37], v[36:37], v[44:45]
	v_add_co_u32_e32 v44, vcc, s4, v140
	global_store_dwordx4 v[58:59], v[38:41], off offset:512
	global_store_dwordx4 v[58:59], v[34:37], off offset:528
	v_addc_co_u32_e32 v45, vcc, 0, v141, vcc
	global_load_dwordx4 v[34:37], v[44:45], off
	global_load_dwordx4 v[38:41], v[42:43], off offset:16
	s_mov_b64 s[4:5], 0xb0000
	s_waitcnt vmcnt(0)
	v_pk_add_f32 v[32:33], v[32:33], v[36:37]
	v_pk_add_f32 v[30:31], v[30:31], v[34:35]
	v_pk_add_f32 v[28:29], v[28:29], v[40:41]
	v_pk_add_f32 v[26:27], v[26:27], v[38:39]
	global_store_dwordx4 v[44:45], v[30:33], off
	global_store_dwordx4 v[42:43], v[26:29], off offset:16
	global_load_dwordx4 v[26:29], v[42:43], off offset:528
	s_nop 0
	global_load_dwordx4 v[30:33], v[42:43], off offset:512
	s_waitcnt vmcnt(0)
	v_pk_add_f32 v[20:21], v[20:21], v[28:29]
	v_pk_add_f32 v[18:19], v[18:19], v[26:27]
	global_store_dwordx4 v[42:43], v[18:21], off offset:528
	v_pk_add_f32 v[24:25], v[24:25], v[32:33]
	v_pk_add_f32 v[22:23], v[22:23], v[30:31]
	v_lshl_add_u64 v[18:19], v[140:141], 0, s[4:5]
	s_mov_b32 s4, 0xb0000
	v_add_co_u32_e32 v28, vcc, s4, v140
	global_store_dwordx4 v[42:43], v[22:25], off offset:512
	s_nop 0
	v_addc_co_u32_e32 v29, vcc, 0, v141, vcc
	global_load_dwordx4 v[20:23], v[28:29], off
	global_load_dwordx4 v[24:27], v[18:19], off offset:16
	s_and_b64 vcc, exec, s[38:39]
	s_waitcnt vmcnt(0)
	v_pk_add_f32 v[16:17], v[16:17], v[22:23]
	v_pk_add_f32 v[14:15], v[14:15], v[20:21]
	v_pk_add_f32 v[12:13], v[12:13], v[26:27]
	v_pk_add_f32 v[10:11], v[10:11], v[24:25]
	global_store_dwordx4 v[28:29], v[14:17], off
	global_store_dwordx4 v[18:19], v[10:13], off offset:16
	global_load_dwordx4 v[10:13], v[18:19], off offset:528
	s_nop 0
	global_load_dwordx4 v[14:17], v[18:19], off offset:512
	s_waitcnt vmcnt(0)
	v_pk_add_f32 v[4:5], v[4:5], v[12:13]
	v_pk_add_f32 v[8:9], v[8:9], v[16:17]
	v_pk_add_f32 v[6:7], v[6:7], v[14:15]
	v_pk_add_f32 v[2:3], v[2:3], v[10:11]
	global_store_dwordx4 v[18:19], v[6:9], off offset:512
	global_store_dwordx4 v[18:19], v[2:5], off offset:528
	s_cbranch_vccz .LBB0_753
	s_waitcnt vmcnt(0)
	s_cmpk_gt_u32 s0, 0xff
	s_cbranch_scc1 .LBB0_766
	s_barrier
